# GEMM K-loop with the barrier moved to mid-period (fragment reads and DMA issue in the second half of the MFMA block) on top of the k-blocked operand layouts
# speedup vs baseline: 1.1377x; 1.0180x over previous
.LBB0_13:
	s_lshr_b32 s13, s12, 4
	s_and_b32 s13, s13, 24
	s_and_b32 s14, s12, 7
	s_or_b32 s13, s13, s14
	s_lshl_b32 s13, s13, 10
	v_mov_b32 v8, v198
	s_or_b32 s14, s13, s65
	v_ashrrev_i32_e32 v12, 2, v8
	v_add_u32_e32 v0, s14, v12
	v_ashrrev_i32_e32 v1, 31, v0
	v_readlane_b32 s16, v253, 21
	s_lshl_b32 s15, s12, 5
	v_lshlrev_b64 v[0:1], 6, v[0:1]
	v_readlane_b32 s17, v253, 22
	v_lshlrev_b32_e32 v2, 4, v8
	s_and_b32 s13, s15, 0xf00
	v_lshl_add_u64 v[0:1], s[16:17], 0, v[0:1]
	v_and_b32_e32 v152, 48, v2
	v_lshl_add_u64 v[14:15], v[0:1], 0, v[152:153]
	v_add_u32_e32 v0, s13, v12
	v_ashrrev_i32_e32 v1, 31, v0
	v_lshlrev_b64 v[0:1], 6, v[0:1]
	v_lshl_add_u64 v[0:1], s[4:5], 0, v[0:1]
	v_add_co_u32_e32 v54, vcc, s62, v14
	v_lshl_add_u64 v[0:1], v[0:1], 0, v[152:153]
	s_nop 0
	v_addc_co_u32_e32 v55, vcc, 0, v15, vcc
	s_lshl_b32 s16, s11, 11
	s_lshl_b32 s17, s12, 6
	s_and_b32 s18, s10, 7
	v_add_co_u32_e32 v2, vcc, s62, v0
	s_and_b32 s16, s16, 0x780000
	s_and_b32 s19, s17, 0x6000
	s_lshl_b32 s18, s18, 10
	v_lshrrev_b32_e32 v6, 2, v8
	v_addc_co_u32_e32 v3, vcc, 0, v1, vcc
	v_and_b32_e32 v6, 12, v6
	v_ashrrev_i32_e32 v13, 31, v12
	s_movk_i32 s17, 0x1230
	s_add_u32 s16, s7, s16
	v_add_co_u32_e32 v4, vcc, s33, v0
	v_lshrrev_b32_e64 v10, v6, s17
	v_lshlrev_b64 v[6:7], 11, v[12:13]
	s_addc_u32 s17, s8, 0
	s_or_b32 s18, s18, s19
	v_addc_co_u32_e32 v5, vcc, 0, v1, vcc
	v_and_b32_e32 v22, 3, v8
	v_xor_b32_e32 v8, v10, v8
	v_lshl_add_u64 v[156:157], s[16:17], 0, v[6:7]
	s_or_b32 s16, s18, s65
	v_add_co_u32_e32 v20, vcc, s72, v0
	v_lshlrev_b32_e32 v9, 6, v12
	v_lshlrev_b32_e32 v8, 4, v8
	v_add_u32_e32 v12, s16, v12
	v_addc_co_u32_e32 v21, vcc, 0, v1, vcc
	s_nop 0
	v_readfirstlane_b32 s26, v14
	v_readfirstlane_b32 s27, v15
	v_readfirstlane_b32 s28, v0
	v_readfirstlane_b32 s29, v1
	v_lshrrev_b32_e32 v250, 6, v198
	s_nop 0
	v_readfirstlane_b32 s24, v250
	s_lshl_b32 s24, s24, 10
	v_lshrrev_b32_e32 v250, 2, v200
	v_lshrrev_b32_e32 v251, 4, v200
	v_lshlrev_b32_e32 v251, 2, v251
	v_mov_b32_e32 v248, 0x1230
	v_lshrrev_b32_e32 v251, v251, v248
	v_xor_b32_e32 v251, v251, v200
	v_and_b32_e32 v251, 3, v251
	v_lshlrev_b32_e32 v251, 4, v251
	v_lshl_add_u32 v244, v250, 11, v251
	v_add_u32_e32 v245, 0x20000, v244
	v_add_u32_e32 v246, 0x40000, v244
	v_add_u32_e32 v247, 0x60000, v244
	v_lshl_add_u32 v156, v250, 6, v251
	v_add_u32_e32 v157, 0x1000, v156
	v_add_u32_e32 v158, 0x2000, v156
	v_add_u32_e32 v159, 0x3000, v156
	s_mov_b32 s25, 0
	s_add_u32 m0, s25, s24
	s_nop 0
	global_load_lds_dwordx4 v156, s[26:27]
	s_add_u32 m0, m0, 0x1000
	s_nop 0
	global_load_lds_dwordx4 v157, s[26:27]
	s_add_u32 m0, m0, 0x1000
	s_nop 0
	global_load_lds_dwordx4 v156, s[28:29]
	s_add_u32 m0, m0, 0x1000
	s_nop 0
	global_load_lds_dwordx4 v157, s[28:29]
	s_add_u32 m0, m0, 0x1000
	s_nop 0
	global_load_lds_dwordx4 v158, s[28:29]
	s_add_u32 m0, m0, 0x1000
	s_nop 0
	global_load_lds_dwordx4 v159, s[28:29]
	s_add_u32 s26, s26, 0x200000
	s_addc_u32 s27, s27, 0
	s_add_u32 s28, s28, 0x40000
	s_addc_u32 s29, s29, 0
	s_add_u32 s25, s25, 24576
	s_cmp_eq_u32 s25, 73728
	s_cselect_b32 s25, 0, s25
	s_add_u32 m0, s25, s24
	s_nop 0
	global_load_lds_dwordx4 v156, s[26:27]
	s_add_u32 m0, m0, 0x1000
	s_nop 0
	global_load_lds_dwordx4 v157, s[26:27]
	s_add_u32 m0, m0, 0x1000
	s_nop 0
	global_load_lds_dwordx4 v156, s[28:29]
	s_add_u32 m0, m0, 0x1000
	s_nop 0
	global_load_lds_dwordx4 v157, s[28:29]
	s_add_u32 m0, m0, 0x1000
	s_nop 0
	global_load_lds_dwordx4 v158, s[28:29]
	s_add_u32 m0, m0, 0x1000
	s_nop 0
	global_load_lds_dwordx4 v159, s[28:29]
	s_add_u32 s26, s26, 0x200000
	s_addc_u32 s27, s27, 0
	s_add_u32 s28, s28, 0x40000
	s_addc_u32 s29, s29, 0
	s_add_u32 s25, s25, 24576
	s_cmp_eq_u32 s25, 73728
	s_cselect_b32 s25, 0, s25
	s_add_u32 m0, s25, s24
	s_nop 0
	global_load_lds_dwordx4 v156, s[26:27]
	s_add_u32 m0, m0, 0x1000
	s_nop 0
	global_load_lds_dwordx4 v157, s[26:27]
	s_add_u32 m0, m0, 0x1000
	s_nop 0
	global_load_lds_dwordx4 v156, s[28:29]
	s_add_u32 m0, m0, 0x1000
	s_nop 0
	global_load_lds_dwordx4 v157, s[28:29]
	s_add_u32 m0, m0, 0x1000
	s_nop 0
	global_load_lds_dwordx4 v158, s[28:29]
	s_add_u32 m0, m0, 0x1000
	s_nop 0
	global_load_lds_dwordx4 v159, s[28:29]
	s_add_u32 s26, s26, 0x200000
	s_addc_u32 s27, s27, 0
	s_add_u32 s28, s28, 0x40000
	s_addc_u32 s29, s29, 0
	s_add_u32 s25, s25, 24576
	s_cmp_eq_u32 s25, 73728
	s_cselect_b32 s25, 0, s25
	v_mov_b32_e32 v24, 0
	v_mov_b32_e32 v25, v24
	v_mov_b32_e32 v26, v24
	v_mov_b32_e32 v27, v24
	v_mov_b32_e32 v28, v24
	v_mov_b32_e32 v29, v24
	v_mov_b32_e32 v84, v24
	v_mov_b32_e32 v85, v24
	v_mov_b32_e32 v86, v24
	v_mov_b32_e32 v87, v24
	v_mov_b32_e32 v88, v24
	v_mov_b32_e32 v89, v24
	v_mov_b32_e32 v90, v24
	v_mov_b32_e32 v91, v24
	v_mov_b32_e32 v92, v24
	v_mov_b32_e32 v93, v24
	v_mov_b32_e32 v94, v24
	v_mov_b32_e32 v95, v24
	v_mov_b32_e32 v96, v24
	v_mov_b32_e32 v97, v24
	v_mov_b32_e32 v98, v24
	v_mov_b32_e32 v99, v24
	v_mov_b32_e32 v54, v24
	v_mov_b32_e32 v55, v24
	v_mov_b32_e32 v100, v24
	v_mov_b32_e32 v101, v24
	v_mov_b32_e32 v30, v24
	v_mov_b32_e32 v31, v24
	v_mov_b32_e32 v32, v24
	v_mov_b32_e32 v33, v24
	v_mov_b32_e32 v34, v24
	v_mov_b32_e32 v35, v24
	v_mov_b32_e32 v36, v24
	v_mov_b32_e32 v37, v24
	v_mov_b32_e32 v38, v24
	v_mov_b32_e32 v39, v24
	v_mov_b32_e32 v40, v24
	v_mov_b32_e32 v41, v24
	v_mov_b32_e32 v42, v24
	v_mov_b32_e32 v43, v24
	v_mov_b32_e32 v44, v24
	v_mov_b32_e32 v45, v24
	v_mov_b32_e32 v46, v24
	v_mov_b32_e32 v47, v24
	v_mov_b32_e32 v48, v24
	v_mov_b32_e32 v49, v24
	v_mov_b32_e32 v50, v24
	v_mov_b32_e32 v51, v24
	v_mov_b32_e32 v52, v24
	v_mov_b32_e32 v53, v24
	v_mov_b32_e32 v102, v24
	v_mov_b32_e32 v103, v24
	v_mov_b32_e32 v104, v24
	v_mov_b32_e32 v105, v24
	v_mov_b32_e32 v106, v24
	v_mov_b32_e32 v107, v24
	v_mov_b32_e32 v116, v24
	v_mov_b32_e32 v117, v24
	v_mov_b32_e32 v118, v24
	v_mov_b32_e32 v119, v24
	v_mov_b32_e32 v128, v24
	v_mov_b32_e32 v129, v24
	v_mov_b32_e32 v130, v24
	v_mov_b32_e32 v131, v24
	v_mov_b32_e32 v108, v24
	v_mov_b32_e32 v109, v24
	v_mov_b32_e32 v110, v24
	v_mov_b32_e32 v111, v24
	v_mov_b32_e32 v112, v24
	v_mov_b32_e32 v113, v24
	v_mov_b32_e32 v114, v24
	v_mov_b32_e32 v115, v24
	v_mov_b32_e32 v120, v24
	v_mov_b32_e32 v121, v24
	v_mov_b32_e32 v122, v24
	v_mov_b32_e32 v123, v24
	v_mov_b32_e32 v124, v24
	v_mov_b32_e32 v125, v24
	v_mov_b32_e32 v126, v24
	v_mov_b32_e32 v127, v24
	v_mov_b32_e32 v64, v24
	v_mov_b32_e32 v65, v24
	v_mov_b32_e32 v66, v24
	v_mov_b32_e32 v67, v24
	v_mov_b32_e32 v68, v24
	v_mov_b32_e32 v69, v24
	v_mov_b32_e32 v70, v24
	v_mov_b32_e32 v71, v24
	v_mov_b32_e32 v80, v24
	v_mov_b32_e32 v81, v24
	v_mov_b32_e32 v82, v24
	v_mov_b32_e32 v83, v24
	v_mov_b32_e32 v56, v24
	v_mov_b32_e32 v57, v24
	v_mov_b32_e32 v58, v24
	v_mov_b32_e32 v59, v24
	v_mov_b32_e32 v132, v24
	v_mov_b32_e32 v133, v24
	v_mov_b32_e32 v134, v24
	v_mov_b32_e32 v135, v24
	v_mov_b32_e32 v136, v24
	v_mov_b32_e32 v137, v24
	v_mov_b32_e32 v138, v24
	v_mov_b32_e32 v139, v24
	v_mov_b32_e32 v140, v24
	v_mov_b32_e32 v141, v24
	v_mov_b32_e32 v142, v24
	v_mov_b32_e32 v143, v24
	v_mov_b32_e32 v144, v24
	v_mov_b32_e32 v145, v24
	v_mov_b32_e32 v146, v24
	v_mov_b32_e32 v147, v24
	v_mov_b32_e32 v76, v24
	v_mov_b32_e32 v77, v24
	v_mov_b32_e32 v78, v24
	v_mov_b32_e32 v79, v24
	v_mov_b32_e32 v72, v24
	v_mov_b32_e32 v73, v24
	v_mov_b32_e32 v74, v24
	v_mov_b32_e32 v75, v24
	v_mov_b32_e32 v60, v24
	v_mov_b32_e32 v61, v24
	v_mov_b32_e32 v62, v24
	v_mov_b32_e32 v63, v24
	v_mov_b32_e32 v148, v24
	v_mov_b32_e32 v149, v24
	v_mov_b32_e32 v150, v24
	v_mov_b32_e32 v151, v24
	s_waitcnt vmcnt(12)
	s_barrier
	s_mov_b32 s30, 0
	v_add_u32_e32 v248, s30, v155
	v_add_u32_e32 v249, s30, v160
	ds_read_b128 v[186:189], v248
	ds_read_b128 v[212:215], v249 offset:8192
	ds_read_b128 v[190:193], v248 offset:1024
	ds_read_b128 v[216:219], v249 offset:9216
	ds_read_b128 v[194:197], v248 offset:2048
	ds_read_b128 v[220:223], v249 offset:10240
	ds_read_b128 v[208:211], v248 offset:3072
	ds_read_b128 v[224:227], v249 offset:11264
	ds_read_b128 v[228:231], v249 offset:12288
	ds_read_b128 v[232:235], v249 offset:13312
	ds_read_b128 v[236:239], v249 offset:14336
	ds_read_b128 v[240:243], v249 offset:15360
	s_add_u32 s30, s30, 24576
	s_cmp_eq_u32 s30, 73728
	s_cselect_b32 s30, 0, s30
	s_waitcnt lgkmcnt(0)
	s_mov_b32 s31, 14
.Lgm0_loop:
	v_mfma_f32_16x16x32_bf16 v[128:131], v[212:215], v[186:189], v[128:131]
	v_mfma_f32_16x16x32_bf16 v[96:99], v[212:215], v[190:193], v[96:99]
	v_mfma_f32_16x16x32_bf16 v[108:111], v[212:215], v[194:197], v[108:111]
	v_mfma_f32_16x16x32_bf16 v[132:135], v[212:215], v[208:211], v[132:135]
	v_mfma_f32_16x16x32_bf16 v[116:119], v[216:219], v[186:189], v[116:119]
	v_mfma_f32_16x16x32_bf16 v[92:95], v[216:219], v[190:193], v[92:95]
	v_mfma_f32_16x16x32_bf16 v[112:115], v[216:219], v[194:197], v[112:115]
	v_mfma_f32_16x16x32_bf16 v[136:139], v[216:219], v[208:211], v[136:139]
	v_mfma_f32_16x16x32_bf16 v[104:107], v[220:223], v[186:189], v[104:107]
	v_mfma_f32_16x16x32_bf16 v[88:91], v[220:223], v[190:193], v[88:91]
	v_mfma_f32_16x16x32_bf16 v[120:123], v[220:223], v[194:197], v[120:123]
	v_mfma_f32_16x16x32_bf16 v[140:143], v[220:223], v[208:211], v[140:143]
	v_mfma_f32_16x16x32_bf16 v[100:103], v[224:227], v[186:189], v[100:103]
	v_mfma_f32_16x16x32_bf16 v[84:87], v[224:227], v[190:193], v[84:87]
	v_mfma_f32_16x16x32_bf16 v[124:127], v[224:227], v[194:197], v[124:127]
	v_mfma_f32_16x16x32_bf16 v[144:147], v[224:227], v[208:211], v[144:147]
	s_waitcnt vmcnt(6)
	s_barrier
	v_add_u32_e32 v248, s30, v155
	v_add_u32_e32 v249, s30, v160
	v_mfma_f32_16x16x32_bf16 v[52:55], v[228:231], v[186:189], v[52:55]
	ds_read_b128 v[0:3], v248
	s_add_u32 m0, s25, s24
	v_mfma_f32_16x16x32_bf16 v[36:39], v[228:231], v[190:193], v[36:39]
	ds_read_b128 v[16:19], v249 offset:8192
	global_load_lds_dwordx4 v156, s[26:27]
	v_mfma_f32_16x16x32_bf16 v[64:67], v[228:231], v[194:197], v[64:67]
	ds_read_b128 v[4:7], v248 offset:1024
	s_add_u32 m0, m0, 0x1000
	v_mfma_f32_16x16x32_bf16 v[76:79], v[228:231], v[208:211], v[76:79]
	ds_read_b128 v[20:23], v249 offset:9216
	global_load_lds_dwordx4 v157, s[26:27]
	v_mfma_f32_16x16x32_bf16 v[48:51], v[232:235], v[186:189], v[48:51]
	ds_read_b128 v[8:11], v248 offset:2048
	s_add_u32 m0, m0, 0x1000
	v_mfma_f32_16x16x32_bf16 v[32:35], v[232:235], v[190:193], v[32:35]
	ds_read_b128 v[162:165], v249 offset:10240
	global_load_lds_dwordx4 v156, s[28:29]
	v_mfma_f32_16x16x32_bf16 v[68:71], v[232:235], v[194:197], v[68:71]
	ds_read_b128 v[12:15], v248 offset:3072
	s_add_u32 m0, m0, 0x1000
	v_mfma_f32_16x16x32_bf16 v[72:75], v[232:235], v[208:211], v[72:75]
	ds_read_b128 v[166:169], v249 offset:11264
	global_load_lds_dwordx4 v157, s[28:29]
	v_mfma_f32_16x16x32_bf16 v[44:47], v[236:239], v[186:189], v[44:47]
	ds_read_b128 v[170:173], v249 offset:12288
	s_add_u32 m0, m0, 0x1000
	v_mfma_f32_16x16x32_bf16 v[28:31], v[236:239], v[190:193], v[28:31]
	ds_read_b128 v[174:177], v249 offset:13312
	global_load_lds_dwordx4 v158, s[28:29]
	v_mfma_f32_16x16x32_bf16 v[80:83], v[236:239], v[194:197], v[80:83]
	ds_read_b128 v[178:181], v249 offset:14336
	s_add_u32 m0, m0, 0x1000
	v_mfma_f32_16x16x32_bf16 v[60:63], v[236:239], v[208:211], v[60:63]
	ds_read_b128 v[182:185], v249 offset:15360
	global_load_lds_dwordx4 v159, s[28:29]
	v_mfma_f32_16x16x32_bf16 v[40:43], v[240:243], v[186:189], v[40:43]
	v_mfma_f32_16x16x32_bf16 v[24:27], v[240:243], v[190:193], v[24:27]
	v_mfma_f32_16x16x32_bf16 v[56:59], v[240:243], v[194:197], v[56:59]
	v_mfma_f32_16x16x32_bf16 v[148:151], v[240:243], v[208:211], v[148:151]
	s_add_u32 s26, s26, 0x200000
	s_addc_u32 s27, s27, 0
	s_add_u32 s28, s28, 0x40000
	s_addc_u32 s29, s29, 0
	s_add_u32 s25, s25, 24576
	s_cmp_eq_u32 s25, 73728
	s_cselect_b32 s25, 0, s25
	s_add_u32 s30, s30, 24576
	s_cmp_eq_u32 s30, 73728
	s_cselect_b32 s30, 0, s30
	s_waitcnt lgkmcnt(0)
	v_mfma_f32_16x16x32_bf16 v[128:131], v[16:19], v[0:3], v[128:131]
	v_mfma_f32_16x16x32_bf16 v[96:99], v[16:19], v[4:7], v[96:99]
	v_mfma_f32_16x16x32_bf16 v[108:111], v[16:19], v[8:11], v[108:111]
	v_mfma_f32_16x16x32_bf16 v[132:135], v[16:19], v[12:15], v[132:135]
	v_mfma_f32_16x16x32_bf16 v[116:119], v[20:23], v[0:3], v[116:119]
	v_mfma_f32_16x16x32_bf16 v[92:95], v[20:23], v[4:7], v[92:95]
	v_mfma_f32_16x16x32_bf16 v[112:115], v[20:23], v[8:11], v[112:115]
	v_mfma_f32_16x16x32_bf16 v[136:139], v[20:23], v[12:15], v[136:139]
	v_mfma_f32_16x16x32_bf16 v[104:107], v[162:165], v[0:3], v[104:107]
	v_mfma_f32_16x16x32_bf16 v[88:91], v[162:165], v[4:7], v[88:91]
	v_mfma_f32_16x16x32_bf16 v[120:123], v[162:165], v[8:11], v[120:123]
	v_mfma_f32_16x16x32_bf16 v[140:143], v[162:165], v[12:15], v[140:143]
	v_mfma_f32_16x16x32_bf16 v[100:103], v[166:169], v[0:3], v[100:103]
	v_mfma_f32_16x16x32_bf16 v[84:87], v[166:169], v[4:7], v[84:87]
	v_mfma_f32_16x16x32_bf16 v[124:127], v[166:169], v[8:11], v[124:127]
	v_mfma_f32_16x16x32_bf16 v[144:147], v[166:169], v[12:15], v[144:147]
	s_waitcnt vmcnt(6)
	s_barrier
	v_add_u32_e32 v248, s30, v155
	v_add_u32_e32 v249, s30, v160
	v_mfma_f32_16x16x32_bf16 v[52:55], v[170:173], v[0:3], v[52:55]
	ds_read_b128 v[186:189], v248
	s_add_u32 m0, s25, s24
	v_mfma_f32_16x16x32_bf16 v[36:39], v[170:173], v[4:7], v[36:39]
	ds_read_b128 v[212:215], v249 offset:8192
	global_load_lds_dwordx4 v156, s[26:27]
	v_mfma_f32_16x16x32_bf16 v[64:67], v[170:173], v[8:11], v[64:67]
	ds_read_b128 v[190:193], v248 offset:1024
	s_add_u32 m0, m0, 0x1000
	v_mfma_f32_16x16x32_bf16 v[76:79], v[170:173], v[12:15], v[76:79]
	ds_read_b128 v[216:219], v249 offset:9216
	global_load_lds_dwordx4 v157, s[26:27]
	v_mfma_f32_16x16x32_bf16 v[48:51], v[174:177], v[0:3], v[48:51]
	ds_read_b128 v[194:197], v248 offset:2048
	s_add_u32 m0, m0, 0x1000
	v_mfma_f32_16x16x32_bf16 v[32:35], v[174:177], v[4:7], v[32:35]
	ds_read_b128 v[220:223], v249 offset:10240
	global_load_lds_dwordx4 v156, s[28:29]
	v_mfma_f32_16x16x32_bf16 v[68:71], v[174:177], v[8:11], v[68:71]
	ds_read_b128 v[208:211], v248 offset:3072
	s_add_u32 m0, m0, 0x1000
	v_mfma_f32_16x16x32_bf16 v[72:75], v[174:177], v[12:15], v[72:75]
	ds_read_b128 v[224:227], v249 offset:11264
	global_load_lds_dwordx4 v157, s[28:29]
	v_mfma_f32_16x16x32_bf16 v[44:47], v[178:181], v[0:3], v[44:47]
	ds_read_b128 v[228:231], v249 offset:12288
	s_add_u32 m0, m0, 0x1000
	v_mfma_f32_16x16x32_bf16 v[28:31], v[178:181], v[4:7], v[28:31]
	ds_read_b128 v[232:235], v249 offset:13312
	global_load_lds_dwordx4 v158, s[28:29]
	v_mfma_f32_16x16x32_bf16 v[80:83], v[178:181], v[8:11], v[80:83]
	ds_read_b128 v[236:239], v249 offset:14336
	s_add_u32 m0, m0, 0x1000
	v_mfma_f32_16x16x32_bf16 v[60:63], v[178:181], v[12:15], v[60:63]
	ds_read_b128 v[240:243], v249 offset:15360
	global_load_lds_dwordx4 v159, s[28:29]
	v_mfma_f32_16x16x32_bf16 v[40:43], v[182:185], v[0:3], v[40:43]
	v_mfma_f32_16x16x32_bf16 v[24:27], v[182:185], v[4:7], v[24:27]
	v_mfma_f32_16x16x32_bf16 v[56:59], v[182:185], v[8:11], v[56:59]
	v_mfma_f32_16x16x32_bf16 v[148:151], v[182:185], v[12:15], v[148:151]
	s_add_u32 s26, s26, 0x200000
	s_addc_u32 s27, s27, 0
	s_add_u32 s28, s28, 0x40000
	s_addc_u32 s29, s29, 0
	s_add_u32 s25, s25, 24576
	s_cmp_eq_u32 s25, 73728
	s_cselect_b32 s25, 0, s25
	s_add_u32 s30, s30, 24576
	s_cmp_eq_u32 s30, 73728
	s_cselect_b32 s30, 0, s30
	s_waitcnt lgkmcnt(0)
	s_sub_u32 s31, s31, 1
	s_cmp_lg_u32 s31, 0
	s_cbranch_scc1 .Lgm0_loop
	v_mfma_f32_16x16x32_bf16 v[128:131], v[212:215], v[186:189], v[128:131]
	v_mfma_f32_16x16x32_bf16 v[96:99], v[212:215], v[190:193], v[96:99]
	v_mfma_f32_16x16x32_bf16 v[108:111], v[212:215], v[194:197], v[108:111]
	v_mfma_f32_16x16x32_bf16 v[132:135], v[212:215], v[208:211], v[132:135]
	v_mfma_f32_16x16x32_bf16 v[116:119], v[216:219], v[186:189], v[116:119]
	v_mfma_f32_16x16x32_bf16 v[92:95], v[216:219], v[190:193], v[92:95]
	v_mfma_f32_16x16x32_bf16 v[112:115], v[216:219], v[194:197], v[112:115]
	v_mfma_f32_16x16x32_bf16 v[136:139], v[216:219], v[208:211], v[136:139]
	v_mfma_f32_16x16x32_bf16 v[104:107], v[220:223], v[186:189], v[104:107]
	v_mfma_f32_16x16x32_bf16 v[88:91], v[220:223], v[190:193], v[88:91]
	v_mfma_f32_16x16x32_bf16 v[120:123], v[220:223], v[194:197], v[120:123]
	v_mfma_f32_16x16x32_bf16 v[140:143], v[220:223], v[208:211], v[140:143]
	v_mfma_f32_16x16x32_bf16 v[100:103], v[224:227], v[186:189], v[100:103]
	v_mfma_f32_16x16x32_bf16 v[84:87], v[224:227], v[190:193], v[84:87]
	v_mfma_f32_16x16x32_bf16 v[124:127], v[224:227], v[194:197], v[124:127]
	v_mfma_f32_16x16x32_bf16 v[144:147], v[224:227], v[208:211], v[144:147]
	s_waitcnt vmcnt(6)
	s_barrier
	v_add_u32_e32 v248, s30, v155
	v_add_u32_e32 v249, s30, v160
	v_mfma_f32_16x16x32_bf16 v[52:55], v[228:231], v[186:189], v[52:55]
	ds_read_b128 v[0:3], v248
	s_add_u32 m0, s25, s24
	v_mfma_f32_16x16x32_bf16 v[36:39], v[228:231], v[190:193], v[36:39]
	ds_read_b128 v[16:19], v249 offset:8192
	global_load_lds_dwordx4 v156, s[26:27]
	v_mfma_f32_16x16x32_bf16 v[64:67], v[228:231], v[194:197], v[64:67]
	ds_read_b128 v[4:7], v248 offset:1024
	s_add_u32 m0, m0, 0x1000
	v_mfma_f32_16x16x32_bf16 v[76:79], v[228:231], v[208:211], v[76:79]
	ds_read_b128 v[20:23], v249 offset:9216
	global_load_lds_dwordx4 v157, s[26:27]
	v_mfma_f32_16x16x32_bf16 v[48:51], v[232:235], v[186:189], v[48:51]
	ds_read_b128 v[8:11], v248 offset:2048
	s_add_u32 m0, m0, 0x1000
	v_mfma_f32_16x16x32_bf16 v[32:35], v[232:235], v[190:193], v[32:35]
	ds_read_b128 v[162:165], v249 offset:10240
	global_load_lds_dwordx4 v156, s[28:29]
	v_mfma_f32_16x16x32_bf16 v[68:71], v[232:235], v[194:197], v[68:71]
	ds_read_b128 v[12:15], v248 offset:3072
	s_add_u32 m0, m0, 0x1000
	v_mfma_f32_16x16x32_bf16 v[72:75], v[232:235], v[208:211], v[72:75]
	ds_read_b128 v[166:169], v249 offset:11264
	global_load_lds_dwordx4 v157, s[28:29]
	v_mfma_f32_16x16x32_bf16 v[44:47], v[236:239], v[186:189], v[44:47]
	ds_read_b128 v[170:173], v249 offset:12288
	s_add_u32 m0, m0, 0x1000
	v_mfma_f32_16x16x32_bf16 v[28:31], v[236:239], v[190:193], v[28:31]
	ds_read_b128 v[174:177], v249 offset:13312
	global_load_lds_dwordx4 v158, s[28:29]
	v_mfma_f32_16x16x32_bf16 v[80:83], v[236:239], v[194:197], v[80:83]
	ds_read_b128 v[178:181], v249 offset:14336
	s_add_u32 m0, m0, 0x1000
	v_mfma_f32_16x16x32_bf16 v[60:63], v[236:239], v[208:211], v[60:63]
	ds_read_b128 v[182:185], v249 offset:15360
	global_load_lds_dwordx4 v159, s[28:29]
	v_mfma_f32_16x16x32_bf16 v[40:43], v[240:243], v[186:189], v[40:43]
	v_mfma_f32_16x16x32_bf16 v[24:27], v[240:243], v[190:193], v[24:27]
	v_mfma_f32_16x16x32_bf16 v[56:59], v[240:243], v[194:197], v[56:59]
	v_mfma_f32_16x16x32_bf16 v[148:151], v[240:243], v[208:211], v[148:151]
	s_add_u32 s26, s26, 0x200000
	s_addc_u32 s27, s27, 0
	s_add_u32 s28, s28, 0x40000
	s_addc_u32 s29, s29, 0
	s_add_u32 s25, s25, 24576
	s_cmp_eq_u32 s25, 73728
	s_cselect_b32 s25, 0, s25
	s_add_u32 s30, s30, 24576
	s_cmp_eq_u32 s30, 73728
	s_cselect_b32 s30, 0, s30
	s_waitcnt lgkmcnt(0)
	v_mfma_f32_16x16x32_bf16 v[128:131], v[16:19], v[0:3], v[128:131]
	v_mfma_f32_16x16x32_bf16 v[96:99], v[16:19], v[4:7], v[96:99]
	v_mfma_f32_16x16x32_bf16 v[108:111], v[16:19], v[8:11], v[108:111]
	v_mfma_f32_16x16x32_bf16 v[132:135], v[16:19], v[12:15], v[132:135]
	v_mfma_f32_16x16x32_bf16 v[116:119], v[20:23], v[0:3], v[116:119]
	v_mfma_f32_16x16x32_bf16 v[92:95], v[20:23], v[4:7], v[92:95]
	v_mfma_f32_16x16x32_bf16 v[112:115], v[20:23], v[8:11], v[112:115]
	v_mfma_f32_16x16x32_bf16 v[136:139], v[20:23], v[12:15], v[136:139]
	v_mfma_f32_16x16x32_bf16 v[104:107], v[162:165], v[0:3], v[104:107]
	v_mfma_f32_16x16x32_bf16 v[88:91], v[162:165], v[4:7], v[88:91]
	v_mfma_f32_16x16x32_bf16 v[120:123], v[162:165], v[8:11], v[120:123]
	v_mfma_f32_16x16x32_bf16 v[140:143], v[162:165], v[12:15], v[140:143]
	v_mfma_f32_16x16x32_bf16 v[100:103], v[166:169], v[0:3], v[100:103]
	v_mfma_f32_16x16x32_bf16 v[84:87], v[166:169], v[4:7], v[84:87]
	v_mfma_f32_16x16x32_bf16 v[124:127], v[166:169], v[8:11], v[124:127]
	v_mfma_f32_16x16x32_bf16 v[144:147], v[166:169], v[12:15], v[144:147]
	s_waitcnt vmcnt(6)
	s_barrier
	v_add_u32_e32 v248, s30, v155
	v_add_u32_e32 v249, s30, v160
	v_mfma_f32_16x16x32_bf16 v[52:55], v[170:173], v[0:3], v[52:55]
	ds_read_b128 v[186:189], v248
	v_mfma_f32_16x16x32_bf16 v[36:39], v[170:173], v[4:7], v[36:39]
	ds_read_b128 v[212:215], v249 offset:8192
	v_mfma_f32_16x16x32_bf16 v[64:67], v[170:173], v[8:11], v[64:67]
	ds_read_b128 v[190:193], v248 offset:1024
	v_mfma_f32_16x16x32_bf16 v[76:79], v[170:173], v[12:15], v[76:79]
	ds_read_b128 v[216:219], v249 offset:9216
	v_mfma_f32_16x16x32_bf16 v[48:51], v[174:177], v[0:3], v[48:51]
	ds_read_b128 v[194:197], v248 offset:2048
	v_mfma_f32_16x16x32_bf16 v[32:35], v[174:177], v[4:7], v[32:35]
	ds_read_b128 v[220:223], v249 offset:10240
	v_mfma_f32_16x16x32_bf16 v[68:71], v[174:177], v[8:11], v[68:71]
	ds_read_b128 v[208:211], v248 offset:3072
	v_mfma_f32_16x16x32_bf16 v[72:75], v[174:177], v[12:15], v[72:75]
	ds_read_b128 v[224:227], v249 offset:11264
	v_mfma_f32_16x16x32_bf16 v[44:47], v[178:181], v[0:3], v[44:47]
	ds_read_b128 v[228:231], v249 offset:12288
	v_mfma_f32_16x16x32_bf16 v[28:31], v[178:181], v[4:7], v[28:31]
	ds_read_b128 v[232:235], v249 offset:13312
	v_mfma_f32_16x16x32_bf16 v[80:83], v[178:181], v[8:11], v[80:83]
	ds_read_b128 v[236:239], v249 offset:14336
	v_mfma_f32_16x16x32_bf16 v[60:63], v[178:181], v[12:15], v[60:63]
	ds_read_b128 v[240:243], v249 offset:15360
	v_mfma_f32_16x16x32_bf16 v[40:43], v[182:185], v[0:3], v[40:43]
	v_mfma_f32_16x16x32_bf16 v[24:27], v[182:185], v[4:7], v[24:27]
	v_mfma_f32_16x16x32_bf16 v[56:59], v[182:185], v[8:11], v[56:59]
	v_mfma_f32_16x16x32_bf16 v[148:151], v[182:185], v[12:15], v[148:151]
	s_add_u32 s30, s30, 24576
	s_cmp_eq_u32 s30, 73728
	s_cselect_b32 s30, 0, s30
	s_waitcnt lgkmcnt(0)
	v_mfma_f32_16x16x32_bf16 v[128:131], v[212:215], v[186:189], v[128:131]
	v_mfma_f32_16x16x32_bf16 v[96:99], v[212:215], v[190:193], v[96:99]
	v_mfma_f32_16x16x32_bf16 v[108:111], v[212:215], v[194:197], v[108:111]
	v_mfma_f32_16x16x32_bf16 v[132:135], v[212:215], v[208:211], v[132:135]
	v_mfma_f32_16x16x32_bf16 v[116:119], v[216:219], v[186:189], v[116:119]
	v_mfma_f32_16x16x32_bf16 v[92:95], v[216:219], v[190:193], v[92:95]
	v_mfma_f32_16x16x32_bf16 v[112:115], v[216:219], v[194:197], v[112:115]
	v_mfma_f32_16x16x32_bf16 v[136:139], v[216:219], v[208:211], v[136:139]
	v_mfma_f32_16x16x32_bf16 v[104:107], v[220:223], v[186:189], v[104:107]
	v_mfma_f32_16x16x32_bf16 v[88:91], v[220:223], v[190:193], v[88:91]
	v_mfma_f32_16x16x32_bf16 v[120:123], v[220:223], v[194:197], v[120:123]
	v_mfma_f32_16x16x32_bf16 v[140:143], v[220:223], v[208:211], v[140:143]
	v_mfma_f32_16x16x32_bf16 v[100:103], v[224:227], v[186:189], v[100:103]
	v_mfma_f32_16x16x32_bf16 v[84:87], v[224:227], v[190:193], v[84:87]
	v_mfma_f32_16x16x32_bf16 v[124:127], v[224:227], v[194:197], v[124:127]
	v_mfma_f32_16x16x32_bf16 v[144:147], v[224:227], v[208:211], v[144:147]
	s_waitcnt vmcnt(0)
	s_barrier
	v_add_u32_e32 v248, s30, v155
	v_add_u32_e32 v249, s30, v160
	v_mfma_f32_16x16x32_bf16 v[52:55], v[228:231], v[186:189], v[52:55]
	ds_read_b128 v[0:3], v248
	v_mfma_f32_16x16x32_bf16 v[36:39], v[228:231], v[190:193], v[36:39]
	ds_read_b128 v[16:19], v249 offset:8192
	v_mfma_f32_16x16x32_bf16 v[64:67], v[228:231], v[194:197], v[64:67]
	ds_read_b128 v[4:7], v248 offset:1024
	v_mfma_f32_16x16x32_bf16 v[76:79], v[228:231], v[208:211], v[76:79]
	ds_read_b128 v[20:23], v249 offset:9216
	v_mfma_f32_16x16x32_bf16 v[48:51], v[232:235], v[186:189], v[48:51]
	ds_read_b128 v[8:11], v248 offset:2048
	v_mfma_f32_16x16x32_bf16 v[32:35], v[232:235], v[190:193], v[32:35]
	ds_read_b128 v[162:165], v249 offset:10240
	v_mfma_f32_16x16x32_bf16 v[68:71], v[232:235], v[194:197], v[68:71]
	ds_read_b128 v[12:15], v248 offset:3072
	v_mfma_f32_16x16x32_bf16 v[72:75], v[232:235], v[208:211], v[72:75]
	ds_read_b128 v[166:169], v249 offset:11264
	v_mfma_f32_16x16x32_bf16 v[44:47], v[236:239], v[186:189], v[44:47]
	ds_read_b128 v[170:173], v249 offset:12288
	v_mfma_f32_16x16x32_bf16 v[28:31], v[236:239], v[190:193], v[28:31]
	ds_read_b128 v[174:177], v249 offset:13312
	v_mfma_f32_16x16x32_bf16 v[80:83], v[236:239], v[194:197], v[80:83]
	ds_read_b128 v[178:181], v249 offset:14336
	v_mfma_f32_16x16x32_bf16 v[60:63], v[236:239], v[208:211], v[60:63]
	ds_read_b128 v[182:185], v249 offset:15360
	v_mfma_f32_16x16x32_bf16 v[40:43], v[240:243], v[186:189], v[40:43]
	v_mfma_f32_16x16x32_bf16 v[24:27], v[240:243], v[190:193], v[24:27]
	v_mfma_f32_16x16x32_bf16 v[56:59], v[240:243], v[194:197], v[56:59]
	v_mfma_f32_16x16x32_bf16 v[148:151], v[240:243], v[208:211], v[148:151]
	s_add_u32 s30, s30, 24576
	s_cmp_eq_u32 s30, 73728
	s_cselect_b32 s30, 0, s30
	s_waitcnt lgkmcnt(0)
	v_mfma_f32_16x16x32_bf16 v[128:131], v[16:19], v[0:3], v[128:131]
	v_mfma_f32_16x16x32_bf16 v[96:99], v[16:19], v[4:7], v[96:99]
	v_mfma_f32_16x16x32_bf16 v[108:111], v[16:19], v[8:11], v[108:111]
	v_mfma_f32_16x16x32_bf16 v[132:135], v[16:19], v[12:15], v[132:135]
	v_mfma_f32_16x16x32_bf16 v[116:119], v[20:23], v[0:3], v[116:119]
	v_mfma_f32_16x16x32_bf16 v[92:95], v[20:23], v[4:7], v[92:95]
	v_mfma_f32_16x16x32_bf16 v[112:115], v[20:23], v[8:11], v[112:115]
	v_mfma_f32_16x16x32_bf16 v[136:139], v[20:23], v[12:15], v[136:139]
	v_mfma_f32_16x16x32_bf16 v[104:107], v[162:165], v[0:3], v[104:107]
	v_mfma_f32_16x16x32_bf16 v[88:91], v[162:165], v[4:7], v[88:91]
	v_mfma_f32_16x16x32_bf16 v[120:123], v[162:165], v[8:11], v[120:123]
	v_mfma_f32_16x16x32_bf16 v[140:143], v[162:165], v[12:15], v[140:143]
	v_mfma_f32_16x16x32_bf16 v[100:103], v[166:169], v[0:3], v[100:103]
	v_mfma_f32_16x16x32_bf16 v[84:87], v[166:169], v[4:7], v[84:87]
	v_mfma_f32_16x16x32_bf16 v[124:127], v[166:169], v[8:11], v[124:127]
	v_mfma_f32_16x16x32_bf16 v[144:147], v[166:169], v[12:15], v[144:147]
	v_mfma_f32_16x16x32_bf16 v[52:55], v[170:173], v[0:3], v[52:55]
	v_mfma_f32_16x16x32_bf16 v[36:39], v[170:173], v[4:7], v[36:39]
	v_mfma_f32_16x16x32_bf16 v[64:67], v[170:173], v[8:11], v[64:67]
	v_mfma_f32_16x16x32_bf16 v[76:79], v[170:173], v[12:15], v[76:79]
	v_mfma_f32_16x16x32_bf16 v[48:51], v[174:177], v[0:3], v[48:51]
	v_mfma_f32_16x16x32_bf16 v[32:35], v[174:177], v[4:7], v[32:35]
	v_mfma_f32_16x16x32_bf16 v[68:71], v[174:177], v[8:11], v[68:71]
	v_mfma_f32_16x16x32_bf16 v[72:75], v[174:177], v[12:15], v[72:75]
	v_mfma_f32_16x16x32_bf16 v[44:47], v[178:181], v[0:3], v[44:47]
	v_mfma_f32_16x16x32_bf16 v[28:31], v[178:181], v[4:7], v[28:31]
	v_mfma_f32_16x16x32_bf16 v[80:83], v[178:181], v[8:11], v[80:83]
	v_mfma_f32_16x16x32_bf16 v[60:63], v[178:181], v[12:15], v[60:63]
	v_mfma_f32_16x16x32_bf16 v[40:43], v[182:185], v[0:3], v[40:43]
	v_mfma_f32_16x16x32_bf16 v[24:27], v[182:185], v[4:7], v[24:27]
	v_mfma_f32_16x16x32_bf16 v[56:59], v[182:185], v[8:11], v[56:59]
	v_mfma_f32_16x16x32_bf16 v[148:151], v[182:185], v[12:15], v[148:151]
	s_add_i32 s12, s12, s6
	s_add_i32 s11, s11, s9
	s_add_i32 s10, s10, s6
	s_cmpk_gt_u32 s12, 0x1ff
	s_cselect_b32 s23, 1, 0
	v_mov_b32 v250, v198
	s_nop 0
	v_and_b32_e32 v251, 15, v250
	v_bfe_u32 v156, v250, 4, 2
	v_bfe_u32 v157, v250, 6, 1
	v_bfe_u32 v158, v250, 7, 1
	v_lshl_add_u32 v158, v158, 6, s14
	v_add_u32_e32 v158, v158, v251
	v_lshl_add_u32 v157, v157, 7, s13
	v_lshl_add_u32 v159, v156, 2, v157
	v_lshlrev_b32_e32 v230, 6, v158
	v_lshrrev_b32_e32 v228, 5, v157
	v_lshlrev_b32_e32 v228, 21, v228
	v_lshl_add_u32 v228, v158, 6, v228
	v_lshl_add_u32 v228, v156, 3, v228
	v_and_b32_e32 v161, 1, v156
	v_mul_u32_u24_e32 v161, 24, v161
	v_add_u32_e32 v229, v228, v161
	s_mov_b32 s30, s92
	s_mov_b32 s31, s93
	global_load_dwordx4 v[0:3], v230, s[94:95]
	global_load_dwordx4 v[4:7], v230, s[94:95] offset:16
	global_load_dwordx4 v[8:11], v230, s[94:95] offset:32
	global_load_dwordx4 v[12:15], v230, s[94:95] offset:48
	global_load_dwordx4 v[16:19], v230, s[94:95] offset:1024
	global_load_dwordx4 v[20:23], v230, s[94:95] offset:1040
	global_load_dwordx4 v[162:165], v230, s[94:95] offset:1056
	global_load_dwordx4 v[166:169], v230, s[94:95] offset:1072
	global_load_dwordx4 v[170:173], v230, s[94:95] offset:2048
	global_load_dwordx4 v[174:177], v230, s[94:95] offset:2064
	global_load_dwordx4 v[178:181], v230, s[94:95] offset:2080
	global_load_dwordx4 v[182:185], v230, s[94:95] offset:2096
	global_load_dwordx4 v[186:189], v230, s[94:95] offset:3072
	global_load_dwordx4 v[190:193], v230, s[94:95] offset:3088
	global_load_dwordx4 v[194:197], v230, s[94:95] offset:3104
	global_load_dwordx4 v[208:211], v230, s[94:95] offset:3120
	s_waitcnt vmcnt(12)
	v_add_f32_e32 v231, v0, v1
	v_add_f32_e32 v248, v2, v3
	v_add_f32_e32 v231, v231, v248
	v_add_f32_e32 v249, v4, v5
	v_add_f32_e32 v248, v6, v7
	v_add_f32_e32 v249, v249, v248
	v_add_f32_e32 v231, v231, v249
	v_add_f32_e32 v249, v8, v9
	v_add_f32_e32 v248, v10, v11
	v_add_f32_e32 v249, v249, v248
	v_add_f32_e32 v231, v231, v249
	v_add_f32_e32 v249, v12, v13
	v_add_f32_e32 v248, v14, v15
	v_add_f32_e32 v249, v249, v248
	v_add_f32_e32 v231, v231, v249
	v_fmamk_f32 v231, v231, 0x3a800000, v199
	v_cmp_gt_f32_e32 vcc, s73, v231
	v_mul_f32_e32 v248, 0x4b800000, v231
	s_nop 0
	v_cndmask_b32_e32 v231, v231, v248, vcc
	v_rsq_f32_e32 v231, v231
	s_nop 0
	v_mul_f32_e32 v248, 0x45800000, v231
	v_cndmask_b32_e32 v231, v231, v248, vcc
	v_mul_f32_e32 v212, v128, v231
	v_mul_f32_e32 v249, v129, v231
	v_mul_f32_e32 v213, v130, v231
	v_mul_f32_e32 v248, v131, v231
	v_max_f32_e32 v212, 0, v212
	v_max_f32_e32 v249, 0, v249
	v_max_f32_e32 v213, 0, v213
	v_max_f32_e32 v248, 0, v248
	v_mul_f32_e32 v212, v212, v212
	v_mul_f32_e32 v249, v249, v249
	v_mul_f32_e32 v213, v213, v213
	v_mul_f32_e32 v248, v248, v248
	v_cvt_pk_bf16_f32 v212, v212, v249
	v_cvt_pk_bf16_f32 v213, v213, v248
	v_mul_f32_e32 v214, v116, v231
	v_mul_f32_e32 v249, v117, v231
	v_mul_f32_e32 v215, v118, v231
	v_mul_f32_e32 v248, v119, v231
	v_max_f32_e32 v214, 0, v214
	v_max_f32_e32 v249, 0, v249
	v_max_f32_e32 v215, 0, v215
	v_max_f32_e32 v248, 0, v248
	v_mul_f32_e32 v214, v214, v214
	v_mul_f32_e32 v249, v249, v249
	v_mul_f32_e32 v215, v215, v215
	v_mul_f32_e32 v248, v248, v248
	v_cvt_pk_bf16_f32 v214, v214, v249
	v_cvt_pk_bf16_f32 v215, v215, v248
	s_add_u32 s30, s92, 0x0
	s_addc_u32 s31, s93, 0
	s_nop 0
	v_permlane16_swap_b32_e32 v212, v214
	v_permlane16_swap_b32_e32 v213, v215
	global_store_dwordx4 v229, v[212:215], s[30:31]
	v_mul_f32_e32 v216, v104, v231
	v_mul_f32_e32 v249, v105, v231
	v_mul_f32_e32 v217, v106, v231
	v_mul_f32_e32 v248, v107, v231
	v_max_f32_e32 v216, 0, v216
	v_max_f32_e32 v249, 0, v249
	v_max_f32_e32 v217, 0, v217
	v_max_f32_e32 v248, 0, v248
	v_mul_f32_e32 v216, v216, v216
	v_mul_f32_e32 v249, v249, v249
	v_mul_f32_e32 v217, v217, v217
	v_mul_f32_e32 v248, v248, v248
	v_cvt_pk_bf16_f32 v216, v216, v249
	v_cvt_pk_bf16_f32 v217, v217, v248
	v_mul_f32_e32 v218, v100, v231
	v_mul_f32_e32 v249, v101, v231
	v_mul_f32_e32 v219, v102, v231
	v_mul_f32_e32 v248, v103, v231
	v_max_f32_e32 v218, 0, v218
	v_max_f32_e32 v249, 0, v249
	v_max_f32_e32 v219, 0, v219
	v_max_f32_e32 v248, 0, v248
	v_mul_f32_e32 v218, v218, v218
	v_mul_f32_e32 v249, v249, v249
	v_mul_f32_e32 v219, v219, v219
	v_mul_f32_e32 v248, v248, v248
	v_cvt_pk_bf16_f32 v218, v218, v249
	v_cvt_pk_bf16_f32 v219, v219, v248
	s_add_u32 s30, s92, 0x200000
	s_addc_u32 s31, s93, 0
	s_nop 0
	v_permlane16_swap_b32_e32 v216, v218
	v_permlane16_swap_b32_e32 v217, v219
	global_store_dwordx4 v229, v[216:219], s[30:31]
	v_mul_f32_e32 v220, v52, v231
	v_mul_f32_e32 v249, v53, v231
	v_mul_f32_e32 v221, v54, v231
	v_mul_f32_e32 v248, v55, v231
	v_max_f32_e32 v220, 0, v220
	v_max_f32_e32 v249, 0, v249
	v_max_f32_e32 v221, 0, v221
	v_max_f32_e32 v248, 0, v248
	v_mul_f32_e32 v220, v220, v220
	v_mul_f32_e32 v249, v249, v249
	v_mul_f32_e32 v221, v221, v221
	v_mul_f32_e32 v248, v248, v248
	v_cvt_pk_bf16_f32 v220, v220, v249
	v_cvt_pk_bf16_f32 v221, v221, v248
	v_mul_f32_e32 v222, v48, v231
	v_mul_f32_e32 v249, v49, v231
	v_mul_f32_e32 v223, v50, v231
	v_mul_f32_e32 v248, v51, v231
	v_max_f32_e32 v222, 0, v222
	v_max_f32_e32 v249, 0, v249
	v_max_f32_e32 v223, 0, v223
	v_max_f32_e32 v248, 0, v248
	v_mul_f32_e32 v222, v222, v222
	v_mul_f32_e32 v249, v249, v249
	v_mul_f32_e32 v223, v223, v223
	v_mul_f32_e32 v248, v248, v248
	v_cvt_pk_bf16_f32 v222, v222, v249
	v_cvt_pk_bf16_f32 v223, v223, v248
	s_add_u32 s30, s92, 0x400000
	s_addc_u32 s31, s93, 0
	s_nop 0
	v_permlane16_swap_b32_e32 v220, v222
	v_permlane16_swap_b32_e32 v221, v223
	global_store_dwordx4 v229, v[220:223], s[30:31]
	v_mul_f32_e32 v224, v44, v231
	v_mul_f32_e32 v249, v45, v231
	v_mul_f32_e32 v225, v46, v231
	v_mul_f32_e32 v248, v47, v231
	v_max_f32_e32 v224, 0, v224
	v_max_f32_e32 v249, 0, v249
	v_max_f32_e32 v225, 0, v225
	v_max_f32_e32 v248, 0, v248
	v_mul_f32_e32 v224, v224, v224
	v_mul_f32_e32 v249, v249, v249
	v_mul_f32_e32 v225, v225, v225
	v_mul_f32_e32 v248, v248, v248
	v_cvt_pk_bf16_f32 v224, v224, v249
	v_cvt_pk_bf16_f32 v225, v225, v248
	v_mul_f32_e32 v226, v40, v231
	v_mul_f32_e32 v249, v41, v231
	v_mul_f32_e32 v227, v42, v231
	v_mul_f32_e32 v248, v43, v231
	v_max_f32_e32 v226, 0, v226
	v_max_f32_e32 v249, 0, v249
	v_max_f32_e32 v227, 0, v227
	v_max_f32_e32 v248, 0, v248
	v_mul_f32_e32 v226, v226, v226
	v_mul_f32_e32 v249, v249, v249
	v_mul_f32_e32 v227, v227, v227
	v_mul_f32_e32 v248, v248, v248
	v_cvt_pk_bf16_f32 v226, v226, v249
	v_cvt_pk_bf16_f32 v227, v227, v248
	s_add_u32 s30, s92, 0x600000
	s_addc_u32 s31, s93, 0
	s_nop 0
	v_permlane16_swap_b32_e32 v224, v226
	v_permlane16_swap_b32_e32 v225, v227
	global_store_dwordx4 v229, v[224:227], s[30:31]
	s_waitcnt vmcnt(12)
	v_add_f32_e32 v231, v16, v17
	v_add_f32_e32 v248, v18, v19
	v_add_f32_e32 v231, v231, v248
	v_add_f32_e32 v249, v20, v21
	v_add_f32_e32 v248, v22, v23
	v_add_f32_e32 v249, v249, v248
	v_add_f32_e32 v231, v231, v249
	v_add_f32_e32 v249, v162, v163
	v_add_f32_e32 v248, v164, v165
	v_add_f32_e32 v249, v249, v248
	v_add_f32_e32 v231, v231, v249
	v_add_f32_e32 v249, v166, v167
	v_add_f32_e32 v248, v168, v169
	v_add_f32_e32 v249, v249, v248
	v_add_f32_e32 v231, v231, v249
	v_fmamk_f32 v231, v231, 0x3a800000, v199
	v_cmp_gt_f32_e32 vcc, s73, v231
	v_mul_f32_e32 v248, 0x4b800000, v231
	s_nop 0
	v_cndmask_b32_e32 v231, v231, v248, vcc
	v_rsq_f32_e32 v231, v231
	s_nop 0
	v_mul_f32_e32 v248, 0x45800000, v231
	v_cndmask_b32_e32 v231, v231, v248, vcc
	v_mul_f32_e32 v212, v96, v231
	v_mul_f32_e32 v249, v97, v231
	v_mul_f32_e32 v213, v98, v231
	v_mul_f32_e32 v248, v99, v231
	v_max_f32_e32 v212, 0, v212
	v_max_f32_e32 v249, 0, v249
	v_max_f32_e32 v213, 0, v213
	v_max_f32_e32 v248, 0, v248
	v_mul_f32_e32 v212, v212, v212
	v_mul_f32_e32 v249, v249, v249
	v_mul_f32_e32 v213, v213, v213
	v_mul_f32_e32 v248, v248, v248
	v_cvt_pk_bf16_f32 v212, v212, v249
	v_cvt_pk_bf16_f32 v213, v213, v248
	v_mul_f32_e32 v214, v92, v231
	v_mul_f32_e32 v249, v93, v231
	v_mul_f32_e32 v215, v94, v231
	v_mul_f32_e32 v248, v95, v231
	v_max_f32_e32 v214, 0, v214
	v_max_f32_e32 v249, 0, v249
	v_max_f32_e32 v215, 0, v215
	v_max_f32_e32 v248, 0, v248
	v_mul_f32_e32 v214, v214, v214
	v_mul_f32_e32 v249, v249, v249
	v_mul_f32_e32 v215, v215, v215
	v_mul_f32_e32 v248, v248, v248
	v_cvt_pk_bf16_f32 v214, v214, v249
	v_cvt_pk_bf16_f32 v215, v215, v248
	s_add_u32 s30, s92, 0x400
	s_addc_u32 s31, s93, 0
	s_nop 0
	v_permlane16_swap_b32_e32 v212, v214
	v_permlane16_swap_b32_e32 v213, v215
	global_store_dwordx4 v229, v[212:215], s[30:31]
	v_mul_f32_e32 v216, v88, v231
	v_mul_f32_e32 v249, v89, v231
	v_mul_f32_e32 v217, v90, v231
	v_mul_f32_e32 v248, v91, v231
	v_max_f32_e32 v216, 0, v216
	v_max_f32_e32 v249, 0, v249
	v_max_f32_e32 v217, 0, v217
	v_max_f32_e32 v248, 0, v248
	v_mul_f32_e32 v216, v216, v216
	v_mul_f32_e32 v249, v249, v249
	v_mul_f32_e32 v217, v217, v217
	v_mul_f32_e32 v248, v248, v248
	v_cvt_pk_bf16_f32 v216, v216, v249
	v_cvt_pk_bf16_f32 v217, v217, v248
	v_mul_f32_e32 v218, v84, v231
	v_mul_f32_e32 v249, v85, v231
	v_mul_f32_e32 v219, v86, v231
	v_mul_f32_e32 v248, v87, v231
	v_max_f32_e32 v218, 0, v218
	v_max_f32_e32 v249, 0, v249
	v_max_f32_e32 v219, 0, v219
	v_max_f32_e32 v248, 0, v248
	v_mul_f32_e32 v218, v218, v218
	v_mul_f32_e32 v249, v249, v249
	v_mul_f32_e32 v219, v219, v219
	v_mul_f32_e32 v248, v248, v248
	v_cvt_pk_bf16_f32 v218, v218, v249
	v_cvt_pk_bf16_f32 v219, v219, v248
	s_add_u32 s30, s92, 0x200400
	s_addc_u32 s31, s93, 0
	s_nop 0
	v_permlane16_swap_b32_e32 v216, v218
	v_permlane16_swap_b32_e32 v217, v219
	global_store_dwordx4 v229, v[216:219], s[30:31]
	v_mul_f32_e32 v220, v36, v231
	v_mul_f32_e32 v249, v37, v231
	v_mul_f32_e32 v221, v38, v231
	v_mul_f32_e32 v248, v39, v231
	v_max_f32_e32 v220, 0, v220
	v_max_f32_e32 v249, 0, v249
	v_max_f32_e32 v221, 0, v221
	v_max_f32_e32 v248, 0, v248
	v_mul_f32_e32 v220, v220, v220
	v_mul_f32_e32 v249, v249, v249
	v_mul_f32_e32 v221, v221, v221
	v_mul_f32_e32 v248, v248, v248
	v_cvt_pk_bf16_f32 v220, v220, v249
	v_cvt_pk_bf16_f32 v221, v221, v248
	v_mul_f32_e32 v222, v32, v231
	v_mul_f32_e32 v249, v33, v231
	v_mul_f32_e32 v223, v34, v231
	v_mul_f32_e32 v248, v35, v231
	v_max_f32_e32 v222, 0, v222
	v_max_f32_e32 v249, 0, v249
	v_max_f32_e32 v223, 0, v223
	v_max_f32_e32 v248, 0, v248
	v_mul_f32_e32 v222, v222, v222
	v_mul_f32_e32 v249, v249, v249
	v_mul_f32_e32 v223, v223, v223
	v_mul_f32_e32 v248, v248, v248
	v_cvt_pk_bf16_f32 v222, v222, v249
	v_cvt_pk_bf16_f32 v223, v223, v248
	s_add_u32 s30, s92, 0x400400
	s_addc_u32 s31, s93, 0
	s_nop 0
	v_permlane16_swap_b32_e32 v220, v222
	v_permlane16_swap_b32_e32 v221, v223
	global_store_dwordx4 v229, v[220:223], s[30:31]
	v_mul_f32_e32 v224, v28, v231
	v_mul_f32_e32 v249, v29, v231
	v_mul_f32_e32 v225, v30, v231
	v_mul_f32_e32 v248, v31, v231
	v_max_f32_e32 v224, 0, v224
	v_max_f32_e32 v249, 0, v249
	v_max_f32_e32 v225, 0, v225
	v_max_f32_e32 v248, 0, v248
	v_mul_f32_e32 v224, v224, v224
	v_mul_f32_e32 v249, v249, v249
	v_mul_f32_e32 v225, v225, v225
	v_mul_f32_e32 v248, v248, v248
	v_cvt_pk_bf16_f32 v224, v224, v249
	v_cvt_pk_bf16_f32 v225, v225, v248
	v_mul_f32_e32 v226, v24, v231
	v_mul_f32_e32 v249, v25, v231
	v_mul_f32_e32 v227, v26, v231
	v_mul_f32_e32 v248, v27, v231
	v_max_f32_e32 v226, 0, v226
	v_max_f32_e32 v249, 0, v249
	v_max_f32_e32 v227, 0, v227
	v_max_f32_e32 v248, 0, v248
	v_mul_f32_e32 v226, v226, v226
	v_mul_f32_e32 v249, v249, v249
	v_mul_f32_e32 v227, v227, v227
	v_mul_f32_e32 v248, v248, v248
	v_cvt_pk_bf16_f32 v226, v226, v249
	v_cvt_pk_bf16_f32 v227, v227, v248
	s_add_u32 s30, s92, 0x600400
	s_addc_u32 s31, s93, 0
	s_nop 0
	v_permlane16_swap_b32_e32 v224, v226
	v_permlane16_swap_b32_e32 v225, v227
	global_store_dwordx4 v229, v[224:227], s[30:31]
	s_waitcnt vmcnt(12)
	v_add_f32_e32 v231, v170, v171
	v_add_f32_e32 v248, v172, v173
	v_add_f32_e32 v231, v231, v248
	v_add_f32_e32 v249, v174, v175
	v_add_f32_e32 v248, v176, v177
	v_add_f32_e32 v249, v249, v248
	v_add_f32_e32 v231, v231, v249
	v_add_f32_e32 v249, v178, v179
	v_add_f32_e32 v248, v180, v181
	v_add_f32_e32 v249, v249, v248
	v_add_f32_e32 v231, v231, v249
	v_add_f32_e32 v249, v182, v183
	v_add_f32_e32 v248, v184, v185
	v_add_f32_e32 v249, v249, v248
	v_add_f32_e32 v231, v231, v249
	v_fmamk_f32 v231, v231, 0x3a800000, v199
	v_cmp_gt_f32_e32 vcc, s73, v231
	v_mul_f32_e32 v248, 0x4b800000, v231
	s_nop 0
	v_cndmask_b32_e32 v231, v231, v248, vcc
	v_rsq_f32_e32 v231, v231
	s_nop 0
	v_mul_f32_e32 v248, 0x45800000, v231
	v_cndmask_b32_e32 v231, v231, v248, vcc
	v_mul_f32_e32 v212, v108, v231
	v_mul_f32_e32 v249, v109, v231
	v_mul_f32_e32 v213, v110, v231
	v_mul_f32_e32 v248, v111, v231
	v_max_f32_e32 v212, 0, v212
	v_max_f32_e32 v249, 0, v249
	v_max_f32_e32 v213, 0, v213
	v_max_f32_e32 v248, 0, v248
	v_mul_f32_e32 v212, v212, v212
	v_mul_f32_e32 v249, v249, v249
	v_mul_f32_e32 v213, v213, v213
	v_mul_f32_e32 v248, v248, v248
	v_cvt_pk_bf16_f32 v212, v212, v249
	v_cvt_pk_bf16_f32 v213, v213, v248
	v_mul_f32_e32 v214, v112, v231
	v_mul_f32_e32 v249, v113, v231
	v_mul_f32_e32 v215, v114, v231
	v_mul_f32_e32 v248, v115, v231
	v_max_f32_e32 v214, 0, v214
	v_max_f32_e32 v249, 0, v249
	v_max_f32_e32 v215, 0, v215
	v_max_f32_e32 v248, 0, v248
	v_mul_f32_e32 v214, v214, v214
	v_mul_f32_e32 v249, v249, v249
	v_mul_f32_e32 v215, v215, v215
	v_mul_f32_e32 v248, v248, v248
	v_cvt_pk_bf16_f32 v214, v214, v249
	v_cvt_pk_bf16_f32 v215, v215, v248
	s_add_u32 s30, s92, 0x800
	s_addc_u32 s31, s93, 0
	s_nop 0
	v_permlane16_swap_b32_e32 v212, v214
	v_permlane16_swap_b32_e32 v213, v215
	global_store_dwordx4 v229, v[212:215], s[30:31]
	v_mul_f32_e32 v216, v120, v231
	v_mul_f32_e32 v249, v121, v231
	v_mul_f32_e32 v217, v122, v231
	v_mul_f32_e32 v248, v123, v231
	v_max_f32_e32 v216, 0, v216
	v_max_f32_e32 v249, 0, v249
	v_max_f32_e32 v217, 0, v217
	v_max_f32_e32 v248, 0, v248
	v_mul_f32_e32 v216, v216, v216
	v_mul_f32_e32 v249, v249, v249
	v_mul_f32_e32 v217, v217, v217
	v_mul_f32_e32 v248, v248, v248
	v_cvt_pk_bf16_f32 v216, v216, v249
	v_cvt_pk_bf16_f32 v217, v217, v248
	v_mul_f32_e32 v218, v124, v231
	v_mul_f32_e32 v249, v125, v231
	v_mul_f32_e32 v219, v126, v231
	v_mul_f32_e32 v248, v127, v231
	v_max_f32_e32 v218, 0, v218
	v_max_f32_e32 v249, 0, v249
	v_max_f32_e32 v219, 0, v219
	v_max_f32_e32 v248, 0, v248
	v_mul_f32_e32 v218, v218, v218
	v_mul_f32_e32 v249, v249, v249
	v_mul_f32_e32 v219, v219, v219
	v_mul_f32_e32 v248, v248, v248
	v_cvt_pk_bf16_f32 v218, v218, v249
	v_cvt_pk_bf16_f32 v219, v219, v248
	s_add_u32 s30, s92, 0x200800
	s_addc_u32 s31, s93, 0
	s_nop 0
	v_permlane16_swap_b32_e32 v216, v218
	v_permlane16_swap_b32_e32 v217, v219
	global_store_dwordx4 v229, v[216:219], s[30:31]
	v_mul_f32_e32 v220, v64, v231
	v_mul_f32_e32 v249, v65, v231
	v_mul_f32_e32 v221, v66, v231
	v_mul_f32_e32 v248, v67, v231
	v_max_f32_e32 v220, 0, v220
	v_max_f32_e32 v249, 0, v249
	v_max_f32_e32 v221, 0, v221
	v_max_f32_e32 v248, 0, v248
	v_mul_f32_e32 v220, v220, v220
	v_mul_f32_e32 v249, v249, v249
	v_mul_f32_e32 v221, v221, v221
	v_mul_f32_e32 v248, v248, v248
	v_cvt_pk_bf16_f32 v220, v220, v249
	v_cvt_pk_bf16_f32 v221, v221, v248
	v_mul_f32_e32 v222, v68, v231
	v_mul_f32_e32 v249, v69, v231
	v_mul_f32_e32 v223, v70, v231
	v_mul_f32_e32 v248, v71, v231
	v_max_f32_e32 v222, 0, v222
	v_max_f32_e32 v249, 0, v249
	v_max_f32_e32 v223, 0, v223
	v_max_f32_e32 v248, 0, v248
	v_mul_f32_e32 v222, v222, v222
	v_mul_f32_e32 v249, v249, v249
	v_mul_f32_e32 v223, v223, v223
	v_mul_f32_e32 v248, v248, v248
	v_cvt_pk_bf16_f32 v222, v222, v249
	v_cvt_pk_bf16_f32 v223, v223, v248
	s_add_u32 s30, s92, 0x400800
	s_addc_u32 s31, s93, 0
	s_nop 0
	v_permlane16_swap_b32_e32 v220, v222
	v_permlane16_swap_b32_e32 v221, v223
	global_store_dwordx4 v229, v[220:223], s[30:31]
	v_mul_f32_e32 v224, v80, v231
	v_mul_f32_e32 v249, v81, v231
	v_mul_f32_e32 v225, v82, v231
	v_mul_f32_e32 v248, v83, v231
	v_max_f32_e32 v224, 0, v224
	v_max_f32_e32 v249, 0, v249
	v_max_f32_e32 v225, 0, v225
	v_max_f32_e32 v248, 0, v248
	v_mul_f32_e32 v224, v224, v224
	v_mul_f32_e32 v249, v249, v249
	v_mul_f32_e32 v225, v225, v225
	v_mul_f32_e32 v248, v248, v248
	v_cvt_pk_bf16_f32 v224, v224, v249
	v_cvt_pk_bf16_f32 v225, v225, v248
	v_mul_f32_e32 v226, v56, v231
	v_mul_f32_e32 v249, v57, v231
	v_mul_f32_e32 v227, v58, v231
	v_mul_f32_e32 v248, v59, v231
	v_max_f32_e32 v226, 0, v226
	v_max_f32_e32 v249, 0, v249
	v_max_f32_e32 v227, 0, v227
	v_max_f32_e32 v248, 0, v248
	v_mul_f32_e32 v226, v226, v226
	v_mul_f32_e32 v249, v249, v249
	v_mul_f32_e32 v227, v227, v227
	v_mul_f32_e32 v248, v248, v248
	v_cvt_pk_bf16_f32 v226, v226, v249
	v_cvt_pk_bf16_f32 v227, v227, v248
	s_add_u32 s30, s92, 0x600800
	s_addc_u32 s31, s93, 0
	s_nop 0
	v_permlane16_swap_b32_e32 v224, v226
	v_permlane16_swap_b32_e32 v225, v227
	global_store_dwordx4 v229, v[224:227], s[30:31]
	s_waitcnt vmcnt(12)
	v_add_f32_e32 v231, v186, v187
	v_add_f32_e32 v248, v188, v189
	v_add_f32_e32 v231, v231, v248
	v_add_f32_e32 v249, v190, v191
	v_add_f32_e32 v248, v192, v193
	v_add_f32_e32 v249, v249, v248
	v_add_f32_e32 v231, v231, v249
	v_add_f32_e32 v249, v194, v195
	v_add_f32_e32 v248, v196, v197
	v_add_f32_e32 v249, v249, v248
	v_add_f32_e32 v231, v231, v249
	v_add_f32_e32 v249, v208, v209
	v_add_f32_e32 v248, v210, v211
	v_add_f32_e32 v249, v249, v248
	v_add_f32_e32 v231, v231, v249
	v_fmamk_f32 v231, v231, 0x3a800000, v199
	v_cmp_gt_f32_e32 vcc, s73, v231
	v_mul_f32_e32 v248, 0x4b800000, v231
	s_nop 0
	v_cndmask_b32_e32 v231, v231, v248, vcc
	v_rsq_f32_e32 v231, v231
	s_nop 0
	v_mul_f32_e32 v248, 0x45800000, v231
	v_cndmask_b32_e32 v231, v231, v248, vcc
	v_mul_f32_e32 v212, v132, v231
	v_mul_f32_e32 v249, v133, v231
	v_mul_f32_e32 v213, v134, v231
	v_mul_f32_e32 v248, v135, v231
	v_max_f32_e32 v212, 0, v212
	v_max_f32_e32 v249, 0, v249
	v_max_f32_e32 v213, 0, v213
	v_max_f32_e32 v248, 0, v248
	v_mul_f32_e32 v212, v212, v212
	v_mul_f32_e32 v249, v249, v249
	v_mul_f32_e32 v213, v213, v213
	v_mul_f32_e32 v248, v248, v248
	v_cvt_pk_bf16_f32 v212, v212, v249
	v_cvt_pk_bf16_f32 v213, v213, v248
	v_mul_f32_e32 v214, v136, v231
	v_mul_f32_e32 v249, v137, v231
	v_mul_f32_e32 v215, v138, v231
	v_mul_f32_e32 v248, v139, v231
	v_max_f32_e32 v214, 0, v214
	v_max_f32_e32 v249, 0, v249
	v_max_f32_e32 v215, 0, v215
	v_max_f32_e32 v248, 0, v248
	v_mul_f32_e32 v214, v214, v214
	v_mul_f32_e32 v249, v249, v249
	v_mul_f32_e32 v215, v215, v215
	v_mul_f32_e32 v248, v248, v248
	v_cvt_pk_bf16_f32 v214, v214, v249
	v_cvt_pk_bf16_f32 v215, v215, v248
	s_add_u32 s30, s92, 0xc00
	s_addc_u32 s31, s93, 0
	s_nop 0
	v_permlane16_swap_b32_e32 v212, v214
	v_permlane16_swap_b32_e32 v213, v215
	global_store_dwordx4 v229, v[212:215], s[30:31]
	v_mul_f32_e32 v216, v140, v231
	v_mul_f32_e32 v249, v141, v231
	v_mul_f32_e32 v217, v142, v231
	v_mul_f32_e32 v248, v143, v231
	v_max_f32_e32 v216, 0, v216
	v_max_f32_e32 v249, 0, v249
	v_max_f32_e32 v217, 0, v217
	v_max_f32_e32 v248, 0, v248
	v_mul_f32_e32 v216, v216, v216
	v_mul_f32_e32 v249, v249, v249
	v_mul_f32_e32 v217, v217, v217
	v_mul_f32_e32 v248, v248, v248
	v_cvt_pk_bf16_f32 v216, v216, v249
	v_cvt_pk_bf16_f32 v217, v217, v248
	v_mul_f32_e32 v218, v144, v231
	v_mul_f32_e32 v249, v145, v231
	v_mul_f32_e32 v219, v146, v231
	v_mul_f32_e32 v248, v147, v231
	v_max_f32_e32 v218, 0, v218
	v_max_f32_e32 v249, 0, v249
	v_max_f32_e32 v219, 0, v219
	v_max_f32_e32 v248, 0, v248
	v_mul_f32_e32 v218, v218, v218
	v_mul_f32_e32 v249, v249, v249
	v_mul_f32_e32 v219, v219, v219
	v_mul_f32_e32 v248, v248, v248
	v_cvt_pk_bf16_f32 v218, v218, v249
	v_cvt_pk_bf16_f32 v219, v219, v248
	s_add_u32 s30, s92, 0x200c00
	s_addc_u32 s31, s93, 0
	s_nop 0
	v_permlane16_swap_b32_e32 v216, v218
	v_permlane16_swap_b32_e32 v217, v219
	global_store_dwordx4 v229, v[216:219], s[30:31]
	v_mul_f32_e32 v220, v76, v231
	v_mul_f32_e32 v249, v77, v231
	v_mul_f32_e32 v221, v78, v231
	v_mul_f32_e32 v248, v79, v231
	v_max_f32_e32 v220, 0, v220
	v_max_f32_e32 v249, 0, v249
	v_max_f32_e32 v221, 0, v221
	v_max_f32_e32 v248, 0, v248
	v_mul_f32_e32 v220, v220, v220
	v_mul_f32_e32 v249, v249, v249
	v_mul_f32_e32 v221, v221, v221
	v_mul_f32_e32 v248, v248, v248
	v_cvt_pk_bf16_f32 v220, v220, v249
	v_cvt_pk_bf16_f32 v221, v221, v248
	v_mul_f32_e32 v222, v72, v231
	v_mul_f32_e32 v249, v73, v231
	v_mul_f32_e32 v223, v74, v231
	v_mul_f32_e32 v248, v75, v231
	v_max_f32_e32 v222, 0, v222
	v_max_f32_e32 v249, 0, v249
	v_max_f32_e32 v223, 0, v223
	v_max_f32_e32 v248, 0, v248
	v_mul_f32_e32 v222, v222, v222
	v_mul_f32_e32 v249, v249, v249
	v_mul_f32_e32 v223, v223, v223
	v_mul_f32_e32 v248, v248, v248
	v_cvt_pk_bf16_f32 v222, v222, v249
	v_cvt_pk_bf16_f32 v223, v223, v248
	s_add_u32 s30, s92, 0x400c00
	s_addc_u32 s31, s93, 0
	s_nop 0
	v_permlane16_swap_b32_e32 v220, v222
	v_permlane16_swap_b32_e32 v221, v223
	global_store_dwordx4 v229, v[220:223], s[30:31]
	v_mul_f32_e32 v224, v60, v231
	v_mul_f32_e32 v249, v61, v231
	v_mul_f32_e32 v225, v62, v231
	v_mul_f32_e32 v248, v63, v231
	v_max_f32_e32 v224, 0, v224
	v_max_f32_e32 v249, 0, v249
	v_max_f32_e32 v225, 0, v225
	v_max_f32_e32 v248, 0, v248
	v_mul_f32_e32 v224, v224, v224
	v_mul_f32_e32 v249, v249, v249
	v_mul_f32_e32 v225, v225, v225
	v_mul_f32_e32 v248, v248, v248
	v_cvt_pk_bf16_f32 v224, v224, v249
	v_cvt_pk_bf16_f32 v225, v225, v248
	v_mul_f32_e32 v226, v148, v231
	v_mul_f32_e32 v249, v149, v231
	v_mul_f32_e32 v227, v150, v231
	v_mul_f32_e32 v248, v151, v231
	v_max_f32_e32 v226, 0, v226
	v_max_f32_e32 v249, 0, v249
	v_max_f32_e32 v227, 0, v227
	v_max_f32_e32 v248, 0, v248
	v_mul_f32_e32 v226, v226, v226
	v_mul_f32_e32 v249, v249, v249
	v_mul_f32_e32 v227, v227, v227
	v_mul_f32_e32 v248, v248, v248
	v_cvt_pk_bf16_f32 v226, v226, v249
	v_cvt_pk_bf16_f32 v227, v227, v248
	s_add_u32 s30, s92, 0x600c00
	s_addc_u32 s31, s93, 0
	s_nop 0
	v_permlane16_swap_b32_e32 v224, v226
	v_permlane16_swap_b32_e32 v225, v227
	global_store_dwordx4 v229, v[224:227], s[30:31]
	s_cmp_lg_u32 s23, 0
	s_cbranch_scc0 .LBB0_13

.LBB0_24:
	s_lshr_b32 s10, s18, 2
	s_and_b32 s10, s10, 24
	s_and_b32 s11, s18, 7
	s_or_b32 s10, s10, s11
	s_lshl_b32 s10, s10, 10
	v_mov_b32 v8, v198
	s_or_b32 s10, s10, s65
	v_ashrrev_i32_e32 v12, 2, v8
	v_add_u32_e32 v0, s10, v12
	s_waitcnt lgkmcnt(0)
	v_ashrrev_i32_e32 v1, 31, v0
	s_lshl_b32 s11, s18, 5
	v_lshlrev_b64 v[0:1], 11, v[0:1]
	v_lshlrev_b32_e32 v2, 4, v8
	s_and_b32 s11, s11, 0x300
	v_lshl_add_u64 v[0:1], s[96:97], 0, v[0:1]
	v_and_b32_e32 v152, 48, v2
	v_lshl_add_u64 v[14:15], v[0:1], 0, v[152:153]
	v_add_u32_e32 v0, s11, v12
	v_ashrrev_i32_e32 v1, 31, v0
	v_lshlrev_b64 v[0:1], 6, v[0:1]
	v_lshl_add_u64 v[0:1], s[4:5], 0, v[0:1]
	v_add_co_u32_e32 v54, vcc, s62, v14
	v_lshl_add_u64 v[0:1], v[0:1], 0, v[152:153]
	s_nop 0
	v_addc_co_u32_e32 v55, vcc, 0, v15, vcc
	s_lshl_b32 s20, s17, 11
	s_lshl_b32 s21, s18, 8
	s_and_b32 s22, s16, 7
	v_add_co_u32_e32 v2, vcc, s62, v0
	s_and_b32 s20, s20, 0x180000
	s_and_b32 s23, s21, 0x6000
	s_lshl_b32 s22, s22, 10
	v_lshrrev_b32_e32 v6, 2, v8
	v_addc_co_u32_e32 v3, vcc, 0, v1, vcc
	v_and_b32_e32 v6, 12, v6
	v_ashrrev_i32_e32 v13, 31, v12
	s_movk_i32 s21, 0x1230
	s_add_u32 s20, s13, s20
	v_add_co_u32_e32 v4, vcc, s33, v0
	v_lshrrev_b32_e64 v10, v6, s21
	v_lshlrev_b64 v[6:7], 11, v[12:13]
	s_addc_u32 s21, s14, 0
	s_or_b32 s22, s22, s23
	v_addc_co_u32_e32 v5, vcc, 0, v1, vcc
	v_and_b32_e32 v22, 3, v8
	v_xor_b32_e32 v8, v10, v8
	v_lshl_add_u64 v[156:157], s[20:21], 0, v[6:7]
	s_or_b32 s20, s22, s65
	v_add_co_u32_e32 v20, vcc, s72, v0
	v_lshlrev_b32_e32 v9, 6, v12
	v_lshlrev_b32_e32 v8, 4, v8
	v_add_u32_e32 v12, s20, v12
	v_addc_co_u32_e32 v21, vcc, 0, v1, vcc
	s_nop 0
	v_readfirstlane_b32 s26, v14
	v_readfirstlane_b32 s27, v15
	v_readfirstlane_b32 s28, v0
	v_readfirstlane_b32 s29, v1
	v_lshrrev_b32_e32 v250, 6, v198
	s_nop 0
	v_readfirstlane_b32 s24, v250
	s_lshl_b32 s24, s24, 10
	v_lshrrev_b32_e32 v250, 2, v200
	v_lshrrev_b32_e32 v251, 4, v200
	v_lshlrev_b32_e32 v251, 2, v251
	v_mov_b32_e32 v248, 0x1230
	v_lshrrev_b32_e32 v251, v251, v248
	v_xor_b32_e32 v251, v251, v200
	v_and_b32_e32 v251, 3, v251
	v_lshlrev_b32_e32 v251, 4, v251
	v_lshl_add_u32 v244, v250, 11, v251
	v_add_u32_e32 v245, 0x20000, v244
	v_add_u32_e32 v246, 0x40000, v244
	v_add_u32_e32 v247, 0x60000, v244
	v_lshl_add_u32 v156, v250, 6, v251
	v_add_u32_e32 v157, 0x1000, v156
	v_add_u32_e32 v158, 0x2000, v156
	v_add_u32_e32 v159, 0x3000, v156
	s_mov_b32 s25, 0
	s_add_u32 m0, s25, s24
	s_nop 0
	global_load_lds_dwordx4 v244, s[26:27]
	s_add_u32 m0, m0, 0x1000
	s_nop 0
	global_load_lds_dwordx4 v245, s[26:27]
	s_add_u32 m0, m0, 0x1000
	s_nop 0
	global_load_lds_dwordx4 v156, s[28:29]
	s_add_u32 m0, m0, 0x1000
	s_nop 0
	global_load_lds_dwordx4 v157, s[28:29]
	s_add_u32 m0, m0, 0x1000
	s_nop 0
	global_load_lds_dwordx4 v158, s[28:29]
	s_add_u32 m0, m0, 0x1000
	s_nop 0
	global_load_lds_dwordx4 v159, s[28:29]
	s_add_u32 s26, s26, 0x40
	s_addc_u32 s27, s27, 0
	s_add_u32 s28, s28, 0x10000
	s_addc_u32 s29, s29, 0
	s_add_u32 s25, s25, 24576
	s_cmp_eq_u32 s25, 73728
	s_cselect_b32 s25, 0, s25
	s_add_u32 m0, s25, s24
	s_nop 0
	global_load_lds_dwordx4 v244, s[26:27]
	s_add_u32 m0, m0, 0x1000
	s_nop 0
	global_load_lds_dwordx4 v245, s[26:27]
	s_add_u32 m0, m0, 0x1000
	s_nop 0
	global_load_lds_dwordx4 v156, s[28:29]
	s_add_u32 m0, m0, 0x1000
	s_nop 0
	global_load_lds_dwordx4 v157, s[28:29]
	s_add_u32 m0, m0, 0x1000
	s_nop 0
	global_load_lds_dwordx4 v158, s[28:29]
	s_add_u32 m0, m0, 0x1000
	s_nop 0
	global_load_lds_dwordx4 v159, s[28:29]
	s_add_u32 s26, s26, 0x40
	s_addc_u32 s27, s27, 0
	s_add_u32 s28, s28, 0x10000
	s_addc_u32 s29, s29, 0
	s_add_u32 s25, s25, 24576
	s_cmp_eq_u32 s25, 73728
	s_cselect_b32 s25, 0, s25
	s_add_u32 m0, s25, s24
	s_nop 0
	global_load_lds_dwordx4 v244, s[26:27]
	s_add_u32 m0, m0, 0x1000
	s_nop 0
	global_load_lds_dwordx4 v245, s[26:27]
	s_add_u32 m0, m0, 0x1000
	s_nop 0
	global_load_lds_dwordx4 v156, s[28:29]
	s_add_u32 m0, m0, 0x1000
	s_nop 0
	global_load_lds_dwordx4 v157, s[28:29]
	s_add_u32 m0, m0, 0x1000
	s_nop 0
	global_load_lds_dwordx4 v158, s[28:29]
	s_add_u32 m0, m0, 0x1000
	s_nop 0
	global_load_lds_dwordx4 v159, s[28:29]
	s_add_u32 s26, s26, 0x40
	s_addc_u32 s27, s27, 0
	s_add_u32 s28, s28, 0x10000
	s_addc_u32 s29, s29, 0
	s_add_u32 s25, s25, 24576
	s_cmp_eq_u32 s25, 73728
	s_cselect_b32 s25, 0, s25
	v_mov_b32_e32 v24, 0
	v_mov_b32_e32 v25, v24
	v_mov_b32_e32 v26, v24
	v_mov_b32_e32 v27, v24
	v_mov_b32_e32 v28, v24
	v_mov_b32_e32 v29, v24
	v_mov_b32_e32 v60, v24
	v_mov_b32_e32 v61, v24
	v_mov_b32_e32 v62, v24
	v_mov_b32_e32 v63, v24
	v_mov_b32_e32 v64, v24
	v_mov_b32_e32 v65, v24
	v_mov_b32_e32 v66, v24
	v_mov_b32_e32 v67, v24
	v_mov_b32_e32 v72, v24
	v_mov_b32_e32 v73, v24
	v_mov_b32_e32 v74, v24
	v_mov_b32_e32 v75, v24
	v_mov_b32_e32 v80, v24
	v_mov_b32_e32 v81, v24
	v_mov_b32_e32 v82, v24
	v_mov_b32_e32 v83, v24
	v_mov_b32_e32 v56, v24
	v_mov_b32_e32 v57, v24
	v_mov_b32_e32 v58, v24
	v_mov_b32_e32 v59, v24
	v_mov_b32_e32 v68, v24
	v_mov_b32_e32 v69, v24
	v_mov_b32_e32 v30, v24
	v_mov_b32_e32 v31, v24
	v_mov_b32_e32 v32, v24
	v_mov_b32_e32 v33, v24
	v_mov_b32_e32 v34, v24
	v_mov_b32_e32 v35, v24
	v_mov_b32_e32 v36, v24
	v_mov_b32_e32 v37, v24
	v_mov_b32_e32 v38, v24
	v_mov_b32_e32 v39, v24
	v_mov_b32_e32 v40, v24
	v_mov_b32_e32 v41, v24
	v_mov_b32_e32 v42, v24
	v_mov_b32_e32 v43, v24
	v_mov_b32_e32 v48, v24
	v_mov_b32_e32 v49, v24
	v_mov_b32_e32 v50, v24
	v_mov_b32_e32 v51, v24
	v_mov_b32_e32 v70, v24
	v_mov_b32_e32 v71, v24
	v_mov_b32_e32 v100, v24
	v_mov_b32_e32 v101, v24
	v_mov_b32_e32 v102, v24
	v_mov_b32_e32 v103, v24
	v_mov_b32_e32 v104, v24
	v_mov_b32_e32 v105, v24
	v_mov_b32_e32 v106, v24
	v_mov_b32_e32 v107, v24
	v_mov_b32_e32 v120, v24
	v_mov_b32_e32 v121, v24
	v_mov_b32_e32 v122, v24
	v_mov_b32_e32 v123, v24
	v_mov_b32_e32 v128, v24
	v_mov_b32_e32 v129, v24
	v_mov_b32_e32 v130, v24
	v_mov_b32_e32 v131, v24
	v_mov_b32_e32 v108, v24
	v_mov_b32_e32 v109, v24
	v_mov_b32_e32 v110, v24
	v_mov_b32_e32 v111, v24
	v_mov_b32_e32 v112, v24
	v_mov_b32_e32 v113, v24
	v_mov_b32_e32 v114, v24
	v_mov_b32_e32 v115, v24
	v_mov_b32_e32 v116, v24
	v_mov_b32_e32 v117, v24
	v_mov_b32_e32 v118, v24
	v_mov_b32_e32 v119, v24
	v_mov_b32_e32 v124, v24
	v_mov_b32_e32 v125, v24
	v_mov_b32_e32 v126, v24
	v_mov_b32_e32 v127, v24
	v_mov_b32_e32 v88, v24
	v_mov_b32_e32 v89, v24
	v_mov_b32_e32 v90, v24
	v_mov_b32_e32 v91, v24
	v_mov_b32_e32 v92, v24
	v_mov_b32_e32 v93, v24
	v_mov_b32_e32 v94, v24
	v_mov_b32_e32 v95, v24
	v_mov_b32_e32 v96, v24
	v_mov_b32_e32 v97, v24
	v_mov_b32_e32 v98, v24
	v_mov_b32_e32 v99, v24
	v_mov_b32_e32 v84, v24
	v_mov_b32_e32 v85, v24
	v_mov_b32_e32 v86, v24
	v_mov_b32_e32 v87, v24
	v_mov_b32_e32 v132, v24
	v_mov_b32_e32 v133, v24
	v_mov_b32_e32 v134, v24
	v_mov_b32_e32 v135, v24
	v_mov_b32_e32 v136, v24
	v_mov_b32_e32 v137, v24
	v_mov_b32_e32 v138, v24
	v_mov_b32_e32 v139, v24
	v_mov_b32_e32 v140, v24
	v_mov_b32_e32 v141, v24
	v_mov_b32_e32 v142, v24
	v_mov_b32_e32 v143, v24
	v_mov_b32_e32 v144, v24
	v_mov_b32_e32 v145, v24
	v_mov_b32_e32 v146, v24
	v_mov_b32_e32 v147, v24
	v_mov_b32_e32 v76, v24
	v_mov_b32_e32 v77, v24
	v_mov_b32_e32 v78, v24
	v_mov_b32_e32 v79, v24
	v_mov_b32_e32 v52, v24
	v_mov_b32_e32 v53, v24
	v_mov_b32_e32 v54, v24
	v_mov_b32_e32 v55, v24
	v_mov_b32_e32 v44, v24
	v_mov_b32_e32 v45, v24
	v_mov_b32_e32 v46, v24
	v_mov_b32_e32 v47, v24
	v_mov_b32_e32 v148, v24
	v_mov_b32_e32 v149, v24
	v_mov_b32_e32 v150, v24
	v_mov_b32_e32 v151, v24
	s_waitcnt vmcnt(12)
	s_barrier
	s_mov_b32 s30, 0
	v_add_u32_e32 v248, s30, v155
	v_add_u32_e32 v249, s30, v160
	ds_read_b128 v[186:189], v248
	ds_read_b128 v[212:215], v249 offset:8192
	ds_read_b128 v[190:193], v248 offset:1024
	ds_read_b128 v[216:219], v249 offset:9216
	ds_read_b128 v[194:197], v248 offset:2048
	ds_read_b128 v[220:223], v249 offset:10240
	ds_read_b128 v[208:211], v248 offset:3072
	ds_read_b128 v[224:227], v249 offset:11264
	ds_read_b128 v[228:231], v249 offset:12288
	ds_read_b128 v[232:235], v249 offset:13312
	ds_read_b128 v[236:239], v249 offset:14336
	ds_read_b128 v[240:243], v249 offset:15360
	s_add_u32 s30, s30, 24576
	s_cmp_eq_u32 s30, 73728
	s_cselect_b32 s30, 0, s30
	s_waitcnt lgkmcnt(0)
	s_mov_b32 s31, 14
.Lgm1_loop:
	v_mfma_f32_16x16x32_bf16 v[128:131], v[212:215], v[186:189], v[128:131]
	v_mfma_f32_16x16x32_bf16 v[80:83], v[212:215], v[190:193], v[80:83]
	v_mfma_f32_16x16x32_bf16 v[108:111], v[212:215], v[194:197], v[108:111]
	v_mfma_f32_16x16x32_bf16 v[132:135], v[212:215], v[208:211], v[132:135]
	v_mfma_f32_16x16x32_bf16 v[120:123], v[216:219], v[186:189], v[120:123]
	v_mfma_f32_16x16x32_bf16 v[72:75], v[216:219], v[190:193], v[72:75]
	v_mfma_f32_16x16x32_bf16 v[112:115], v[216:219], v[194:197], v[112:115]
	v_mfma_f32_16x16x32_bf16 v[136:139], v[216:219], v[208:211], v[136:139]
	v_mfma_f32_16x16x32_bf16 v[104:107], v[220:223], v[186:189], v[104:107]
	v_mfma_f32_16x16x32_bf16 v[64:67], v[220:223], v[190:193], v[64:67]
	v_mfma_f32_16x16x32_bf16 v[116:119], v[220:223], v[194:197], v[116:119]
	v_mfma_f32_16x16x32_bf16 v[140:143], v[220:223], v[208:211], v[140:143]
	v_mfma_f32_16x16x32_bf16 v[100:103], v[224:227], v[186:189], v[100:103]
	v_mfma_f32_16x16x32_bf16 v[60:63], v[224:227], v[190:193], v[60:63]
	v_mfma_f32_16x16x32_bf16 v[124:127], v[224:227], v[194:197], v[124:127]
	v_mfma_f32_16x16x32_bf16 v[144:147], v[224:227], v[208:211], v[144:147]
	s_waitcnt vmcnt(6)
	s_barrier
	v_add_u32_e32 v248, s30, v155
	v_add_u32_e32 v249, s30, v160
	v_mfma_f32_16x16x32_bf16 v[68:71], v[228:231], v[186:189], v[68:71]
	ds_read_b128 v[0:3], v248
	s_add_u32 m0, s25, s24
	v_mfma_f32_16x16x32_bf16 v[36:39], v[228:231], v[190:193], v[36:39]
	ds_read_b128 v[16:19], v249 offset:8192
	global_load_lds_dwordx4 v244, s[26:27]
	v_mfma_f32_16x16x32_bf16 v[88:91], v[228:231], v[194:197], v[88:91]
	ds_read_b128 v[4:7], v248 offset:1024
	s_add_u32 m0, m0, 0x1000
	v_mfma_f32_16x16x32_bf16 v[76:79], v[228:231], v[208:211], v[76:79]
	ds_read_b128 v[20:23], v249 offset:9216
	global_load_lds_dwordx4 v245, s[26:27]
	v_mfma_f32_16x16x32_bf16 v[56:59], v[232:235], v[186:189], v[56:59]
	ds_read_b128 v[8:11], v248 offset:2048
	s_add_u32 m0, m0, 0x1000
	v_mfma_f32_16x16x32_bf16 v[32:35], v[232:235], v[190:193], v[32:35]
	ds_read_b128 v[162:165], v249 offset:10240
	global_load_lds_dwordx4 v156, s[28:29]
	v_mfma_f32_16x16x32_bf16 v[92:95], v[232:235], v[194:197], v[92:95]
	ds_read_b128 v[12:15], v248 offset:3072
	s_add_u32 m0, m0, 0x1000
	v_mfma_f32_16x16x32_bf16 v[52:55], v[232:235], v[208:211], v[52:55]
	ds_read_b128 v[166:169], v249 offset:11264
	global_load_lds_dwordx4 v157, s[28:29]
	v_mfma_f32_16x16x32_bf16 v[48:51], v[236:239], v[186:189], v[48:51]
	ds_read_b128 v[170:173], v249 offset:12288
	s_add_u32 m0, m0, 0x1000
	v_mfma_f32_16x16x32_bf16 v[28:31], v[236:239], v[190:193], v[28:31]
	ds_read_b128 v[174:177], v249 offset:13312
	global_load_lds_dwordx4 v158, s[28:29]
	v_mfma_f32_16x16x32_bf16 v[96:99], v[236:239], v[194:197], v[96:99]
	ds_read_b128 v[178:181], v249 offset:14336
	s_add_u32 m0, m0, 0x1000
	v_mfma_f32_16x16x32_bf16 v[44:47], v[236:239], v[208:211], v[44:47]
	ds_read_b128 v[182:185], v249 offset:15360
	global_load_lds_dwordx4 v159, s[28:29]
	v_mfma_f32_16x16x32_bf16 v[40:43], v[240:243], v[186:189], v[40:43]
	v_mfma_f32_16x16x32_bf16 v[24:27], v[240:243], v[190:193], v[24:27]
	v_mfma_f32_16x16x32_bf16 v[84:87], v[240:243], v[194:197], v[84:87]
	v_mfma_f32_16x16x32_bf16 v[148:151], v[240:243], v[208:211], v[148:151]
	s_add_u32 s26, s26, 0x40
	s_addc_u32 s27, s27, 0
	s_add_u32 s28, s28, 0x10000
	s_addc_u32 s29, s29, 0
	s_add_u32 s25, s25, 24576
	s_cmp_eq_u32 s25, 73728
	s_cselect_b32 s25, 0, s25
	s_add_u32 s30, s30, 24576
	s_cmp_eq_u32 s30, 73728
	s_cselect_b32 s30, 0, s30
	s_waitcnt lgkmcnt(0)
	v_mfma_f32_16x16x32_bf16 v[128:131], v[16:19], v[0:3], v[128:131]
	v_mfma_f32_16x16x32_bf16 v[80:83], v[16:19], v[4:7], v[80:83]
	v_mfma_f32_16x16x32_bf16 v[108:111], v[16:19], v[8:11], v[108:111]
	v_mfma_f32_16x16x32_bf16 v[132:135], v[16:19], v[12:15], v[132:135]
	v_mfma_f32_16x16x32_bf16 v[120:123], v[20:23], v[0:3], v[120:123]
	v_mfma_f32_16x16x32_bf16 v[72:75], v[20:23], v[4:7], v[72:75]
	v_mfma_f32_16x16x32_bf16 v[112:115], v[20:23], v[8:11], v[112:115]
	v_mfma_f32_16x16x32_bf16 v[136:139], v[20:23], v[12:15], v[136:139]
	v_mfma_f32_16x16x32_bf16 v[104:107], v[162:165], v[0:3], v[104:107]
	v_mfma_f32_16x16x32_bf16 v[64:67], v[162:165], v[4:7], v[64:67]
	v_mfma_f32_16x16x32_bf16 v[116:119], v[162:165], v[8:11], v[116:119]
	v_mfma_f32_16x16x32_bf16 v[140:143], v[162:165], v[12:15], v[140:143]
	v_mfma_f32_16x16x32_bf16 v[100:103], v[166:169], v[0:3], v[100:103]
	v_mfma_f32_16x16x32_bf16 v[60:63], v[166:169], v[4:7], v[60:63]
	v_mfma_f32_16x16x32_bf16 v[124:127], v[166:169], v[8:11], v[124:127]
	v_mfma_f32_16x16x32_bf16 v[144:147], v[166:169], v[12:15], v[144:147]
	s_waitcnt vmcnt(6)
	s_barrier
	v_add_u32_e32 v248, s30, v155
	v_add_u32_e32 v249, s30, v160
	v_mfma_f32_16x16x32_bf16 v[68:71], v[170:173], v[0:3], v[68:71]
	ds_read_b128 v[186:189], v248
	s_add_u32 m0, s25, s24
	v_mfma_f32_16x16x32_bf16 v[36:39], v[170:173], v[4:7], v[36:39]
	ds_read_b128 v[212:215], v249 offset:8192
	global_load_lds_dwordx4 v244, s[26:27]
	v_mfma_f32_16x16x32_bf16 v[88:91], v[170:173], v[8:11], v[88:91]
	ds_read_b128 v[190:193], v248 offset:1024
	s_add_u32 m0, m0, 0x1000
	v_mfma_f32_16x16x32_bf16 v[76:79], v[170:173], v[12:15], v[76:79]
	ds_read_b128 v[216:219], v249 offset:9216
	global_load_lds_dwordx4 v245, s[26:27]
	v_mfma_f32_16x16x32_bf16 v[56:59], v[174:177], v[0:3], v[56:59]
	ds_read_b128 v[194:197], v248 offset:2048
	s_add_u32 m0, m0, 0x1000
	v_mfma_f32_16x16x32_bf16 v[32:35], v[174:177], v[4:7], v[32:35]
	ds_read_b128 v[220:223], v249 offset:10240
	global_load_lds_dwordx4 v156, s[28:29]
	v_mfma_f32_16x16x32_bf16 v[92:95], v[174:177], v[8:11], v[92:95]
	ds_read_b128 v[208:211], v248 offset:3072
	s_add_u32 m0, m0, 0x1000
	v_mfma_f32_16x16x32_bf16 v[52:55], v[174:177], v[12:15], v[52:55]
	ds_read_b128 v[224:227], v249 offset:11264
	global_load_lds_dwordx4 v157, s[28:29]
	v_mfma_f32_16x16x32_bf16 v[48:51], v[178:181], v[0:3], v[48:51]
	ds_read_b128 v[228:231], v249 offset:12288
	s_add_u32 m0, m0, 0x1000
	v_mfma_f32_16x16x32_bf16 v[28:31], v[178:181], v[4:7], v[28:31]
	ds_read_b128 v[232:235], v249 offset:13312
	global_load_lds_dwordx4 v158, s[28:29]
	v_mfma_f32_16x16x32_bf16 v[96:99], v[178:181], v[8:11], v[96:99]
	ds_read_b128 v[236:239], v249 offset:14336
	s_add_u32 m0, m0, 0x1000
	v_mfma_f32_16x16x32_bf16 v[44:47], v[178:181], v[12:15], v[44:47]
	ds_read_b128 v[240:243], v249 offset:15360
	global_load_lds_dwordx4 v159, s[28:29]
	v_mfma_f32_16x16x32_bf16 v[40:43], v[182:185], v[0:3], v[40:43]
	v_mfma_f32_16x16x32_bf16 v[24:27], v[182:185], v[4:7], v[24:27]
	v_mfma_f32_16x16x32_bf16 v[84:87], v[182:185], v[8:11], v[84:87]
	v_mfma_f32_16x16x32_bf16 v[148:151], v[182:185], v[12:15], v[148:151]
	s_add_u32 s26, s26, 0x40
	s_addc_u32 s27, s27, 0
	s_add_u32 s28, s28, 0x10000
	s_addc_u32 s29, s29, 0
	s_add_u32 s25, s25, 24576
	s_cmp_eq_u32 s25, 73728
	s_cselect_b32 s25, 0, s25
	s_add_u32 s30, s30, 24576
	s_cmp_eq_u32 s30, 73728
	s_cselect_b32 s30, 0, s30
	s_waitcnt lgkmcnt(0)
	s_sub_u32 s31, s31, 1
	s_cmp_lg_u32 s31, 0
	s_cbranch_scc1 .Lgm1_loop
	v_mfma_f32_16x16x32_bf16 v[128:131], v[212:215], v[186:189], v[128:131]
	v_mfma_f32_16x16x32_bf16 v[80:83], v[212:215], v[190:193], v[80:83]
	v_mfma_f32_16x16x32_bf16 v[108:111], v[212:215], v[194:197], v[108:111]
	v_mfma_f32_16x16x32_bf16 v[132:135], v[212:215], v[208:211], v[132:135]
	v_mfma_f32_16x16x32_bf16 v[120:123], v[216:219], v[186:189], v[120:123]
	v_mfma_f32_16x16x32_bf16 v[72:75], v[216:219], v[190:193], v[72:75]
	v_mfma_f32_16x16x32_bf16 v[112:115], v[216:219], v[194:197], v[112:115]
	v_mfma_f32_16x16x32_bf16 v[136:139], v[216:219], v[208:211], v[136:139]
	v_mfma_f32_16x16x32_bf16 v[104:107], v[220:223], v[186:189], v[104:107]
	v_mfma_f32_16x16x32_bf16 v[64:67], v[220:223], v[190:193], v[64:67]
	v_mfma_f32_16x16x32_bf16 v[116:119], v[220:223], v[194:197], v[116:119]
	v_mfma_f32_16x16x32_bf16 v[140:143], v[220:223], v[208:211], v[140:143]
	v_mfma_f32_16x16x32_bf16 v[100:103], v[224:227], v[186:189], v[100:103]
	v_mfma_f32_16x16x32_bf16 v[60:63], v[224:227], v[190:193], v[60:63]
	v_mfma_f32_16x16x32_bf16 v[124:127], v[224:227], v[194:197], v[124:127]
	v_mfma_f32_16x16x32_bf16 v[144:147], v[224:227], v[208:211], v[144:147]
	s_waitcnt vmcnt(6)
	s_barrier
	v_add_u32_e32 v248, s30, v155
	v_add_u32_e32 v249, s30, v160
	v_mfma_f32_16x16x32_bf16 v[68:71], v[228:231], v[186:189], v[68:71]
	ds_read_b128 v[0:3], v248
	s_add_u32 m0, s25, s24
	v_mfma_f32_16x16x32_bf16 v[36:39], v[228:231], v[190:193], v[36:39]
	ds_read_b128 v[16:19], v249 offset:8192
	global_load_lds_dwordx4 v244, s[26:27]
	v_mfma_f32_16x16x32_bf16 v[88:91], v[228:231], v[194:197], v[88:91]
	ds_read_b128 v[4:7], v248 offset:1024
	s_add_u32 m0, m0, 0x1000
	v_mfma_f32_16x16x32_bf16 v[76:79], v[228:231], v[208:211], v[76:79]
	ds_read_b128 v[20:23], v249 offset:9216
	global_load_lds_dwordx4 v245, s[26:27]
	v_mfma_f32_16x16x32_bf16 v[56:59], v[232:235], v[186:189], v[56:59]
	ds_read_b128 v[8:11], v248 offset:2048
	s_add_u32 m0, m0, 0x1000
	v_mfma_f32_16x16x32_bf16 v[32:35], v[232:235], v[190:193], v[32:35]
	ds_read_b128 v[162:165], v249 offset:10240
	global_load_lds_dwordx4 v156, s[28:29]
	v_mfma_f32_16x16x32_bf16 v[92:95], v[232:235], v[194:197], v[92:95]
	ds_read_b128 v[12:15], v248 offset:3072
	s_add_u32 m0, m0, 0x1000
	v_mfma_f32_16x16x32_bf16 v[52:55], v[232:235], v[208:211], v[52:55]
	ds_read_b128 v[166:169], v249 offset:11264
	global_load_lds_dwordx4 v157, s[28:29]
	v_mfma_f32_16x16x32_bf16 v[48:51], v[236:239], v[186:189], v[48:51]
	ds_read_b128 v[170:173], v249 offset:12288
	s_add_u32 m0, m0, 0x1000
	v_mfma_f32_16x16x32_bf16 v[28:31], v[236:239], v[190:193], v[28:31]
	ds_read_b128 v[174:177], v249 offset:13312
	global_load_lds_dwordx4 v158, s[28:29]
	v_mfma_f32_16x16x32_bf16 v[96:99], v[236:239], v[194:197], v[96:99]
	ds_read_b128 v[178:181], v249 offset:14336
	s_add_u32 m0, m0, 0x1000
	v_mfma_f32_16x16x32_bf16 v[44:47], v[236:239], v[208:211], v[44:47]
	ds_read_b128 v[182:185], v249 offset:15360
	global_load_lds_dwordx4 v159, s[28:29]
	v_mfma_f32_16x16x32_bf16 v[40:43], v[240:243], v[186:189], v[40:43]
	v_mfma_f32_16x16x32_bf16 v[24:27], v[240:243], v[190:193], v[24:27]
	v_mfma_f32_16x16x32_bf16 v[84:87], v[240:243], v[194:197], v[84:87]
	v_mfma_f32_16x16x32_bf16 v[148:151], v[240:243], v[208:211], v[148:151]
	s_add_u32 s26, s26, 0x40
	s_addc_u32 s27, s27, 0
	s_add_u32 s28, s28, 0x10000
	s_addc_u32 s29, s29, 0
	s_add_u32 s25, s25, 24576
	s_cmp_eq_u32 s25, 73728
	s_cselect_b32 s25, 0, s25
	s_add_u32 s30, s30, 24576
	s_cmp_eq_u32 s30, 73728
	s_cselect_b32 s30, 0, s30
	s_waitcnt lgkmcnt(0)
	v_mfma_f32_16x16x32_bf16 v[128:131], v[16:19], v[0:3], v[128:131]
	v_mfma_f32_16x16x32_bf16 v[80:83], v[16:19], v[4:7], v[80:83]
	v_mfma_f32_16x16x32_bf16 v[108:111], v[16:19], v[8:11], v[108:111]
	v_mfma_f32_16x16x32_bf16 v[132:135], v[16:19], v[12:15], v[132:135]
	v_mfma_f32_16x16x32_bf16 v[120:123], v[20:23], v[0:3], v[120:123]
	v_mfma_f32_16x16x32_bf16 v[72:75], v[20:23], v[4:7], v[72:75]
	v_mfma_f32_16x16x32_bf16 v[112:115], v[20:23], v[8:11], v[112:115]
	v_mfma_f32_16x16x32_bf16 v[136:139], v[20:23], v[12:15], v[136:139]
	v_mfma_f32_16x16x32_bf16 v[104:107], v[162:165], v[0:3], v[104:107]
	v_mfma_f32_16x16x32_bf16 v[64:67], v[162:165], v[4:7], v[64:67]
	v_mfma_f32_16x16x32_bf16 v[116:119], v[162:165], v[8:11], v[116:119]
	v_mfma_f32_16x16x32_bf16 v[140:143], v[162:165], v[12:15], v[140:143]
	v_mfma_f32_16x16x32_bf16 v[100:103], v[166:169], v[0:3], v[100:103]
	v_mfma_f32_16x16x32_bf16 v[60:63], v[166:169], v[4:7], v[60:63]
	v_mfma_f32_16x16x32_bf16 v[124:127], v[166:169], v[8:11], v[124:127]
	v_mfma_f32_16x16x32_bf16 v[144:147], v[166:169], v[12:15], v[144:147]
	s_waitcnt vmcnt(6)
	s_barrier
	v_add_u32_e32 v248, s30, v155
	v_add_u32_e32 v249, s30, v160
	v_mfma_f32_16x16x32_bf16 v[68:71], v[170:173], v[0:3], v[68:71]
	ds_read_b128 v[186:189], v248
	v_mfma_f32_16x16x32_bf16 v[36:39], v[170:173], v[4:7], v[36:39]
	ds_read_b128 v[212:215], v249 offset:8192
	v_mfma_f32_16x16x32_bf16 v[88:91], v[170:173], v[8:11], v[88:91]
	ds_read_b128 v[190:193], v248 offset:1024
	v_mfma_f32_16x16x32_bf16 v[76:79], v[170:173], v[12:15], v[76:79]
	ds_read_b128 v[216:219], v249 offset:9216
	v_mfma_f32_16x16x32_bf16 v[56:59], v[174:177], v[0:3], v[56:59]
	ds_read_b128 v[194:197], v248 offset:2048
	v_mfma_f32_16x16x32_bf16 v[32:35], v[174:177], v[4:7], v[32:35]
	ds_read_b128 v[220:223], v249 offset:10240
	v_mfma_f32_16x16x32_bf16 v[92:95], v[174:177], v[8:11], v[92:95]
	ds_read_b128 v[208:211], v248 offset:3072
	v_mfma_f32_16x16x32_bf16 v[52:55], v[174:177], v[12:15], v[52:55]
	ds_read_b128 v[224:227], v249 offset:11264
	v_mfma_f32_16x16x32_bf16 v[48:51], v[178:181], v[0:3], v[48:51]
	ds_read_b128 v[228:231], v249 offset:12288
	v_mfma_f32_16x16x32_bf16 v[28:31], v[178:181], v[4:7], v[28:31]
	ds_read_b128 v[232:235], v249 offset:13312
	v_mfma_f32_16x16x32_bf16 v[96:99], v[178:181], v[8:11], v[96:99]
	ds_read_b128 v[236:239], v249 offset:14336
	v_mfma_f32_16x16x32_bf16 v[44:47], v[178:181], v[12:15], v[44:47]
	ds_read_b128 v[240:243], v249 offset:15360
	v_mfma_f32_16x16x32_bf16 v[40:43], v[182:185], v[0:3], v[40:43]
	v_mfma_f32_16x16x32_bf16 v[24:27], v[182:185], v[4:7], v[24:27]
	v_mfma_f32_16x16x32_bf16 v[84:87], v[182:185], v[8:11], v[84:87]
	v_mfma_f32_16x16x32_bf16 v[148:151], v[182:185], v[12:15], v[148:151]
	s_add_u32 s30, s30, 24576
	s_cmp_eq_u32 s30, 73728
	s_cselect_b32 s30, 0, s30
	s_waitcnt lgkmcnt(0)
	v_mfma_f32_16x16x32_bf16 v[128:131], v[212:215], v[186:189], v[128:131]
	v_mfma_f32_16x16x32_bf16 v[80:83], v[212:215], v[190:193], v[80:83]
	v_mfma_f32_16x16x32_bf16 v[108:111], v[212:215], v[194:197], v[108:111]
	v_mfma_f32_16x16x32_bf16 v[132:135], v[212:215], v[208:211], v[132:135]
	v_mfma_f32_16x16x32_bf16 v[120:123], v[216:219], v[186:189], v[120:123]
	v_mfma_f32_16x16x32_bf16 v[72:75], v[216:219], v[190:193], v[72:75]
	v_mfma_f32_16x16x32_bf16 v[112:115], v[216:219], v[194:197], v[112:115]
	v_mfma_f32_16x16x32_bf16 v[136:139], v[216:219], v[208:211], v[136:139]
	v_mfma_f32_16x16x32_bf16 v[104:107], v[220:223], v[186:189], v[104:107]
	v_mfma_f32_16x16x32_bf16 v[64:67], v[220:223], v[190:193], v[64:67]
	v_mfma_f32_16x16x32_bf16 v[116:119], v[220:223], v[194:197], v[116:119]
	v_mfma_f32_16x16x32_bf16 v[140:143], v[220:223], v[208:211], v[140:143]
	v_mfma_f32_16x16x32_bf16 v[100:103], v[224:227], v[186:189], v[100:103]
	v_mfma_f32_16x16x32_bf16 v[60:63], v[224:227], v[190:193], v[60:63]
	v_mfma_f32_16x16x32_bf16 v[124:127], v[224:227], v[194:197], v[124:127]
	v_mfma_f32_16x16x32_bf16 v[144:147], v[224:227], v[208:211], v[144:147]
	s_waitcnt vmcnt(0)
	s_barrier
	v_add_u32_e32 v248, s30, v155
	v_add_u32_e32 v249, s30, v160
	v_mfma_f32_16x16x32_bf16 v[68:71], v[228:231], v[186:189], v[68:71]
	ds_read_b128 v[0:3], v248
	v_mfma_f32_16x16x32_bf16 v[36:39], v[228:231], v[190:193], v[36:39]
	ds_read_b128 v[16:19], v249 offset:8192
	v_mfma_f32_16x16x32_bf16 v[88:91], v[228:231], v[194:197], v[88:91]
	ds_read_b128 v[4:7], v248 offset:1024
	v_mfma_f32_16x16x32_bf16 v[76:79], v[228:231], v[208:211], v[76:79]
	ds_read_b128 v[20:23], v249 offset:9216
	v_mfma_f32_16x16x32_bf16 v[56:59], v[232:235], v[186:189], v[56:59]
	ds_read_b128 v[8:11], v248 offset:2048
	v_mfma_f32_16x16x32_bf16 v[32:35], v[232:235], v[190:193], v[32:35]
	ds_read_b128 v[162:165], v249 offset:10240
	v_mfma_f32_16x16x32_bf16 v[92:95], v[232:235], v[194:197], v[92:95]
	ds_read_b128 v[12:15], v248 offset:3072
	v_mfma_f32_16x16x32_bf16 v[52:55], v[232:235], v[208:211], v[52:55]
	ds_read_b128 v[166:169], v249 offset:11264
	v_mfma_f32_16x16x32_bf16 v[48:51], v[236:239], v[186:189], v[48:51]
	ds_read_b128 v[170:173], v249 offset:12288
	v_mfma_f32_16x16x32_bf16 v[28:31], v[236:239], v[190:193], v[28:31]
	ds_read_b128 v[174:177], v249 offset:13312
	v_mfma_f32_16x16x32_bf16 v[96:99], v[236:239], v[194:197], v[96:99]
	ds_read_b128 v[178:181], v249 offset:14336
	v_mfma_f32_16x16x32_bf16 v[44:47], v[236:239], v[208:211], v[44:47]
	ds_read_b128 v[182:185], v249 offset:15360
	v_mfma_f32_16x16x32_bf16 v[40:43], v[240:243], v[186:189], v[40:43]
	v_mfma_f32_16x16x32_bf16 v[24:27], v[240:243], v[190:193], v[24:27]
	v_mfma_f32_16x16x32_bf16 v[84:87], v[240:243], v[194:197], v[84:87]
	v_mfma_f32_16x16x32_bf16 v[148:151], v[240:243], v[208:211], v[148:151]
	s_add_u32 s30, s30, 24576
	s_cmp_eq_u32 s30, 73728
	s_cselect_b32 s30, 0, s30
	s_waitcnt lgkmcnt(0)
	v_mfma_f32_16x16x32_bf16 v[128:131], v[16:19], v[0:3], v[128:131]
	v_mfma_f32_16x16x32_bf16 v[80:83], v[16:19], v[4:7], v[80:83]
	v_mfma_f32_16x16x32_bf16 v[108:111], v[16:19], v[8:11], v[108:111]
	v_mfma_f32_16x16x32_bf16 v[132:135], v[16:19], v[12:15], v[132:135]
	v_mfma_f32_16x16x32_bf16 v[120:123], v[20:23], v[0:3], v[120:123]
	v_mfma_f32_16x16x32_bf16 v[72:75], v[20:23], v[4:7], v[72:75]
	v_mfma_f32_16x16x32_bf16 v[112:115], v[20:23], v[8:11], v[112:115]
	v_mfma_f32_16x16x32_bf16 v[136:139], v[20:23], v[12:15], v[136:139]
	v_mfma_f32_16x16x32_bf16 v[104:107], v[162:165], v[0:3], v[104:107]
	v_mfma_f32_16x16x32_bf16 v[64:67], v[162:165], v[4:7], v[64:67]
	v_mfma_f32_16x16x32_bf16 v[116:119], v[162:165], v[8:11], v[116:119]
	v_mfma_f32_16x16x32_bf16 v[140:143], v[162:165], v[12:15], v[140:143]
	v_mfma_f32_16x16x32_bf16 v[100:103], v[166:169], v[0:3], v[100:103]
	v_mfma_f32_16x16x32_bf16 v[60:63], v[166:169], v[4:7], v[60:63]
	v_mfma_f32_16x16x32_bf16 v[124:127], v[166:169], v[8:11], v[124:127]
	v_mfma_f32_16x16x32_bf16 v[144:147], v[166:169], v[12:15], v[144:147]
	v_mfma_f32_16x16x32_bf16 v[68:71], v[170:173], v[0:3], v[68:71]
	v_mfma_f32_16x16x32_bf16 v[36:39], v[170:173], v[4:7], v[36:39]
	v_mfma_f32_16x16x32_bf16 v[88:91], v[170:173], v[8:11], v[88:91]
	v_mfma_f32_16x16x32_bf16 v[76:79], v[170:173], v[12:15], v[76:79]
	v_mfma_f32_16x16x32_bf16 v[56:59], v[174:177], v[0:3], v[56:59]
	v_mfma_f32_16x16x32_bf16 v[32:35], v[174:177], v[4:7], v[32:35]
	v_mfma_f32_16x16x32_bf16 v[92:95], v[174:177], v[8:11], v[92:95]
	v_mfma_f32_16x16x32_bf16 v[52:55], v[174:177], v[12:15], v[52:55]
	v_mfma_f32_16x16x32_bf16 v[48:51], v[178:181], v[0:3], v[48:51]
	v_mfma_f32_16x16x32_bf16 v[28:31], v[178:181], v[4:7], v[28:31]
	v_mfma_f32_16x16x32_bf16 v[96:99], v[178:181], v[8:11], v[96:99]
	v_mfma_f32_16x16x32_bf16 v[44:47], v[178:181], v[12:15], v[44:47]
	v_mfma_f32_16x16x32_bf16 v[40:43], v[182:185], v[0:3], v[40:43]
	v_mfma_f32_16x16x32_bf16 v[24:27], v[182:185], v[4:7], v[24:27]
	v_mfma_f32_16x16x32_bf16 v[84:87], v[182:185], v[8:11], v[84:87]
	v_mfma_f32_16x16x32_bf16 v[148:151], v[182:185], v[12:15], v[148:151]
	v_mov_b32 v250, v198
	s_nop 0
	v_and_b32_e32 v251, 15, v250
	v_bfe_u32 v156, v250, 4, 2
	v_bfe_u32 v157, v250, 6, 1
	v_bfe_u32 v158, v250, 7, 1
	v_lshl_add_u32 v158, v158, 6, s10
	v_add_u32_e32 v158, v158, v251
	v_lshl_add_u32 v157, v157, 7, s11
	v_lshl_add_u32 v159, v156, 2, v157
	v_lshlrev_b32_e32 v246, 2, v159
	v_lshl_add_u32 v244, v158, 12, v246
	v_lshlrev_b32_e32 v161, 1, v159
	v_lshl_add_u32 v245, v158, 11, v161
	v_and_b32_e32 v254, 1, v156
	v_mul_u32_u24_e32 v254, 24, v254
	v_lshl_add_u32 v254, v156, 3, v254
	v_lshl_add_u32 v254, v158, 6, v254
	v_lshrrev_b32_e32 v161, 5, v157
	v_lshl_add_u32 v254, v161, 21, v254
	v_lshrrev_b32_e32 v161, 6, v157
	v_lshlrev_b32_e32 v161, 2, v161
	v_lshl_add_u32 v247, v158, 6, v161
	v_xor_b32_e32 v248, 16, v200
	v_lshlrev_b32_e32 v248, 2, v248
	v_xor_b32_e32 v249, 32, v200
	v_lshlrev_b32_e32 v249, 2, v249
	s_mov_b32 s24, s6
	s_mov_b32 s25, s7
	s_mov_b32 s26, s78
	s_mov_b32 s27, s79
	v_readlane_b32 s28, v253, 21
	v_readlane_b32 s29, v253, 22
	s_mov_b32 s30, s94
	s_mov_b32 s31, s95
	s_mov_b32 s22, s28
	s_mov_b32 s23, s29
	global_load_dwordx4 v[208:211], v246, s[8:9]
	global_load_dwordx4 v[212:215], v246, s[8:9] offset:64
	global_load_dwordx4 v[216:219], v246, s[8:9] offset:128
	global_load_dwordx4 v[220:223], v246, s[8:9] offset:192
	global_load_dwordx4 v[224:227], v246, s[8:9] offset:256
	global_load_dwordx4 v[228:231], v246, s[8:9] offset:320
	global_load_dwordx4 v[232:235], v246, s[8:9] offset:384
	global_load_dwordx4 v[236:239], v246, s[8:9] offset:448
	global_load_dwordx4 v[0:3], v244, s[24:25]
	global_load_dwordx4 v[4:7], v244, s[24:25] offset:64
	global_load_dwordx4 v[8:11], v244, s[24:25] offset:128
	global_load_dwordx4 v[12:15], v244, s[24:25] offset:192
	global_load_dwordx4 v[16:19], v244, s[24:25] offset:256
	global_load_dwordx4 v[20:23], v244, s[24:25] offset:320
	global_load_dwordx4 v[162:165], v244, s[24:25] offset:384
	global_load_dwordx4 v[166:169], v244, s[24:25] offset:448
	s_add_u32 s24, s24, 0x10000
	s_addc_u32 s25, s25, 0
	global_load_dwordx4 v[170:173], v244, s[24:25]
	global_load_dwordx4 v[174:177], v244, s[24:25] offset:64
	global_load_dwordx4 v[178:181], v244, s[24:25] offset:128
	global_load_dwordx4 v[182:185], v244, s[24:25] offset:192
	global_load_dwordx4 v[186:189], v244, s[24:25] offset:256
	global_load_dwordx4 v[190:193], v244, s[24:25] offset:320
	global_load_dwordx4 v[194:197], v244, s[24:25] offset:384
	global_load_dwordx4 v[240:243], v244, s[24:25] offset:448
	s_add_u32 s24, s24, 0x10000
	s_addc_u32 s25, s25, 0
	s_waitcnt vmcnt(12)
	v_add_f32_e32 v0, v128, v0
	v_add_f32_e32 v1, v129, v1
	v_add_f32_e32 v2, v130, v2
	v_add_f32_e32 v3, v131, v3
	global_store_dwordx4 v244, v[0:3], s[26:27]
	v_mul_f32_e32 v158, v0, v0
	v_mul_f32_e32 v159, v1, v1
	v_mul_f32_e32 v250, v2, v2
	v_mul_f32_e32 v251, v3, v3
	v_add_f32_e32 v158, v158, v159
	v_add_f32_e32 v250, v250, v251
	v_add_f32_e32 v161, v158, v250
	v_mul_f32_e32 v156, v0, v208
	v_mul_f32_e32 v157, v1, v209
	v_mul_f32_e32 v158, v2, v210
	v_mul_f32_e32 v159, v3, v211
	v_cvt_pk_bf16_f32 v156, v156, v157
	v_cvt_pk_bf16_f32 v157, v158, v159
	v_add_f32_e32 v4, v120, v4
	v_add_f32_e32 v5, v121, v5
	v_add_f32_e32 v6, v122, v6
	v_add_f32_e32 v7, v123, v7
	global_store_dwordx4 v244, v[4:7], s[26:27] offset:64
	v_mul_f32_e32 v158, v4, v4
	v_mul_f32_e32 v159, v5, v5
	v_mul_f32_e32 v250, v6, v6
	v_mul_f32_e32 v251, v7, v7
	v_add_f32_e32 v158, v158, v159
	v_add_f32_e32 v250, v250, v251
	v_add_f32_e32 v158, v158, v250
	v_add_f32_e32 v161, v161, v158
	v_mul_f32_e32 v158, v4, v212
	v_mul_f32_e32 v159, v5, v213
	v_mul_f32_e32 v250, v6, v214
	v_mul_f32_e32 v251, v7, v215
	v_cvt_pk_bf16_f32 v158, v158, v159
	v_cvt_pk_bf16_f32 v159, v250, v251
	s_nop 1
	v_permlane16_swap_b32_e32 v156, v158
	v_permlane16_swap_b32_e32 v157, v159
	s_add_u32 s28, s22, 0x0
	s_addc_u32 s29, s23, 0
	global_store_dwordx4 v254, v[156:159], s[28:29]
	v_add_f32_e32 v8, v104, v8
	v_add_f32_e32 v9, v105, v9
	v_add_f32_e32 v10, v106, v10
	v_add_f32_e32 v11, v107, v11
	global_store_dwordx4 v244, v[8:11], s[26:27] offset:128
	v_mul_f32_e32 v158, v8, v8
	v_mul_f32_e32 v159, v9, v9
	v_mul_f32_e32 v250, v10, v10
	v_mul_f32_e32 v251, v11, v11
	v_add_f32_e32 v158, v158, v159
	v_add_f32_e32 v250, v250, v251
	v_add_f32_e32 v158, v158, v250
	v_add_f32_e32 v161, v161, v158
	v_mul_f32_e32 v156, v8, v216
	v_mul_f32_e32 v157, v9, v217
	v_mul_f32_e32 v158, v10, v218
	v_mul_f32_e32 v159, v11, v219
	v_cvt_pk_bf16_f32 v156, v156, v157
	v_cvt_pk_bf16_f32 v157, v158, v159
	v_add_f32_e32 v12, v100, v12
	v_add_f32_e32 v13, v101, v13
	v_add_f32_e32 v14, v102, v14
	v_add_f32_e32 v15, v103, v15
	global_store_dwordx4 v244, v[12:15], s[26:27] offset:192
	v_mul_f32_e32 v158, v12, v12
	v_mul_f32_e32 v159, v13, v13
	v_mul_f32_e32 v250, v14, v14
	v_mul_f32_e32 v251, v15, v15
	v_add_f32_e32 v158, v158, v159
	v_add_f32_e32 v250, v250, v251
	v_add_f32_e32 v158, v158, v250
	v_add_f32_e32 v161, v161, v158
	v_mul_f32_e32 v158, v12, v220
	v_mul_f32_e32 v159, v13, v221
	v_mul_f32_e32 v250, v14, v222
	v_mul_f32_e32 v251, v15, v223
	v_cvt_pk_bf16_f32 v158, v158, v159
	v_cvt_pk_bf16_f32 v159, v250, v251
	s_nop 1
	v_permlane16_swap_b32_e32 v156, v158
	v_permlane16_swap_b32_e32 v157, v159
	s_add_u32 s28, s22, 0x200000
	s_addc_u32 s29, s23, 0
	global_store_dwordx4 v254, v[156:159], s[28:29]
	ds_bpermute_b32 v158, v248, v161
	s_waitcnt lgkmcnt(0)
	v_add_f32_e32 v161, v161, v158
	ds_bpermute_b32 v158, v249, v161
	s_waitcnt lgkmcnt(0)
	v_add_f32_e32 v161, v161, v158
	global_store_dword v247, v161, s[30:31]
	global_load_dwordx4 v[0:3], v244, s[24:25]
	global_load_dwordx4 v[4:7], v244, s[24:25] offset:64
	global_load_dwordx4 v[8:11], v244, s[24:25] offset:128
	global_load_dwordx4 v[12:15], v244, s[24:25] offset:192
	s_waitcnt vmcnt(19)
	v_add_f32_e32 v16, v68, v16
	v_add_f32_e32 v17, v69, v17
	v_add_f32_e32 v18, v70, v18
	v_add_f32_e32 v19, v71, v19
	global_store_dwordx4 v244, v[16:19], s[26:27] offset:256
	v_mul_f32_e32 v158, v16, v16
	v_mul_f32_e32 v159, v17, v17
	v_mul_f32_e32 v250, v18, v18
	v_mul_f32_e32 v251, v19, v19
	v_add_f32_e32 v158, v158, v159
	v_add_f32_e32 v250, v250, v251
	v_add_f32_e32 v161, v158, v250
	v_mul_f32_e32 v156, v16, v224
	v_mul_f32_e32 v157, v17, v225
	v_mul_f32_e32 v158, v18, v226
	v_mul_f32_e32 v159, v19, v227
	v_cvt_pk_bf16_f32 v156, v156, v157
	v_cvt_pk_bf16_f32 v157, v158, v159
	v_add_f32_e32 v20, v56, v20
	v_add_f32_e32 v21, v57, v21
	v_add_f32_e32 v22, v58, v22
	v_add_f32_e32 v23, v59, v23
	global_store_dwordx4 v244, v[20:23], s[26:27] offset:320
	v_mul_f32_e32 v158, v20, v20
	v_mul_f32_e32 v159, v21, v21
	v_mul_f32_e32 v250, v22, v22
	v_mul_f32_e32 v251, v23, v23
	v_add_f32_e32 v158, v158, v159
	v_add_f32_e32 v250, v250, v251
	v_add_f32_e32 v158, v158, v250
	v_add_f32_e32 v161, v161, v158
	v_mul_f32_e32 v158, v20, v228
	v_mul_f32_e32 v159, v21, v229
	v_mul_f32_e32 v250, v22, v230
	v_mul_f32_e32 v251, v23, v231
	v_cvt_pk_bf16_f32 v158, v158, v159
	v_cvt_pk_bf16_f32 v159, v250, v251
	s_nop 1
	v_permlane16_swap_b32_e32 v156, v158
	v_permlane16_swap_b32_e32 v157, v159
	s_add_u32 s28, s22, 0x400000
	s_addc_u32 s29, s23, 0
	global_store_dwordx4 v254, v[156:159], s[28:29]
	v_add_f32_e32 v162, v48, v162
	v_add_f32_e32 v163, v49, v163
	v_add_f32_e32 v164, v50, v164
	v_add_f32_e32 v165, v51, v165
	global_store_dwordx4 v244, v[162:165], s[26:27] offset:384
	v_mul_f32_e32 v158, v162, v162
	v_mul_f32_e32 v159, v163, v163
	v_mul_f32_e32 v250, v164, v164
	v_mul_f32_e32 v251, v165, v165
	v_add_f32_e32 v158, v158, v159
	v_add_f32_e32 v250, v250, v251
	v_add_f32_e32 v158, v158, v250
	v_add_f32_e32 v161, v161, v158
	v_mul_f32_e32 v156, v162, v232
	v_mul_f32_e32 v157, v163, v233
	v_mul_f32_e32 v158, v164, v234
	v_mul_f32_e32 v159, v165, v235
	v_cvt_pk_bf16_f32 v156, v156, v157
	v_cvt_pk_bf16_f32 v157, v158, v159
	v_add_f32_e32 v166, v40, v166
	v_add_f32_e32 v167, v41, v167
	v_add_f32_e32 v168, v42, v168
	v_add_f32_e32 v169, v43, v169
	global_store_dwordx4 v244, v[166:169], s[26:27] offset:448
	v_mul_f32_e32 v158, v166, v166
	v_mul_f32_e32 v159, v167, v167
	v_mul_f32_e32 v250, v168, v168
	v_mul_f32_e32 v251, v169, v169
	v_add_f32_e32 v158, v158, v159
	v_add_f32_e32 v250, v250, v251
	v_add_f32_e32 v158, v158, v250
	v_add_f32_e32 v161, v161, v158
	v_mul_f32_e32 v158, v166, v236
	v_mul_f32_e32 v159, v167, v237
	v_mul_f32_e32 v250, v168, v238
	v_mul_f32_e32 v251, v169, v239
	v_cvt_pk_bf16_f32 v158, v158, v159
	v_cvt_pk_bf16_f32 v159, v250, v251
	s_nop 1
	v_permlane16_swap_b32_e32 v156, v158
	v_permlane16_swap_b32_e32 v157, v159
	s_add_u32 s28, s22, 0x600000
	s_addc_u32 s29, s23, 0
	global_store_dwordx4 v254, v[156:159], s[28:29]
	ds_bpermute_b32 v158, v248, v161
	s_waitcnt lgkmcnt(0)
	v_add_f32_e32 v161, v161, v158
	ds_bpermute_b32 v158, v249, v161
	s_waitcnt lgkmcnt(0)
	v_add_f32_e32 v161, v161, v158
	global_store_dword v247, v161, s[30:31] offset:4
	s_add_u32 s26, s26, 0x10000
	s_addc_u32 s27, s27, 0
	s_add_u32 s30, s30, 0x400
	s_addc_u32 s31, s31, 0
	global_load_dwordx4 v[16:19], v244, s[24:25] offset:256
	global_load_dwordx4 v[20:23], v244, s[24:25] offset:320
	global_load_dwordx4 v[162:165], v244, s[24:25] offset:384
	global_load_dwordx4 v[166:169], v244, s[24:25] offset:448
	s_add_u32 s24, s24, 0x10000
	s_addc_u32 s25, s25, 0
	s_waitcnt vmcnt(26)
	v_add_f32_e32 v170, v80, v170
	v_add_f32_e32 v171, v81, v171
	v_add_f32_e32 v172, v82, v172
	v_add_f32_e32 v173, v83, v173
	global_store_dwordx4 v244, v[170:173], s[26:27]
	v_mul_f32_e32 v158, v170, v170
	v_mul_f32_e32 v159, v171, v171
	v_mul_f32_e32 v250, v172, v172
	v_mul_f32_e32 v251, v173, v173
	v_add_f32_e32 v158, v158, v159
	v_add_f32_e32 v250, v250, v251
	v_add_f32_e32 v161, v158, v250
	v_mul_f32_e32 v156, v170, v208
	v_mul_f32_e32 v157, v171, v209
	v_mul_f32_e32 v158, v172, v210
	v_mul_f32_e32 v159, v173, v211
	v_cvt_pk_bf16_f32 v156, v156, v157
	v_cvt_pk_bf16_f32 v157, v158, v159
	v_add_f32_e32 v174, v72, v174
	v_add_f32_e32 v175, v73, v175
	v_add_f32_e32 v176, v74, v176
	v_add_f32_e32 v177, v75, v177
	global_store_dwordx4 v244, v[174:177], s[26:27] offset:64
	v_mul_f32_e32 v158, v174, v174
	v_mul_f32_e32 v159, v175, v175
	v_mul_f32_e32 v250, v176, v176
	v_mul_f32_e32 v251, v177, v177
	v_add_f32_e32 v158, v158, v159
	v_add_f32_e32 v250, v250, v251
	v_add_f32_e32 v158, v158, v250
	v_add_f32_e32 v161, v161, v158
	v_mul_f32_e32 v158, v174, v212
	v_mul_f32_e32 v159, v175, v213
	v_mul_f32_e32 v250, v176, v214
	v_mul_f32_e32 v251, v177, v215
	v_cvt_pk_bf16_f32 v158, v158, v159
	v_cvt_pk_bf16_f32 v159, v250, v251
	s_nop 1
	v_permlane16_swap_b32_e32 v156, v158
	v_permlane16_swap_b32_e32 v157, v159
	s_add_u32 s28, s22, 0x400
	s_addc_u32 s29, s23, 0
	global_store_dwordx4 v254, v[156:159], s[28:29]
	v_add_f32_e32 v178, v64, v178
	v_add_f32_e32 v179, v65, v179
	v_add_f32_e32 v180, v66, v180
	v_add_f32_e32 v181, v67, v181
	global_store_dwordx4 v244, v[178:181], s[26:27] offset:128
	v_mul_f32_e32 v158, v178, v178
	v_mul_f32_e32 v159, v179, v179
	v_mul_f32_e32 v250, v180, v180
	v_mul_f32_e32 v251, v181, v181
	v_add_f32_e32 v158, v158, v159
	v_add_f32_e32 v250, v250, v251
	v_add_f32_e32 v158, v158, v250
	v_add_f32_e32 v161, v161, v158
	v_mul_f32_e32 v156, v178, v216
	v_mul_f32_e32 v157, v179, v217
	v_mul_f32_e32 v158, v180, v218
	v_mul_f32_e32 v159, v181, v219
	v_cvt_pk_bf16_f32 v156, v156, v157
	v_cvt_pk_bf16_f32 v157, v158, v159
	v_add_f32_e32 v182, v60, v182
	v_add_f32_e32 v183, v61, v183
	v_add_f32_e32 v184, v62, v184
	v_add_f32_e32 v185, v63, v185
	global_store_dwordx4 v244, v[182:185], s[26:27] offset:192
	v_mul_f32_e32 v158, v182, v182
	v_mul_f32_e32 v159, v183, v183
	v_mul_f32_e32 v250, v184, v184
	v_mul_f32_e32 v251, v185, v185
	v_add_f32_e32 v158, v158, v159
	v_add_f32_e32 v250, v250, v251
	v_add_f32_e32 v158, v158, v250
	v_add_f32_e32 v161, v161, v158
	v_mul_f32_e32 v158, v182, v220
	v_mul_f32_e32 v159, v183, v221
	v_mul_f32_e32 v250, v184, v222
	v_mul_f32_e32 v251, v185, v223
	v_cvt_pk_bf16_f32 v158, v158, v159
	v_cvt_pk_bf16_f32 v159, v250, v251
	s_nop 1
	v_permlane16_swap_b32_e32 v156, v158
	v_permlane16_swap_b32_e32 v157, v159
	s_add_u32 s28, s22, 0x200400
	s_addc_u32 s29, s23, 0
	global_store_dwordx4 v254, v[156:159], s[28:29]
	ds_bpermute_b32 v158, v248, v161
	s_waitcnt lgkmcnt(0)
	v_add_f32_e32 v161, v161, v158
	ds_bpermute_b32 v158, v249, v161
	s_waitcnt lgkmcnt(0)
	v_add_f32_e32 v161, v161, v158
	global_store_dword v247, v161, s[30:31]
	global_load_dwordx4 v[170:173], v244, s[24:25]
	global_load_dwordx4 v[174:177], v244, s[24:25] offset:64
	global_load_dwordx4 v[178:181], v244, s[24:25] offset:128
	global_load_dwordx4 v[182:185], v244, s[24:25] offset:192
	s_waitcnt vmcnt(33)
	v_add_f32_e32 v186, v36, v186
	v_add_f32_e32 v187, v37, v187
	v_add_f32_e32 v188, v38, v188
	v_add_f32_e32 v189, v39, v189
	global_store_dwordx4 v244, v[186:189], s[26:27] offset:256
	v_mul_f32_e32 v158, v186, v186
	v_mul_f32_e32 v159, v187, v187
	v_mul_f32_e32 v250, v188, v188
	v_mul_f32_e32 v251, v189, v189
	v_add_f32_e32 v158, v158, v159
	v_add_f32_e32 v250, v250, v251
	v_add_f32_e32 v161, v158, v250
	v_mul_f32_e32 v156, v186, v224
	v_mul_f32_e32 v157, v187, v225
	v_mul_f32_e32 v158, v188, v226
	v_mul_f32_e32 v159, v189, v227
	v_cvt_pk_bf16_f32 v156, v156, v157
	v_cvt_pk_bf16_f32 v157, v158, v159
	v_add_f32_e32 v190, v32, v190
	v_add_f32_e32 v191, v33, v191
	v_add_f32_e32 v192, v34, v192
	v_add_f32_e32 v193, v35, v193
	global_store_dwordx4 v244, v[190:193], s[26:27] offset:320
	v_mul_f32_e32 v158, v190, v190
	v_mul_f32_e32 v159, v191, v191
	v_mul_f32_e32 v250, v192, v192
	v_mul_f32_e32 v251, v193, v193
	v_add_f32_e32 v158, v158, v159
	v_add_f32_e32 v250, v250, v251
	v_add_f32_e32 v158, v158, v250
	v_add_f32_e32 v161, v161, v158
	v_mul_f32_e32 v158, v190, v228
	v_mul_f32_e32 v159, v191, v229
	v_mul_f32_e32 v250, v192, v230
	v_mul_f32_e32 v251, v193, v231
	v_cvt_pk_bf16_f32 v158, v158, v159
	v_cvt_pk_bf16_f32 v159, v250, v251
	s_nop 1
	v_permlane16_swap_b32_e32 v156, v158
	v_permlane16_swap_b32_e32 v157, v159
	s_add_u32 s28, s22, 0x400400
	s_addc_u32 s29, s23, 0
	global_store_dwordx4 v254, v[156:159], s[28:29]
	v_add_f32_e32 v194, v28, v194
	v_add_f32_e32 v195, v29, v195
	v_add_f32_e32 v196, v30, v196
	v_add_f32_e32 v197, v31, v197
	global_store_dwordx4 v244, v[194:197], s[26:27] offset:384
	v_mul_f32_e32 v158, v194, v194
	v_mul_f32_e32 v159, v195, v195
	v_mul_f32_e32 v250, v196, v196
	v_mul_f32_e32 v251, v197, v197
	v_add_f32_e32 v158, v158, v159
	v_add_f32_e32 v250, v250, v251
	v_add_f32_e32 v158, v158, v250
	v_add_f32_e32 v161, v161, v158
	v_mul_f32_e32 v156, v194, v232
	v_mul_f32_e32 v157, v195, v233
	v_mul_f32_e32 v158, v196, v234
	v_mul_f32_e32 v159, v197, v235
	v_cvt_pk_bf16_f32 v156, v156, v157
	v_cvt_pk_bf16_f32 v157, v158, v159
	v_add_f32_e32 v240, v24, v240
	v_add_f32_e32 v241, v25, v241
	v_add_f32_e32 v242, v26, v242
	v_add_f32_e32 v243, v27, v243
	global_store_dwordx4 v244, v[240:243], s[26:27] offset:448
	v_mul_f32_e32 v158, v240, v240
	v_mul_f32_e32 v159, v241, v241
	v_mul_f32_e32 v250, v242, v242
	v_mul_f32_e32 v251, v243, v243
	v_add_f32_e32 v158, v158, v159
	v_add_f32_e32 v250, v250, v251
	v_add_f32_e32 v158, v158, v250
	v_add_f32_e32 v161, v161, v158
	v_mul_f32_e32 v158, v240, v236
	v_mul_f32_e32 v159, v241, v237
	v_mul_f32_e32 v250, v242, v238
	v_mul_f32_e32 v251, v243, v239
	v_cvt_pk_bf16_f32 v158, v158, v159
	v_cvt_pk_bf16_f32 v159, v250, v251
	s_nop 1
	v_permlane16_swap_b32_e32 v156, v158
	v_permlane16_swap_b32_e32 v157, v159
	s_add_u32 s28, s22, 0x600400
	s_addc_u32 s29, s23, 0
	global_store_dwordx4 v254, v[156:159], s[28:29]
	ds_bpermute_b32 v158, v248, v161
	s_waitcnt lgkmcnt(0)
	v_add_f32_e32 v161, v161, v158
	ds_bpermute_b32 v158, v249, v161
	s_waitcnt lgkmcnt(0)
	v_add_f32_e32 v161, v161, v158
	global_store_dword v247, v161, s[30:31] offset:4
	s_add_u32 s26, s26, 0x10000
	s_addc_u32 s27, s27, 0
	s_add_u32 s30, s30, 0x400
	s_addc_u32 s31, s31, 0
	global_load_dwordx4 v[186:189], v244, s[24:25] offset:256
	global_load_dwordx4 v[190:193], v244, s[24:25] offset:320
	global_load_dwordx4 v[194:197], v244, s[24:25] offset:384
	global_load_dwordx4 v[240:243], v244, s[24:25] offset:448
	s_add_u32 s24, s24, 0x10000
	s_addc_u32 s25, s25, 0
	s_waitcnt vmcnt(33)
	v_add_f32_e32 v0, v108, v0
	v_add_f32_e32 v1, v109, v1
	v_add_f32_e32 v2, v110, v2
	v_add_f32_e32 v3, v111, v3
	global_store_dwordx4 v244, v[0:3], s[26:27]
	v_mul_f32_e32 v158, v0, v0
	v_mul_f32_e32 v159, v1, v1
	v_mul_f32_e32 v250, v2, v2
	v_mul_f32_e32 v251, v3, v3
	v_add_f32_e32 v158, v158, v159
	v_add_f32_e32 v250, v250, v251
	v_add_f32_e32 v161, v158, v250
	v_mul_f32_e32 v156, v0, v208
	v_mul_f32_e32 v157, v1, v209
	v_mul_f32_e32 v158, v2, v210
	v_mul_f32_e32 v159, v3, v211
	v_cvt_pk_bf16_f32 v156, v156, v157
	v_cvt_pk_bf16_f32 v157, v158, v159
	v_add_f32_e32 v4, v112, v4
	v_add_f32_e32 v5, v113, v5
	v_add_f32_e32 v6, v114, v6
	v_add_f32_e32 v7, v115, v7
	global_store_dwordx4 v244, v[4:7], s[26:27] offset:64
	v_mul_f32_e32 v158, v4, v4
	v_mul_f32_e32 v159, v5, v5
	v_mul_f32_e32 v250, v6, v6
	v_mul_f32_e32 v251, v7, v7
	v_add_f32_e32 v158, v158, v159
	v_add_f32_e32 v250, v250, v251
	v_add_f32_e32 v158, v158, v250
	v_add_f32_e32 v161, v161, v158
	v_mul_f32_e32 v158, v4, v212
	v_mul_f32_e32 v159, v5, v213
	v_mul_f32_e32 v250, v6, v214
	v_mul_f32_e32 v251, v7, v215
	v_cvt_pk_bf16_f32 v158, v158, v159
	v_cvt_pk_bf16_f32 v159, v250, v251
	s_nop 1
	v_permlane16_swap_b32_e32 v156, v158
	v_permlane16_swap_b32_e32 v157, v159
	s_add_u32 s28, s22, 0x800
	s_addc_u32 s29, s23, 0
	global_store_dwordx4 v254, v[156:159], s[28:29]
	v_add_f32_e32 v8, v116, v8
	v_add_f32_e32 v9, v117, v9
	v_add_f32_e32 v10, v118, v10
	v_add_f32_e32 v11, v119, v11
	global_store_dwordx4 v244, v[8:11], s[26:27] offset:128
	v_mul_f32_e32 v158, v8, v8
	v_mul_f32_e32 v159, v9, v9
	v_mul_f32_e32 v250, v10, v10
	v_mul_f32_e32 v251, v11, v11
	v_add_f32_e32 v158, v158, v159
	v_add_f32_e32 v250, v250, v251
	v_add_f32_e32 v158, v158, v250
	v_add_f32_e32 v161, v161, v158
	v_mul_f32_e32 v156, v8, v216
	v_mul_f32_e32 v157, v9, v217
	v_mul_f32_e32 v158, v10, v218
	v_mul_f32_e32 v159, v11, v219
	v_cvt_pk_bf16_f32 v156, v156, v157
	v_cvt_pk_bf16_f32 v157, v158, v159
	v_add_f32_e32 v12, v124, v12
	v_add_f32_e32 v13, v125, v13
	v_add_f32_e32 v14, v126, v14
	v_add_f32_e32 v15, v127, v15
	global_store_dwordx4 v244, v[12:15], s[26:27] offset:192
	v_mul_f32_e32 v158, v12, v12
	v_mul_f32_e32 v159, v13, v13
	v_mul_f32_e32 v250, v14, v14
	v_mul_f32_e32 v251, v15, v15
	v_add_f32_e32 v158, v158, v159
	v_add_f32_e32 v250, v250, v251
	v_add_f32_e32 v158, v158, v250
	v_add_f32_e32 v161, v161, v158
	v_mul_f32_e32 v158, v12, v220
	v_mul_f32_e32 v159, v13, v221
	v_mul_f32_e32 v250, v14, v222
	v_mul_f32_e32 v251, v15, v223
	v_cvt_pk_bf16_f32 v158, v158, v159
	v_cvt_pk_bf16_f32 v159, v250, v251
	s_nop 1
	v_permlane16_swap_b32_e32 v156, v158
	v_permlane16_swap_b32_e32 v157, v159
	s_add_u32 s28, s22, 0x200800
	s_addc_u32 s29, s23, 0
	global_store_dwordx4 v254, v[156:159], s[28:29]
	ds_bpermute_b32 v158, v248, v161
	s_waitcnt lgkmcnt(0)
	v_add_f32_e32 v161, v161, v158
	ds_bpermute_b32 v158, v249, v161
	s_waitcnt lgkmcnt(0)
	v_add_f32_e32 v161, v161, v158
	global_store_dword v247, v161, s[30:31]
	s_waitcnt vmcnt(29)
	v_add_f32_e32 v16, v88, v16
	v_add_f32_e32 v17, v89, v17
	v_add_f32_e32 v18, v90, v18
	v_add_f32_e32 v19, v91, v19
	global_store_dwordx4 v244, v[16:19], s[26:27] offset:256
	v_mul_f32_e32 v158, v16, v16
	v_mul_f32_e32 v159, v17, v17
	v_mul_f32_e32 v250, v18, v18
	v_mul_f32_e32 v251, v19, v19
	v_add_f32_e32 v158, v158, v159
	v_add_f32_e32 v250, v250, v251
	v_add_f32_e32 v161, v158, v250
	v_mul_f32_e32 v156, v16, v224
	v_mul_f32_e32 v157, v17, v225
	v_mul_f32_e32 v158, v18, v226
	v_mul_f32_e32 v159, v19, v227
	v_cvt_pk_bf16_f32 v156, v156, v157
	v_cvt_pk_bf16_f32 v157, v158, v159
	v_add_f32_e32 v20, v92, v20
	v_add_f32_e32 v21, v93, v21
	v_add_f32_e32 v22, v94, v22
	v_add_f32_e32 v23, v95, v23
	global_store_dwordx4 v244, v[20:23], s[26:27] offset:320
	v_mul_f32_e32 v158, v20, v20
	v_mul_f32_e32 v159, v21, v21
	v_mul_f32_e32 v250, v22, v22
	v_mul_f32_e32 v251, v23, v23
	v_add_f32_e32 v158, v158, v159
	v_add_f32_e32 v250, v250, v251
	v_add_f32_e32 v158, v158, v250
	v_add_f32_e32 v161, v161, v158
	v_mul_f32_e32 v158, v20, v228
	v_mul_f32_e32 v159, v21, v229
	v_mul_f32_e32 v250, v22, v230
	v_mul_f32_e32 v251, v23, v231
	v_cvt_pk_bf16_f32 v158, v158, v159
	v_cvt_pk_bf16_f32 v159, v250, v251
	s_nop 1
	v_permlane16_swap_b32_e32 v156, v158
	v_permlane16_swap_b32_e32 v157, v159
	s_add_u32 s28, s22, 0x400800
	s_addc_u32 s29, s23, 0
	global_store_dwordx4 v254, v[156:159], s[28:29]
	v_add_f32_e32 v162, v96, v162
	v_add_f32_e32 v163, v97, v163
	v_add_f32_e32 v164, v98, v164
	v_add_f32_e32 v165, v99, v165
	global_store_dwordx4 v244, v[162:165], s[26:27] offset:384
	v_mul_f32_e32 v158, v162, v162
	v_mul_f32_e32 v159, v163, v163
	v_mul_f32_e32 v250, v164, v164
	v_mul_f32_e32 v251, v165, v165
	v_add_f32_e32 v158, v158, v159
	v_add_f32_e32 v250, v250, v251
	v_add_f32_e32 v158, v158, v250
	v_add_f32_e32 v161, v161, v158
	v_mul_f32_e32 v156, v162, v232
	v_mul_f32_e32 v157, v163, v233
	v_mul_f32_e32 v158, v164, v234
	v_mul_f32_e32 v159, v165, v235
	v_cvt_pk_bf16_f32 v156, v156, v157
	v_cvt_pk_bf16_f32 v157, v158, v159
	v_add_f32_e32 v166, v84, v166
	v_add_f32_e32 v167, v85, v167
	v_add_f32_e32 v168, v86, v168
	v_add_f32_e32 v169, v87, v169
	global_store_dwordx4 v244, v[166:169], s[26:27] offset:448
	v_mul_f32_e32 v158, v166, v166
	v_mul_f32_e32 v159, v167, v167
	v_mul_f32_e32 v250, v168, v168
	v_mul_f32_e32 v251, v169, v169
	v_add_f32_e32 v158, v158, v159
	v_add_f32_e32 v250, v250, v251
	v_add_f32_e32 v158, v158, v250
	v_add_f32_e32 v161, v161, v158
	v_mul_f32_e32 v158, v166, v236
	v_mul_f32_e32 v159, v167, v237
	v_mul_f32_e32 v250, v168, v238
	v_mul_f32_e32 v251, v169, v239
	v_cvt_pk_bf16_f32 v158, v158, v159
	v_cvt_pk_bf16_f32 v159, v250, v251
	s_nop 1
	v_permlane16_swap_b32_e32 v156, v158
	v_permlane16_swap_b32_e32 v157, v159
	s_add_u32 s28, s22, 0x600800
	s_addc_u32 s29, s23, 0
	global_store_dwordx4 v254, v[156:159], s[28:29]
	ds_bpermute_b32 v158, v248, v161
	s_waitcnt lgkmcnt(0)
	v_add_f32_e32 v161, v161, v158
	ds_bpermute_b32 v158, v249, v161
	s_waitcnt lgkmcnt(0)
	v_add_f32_e32 v161, v161, v158
	global_store_dword v247, v161, s[30:31] offset:4
	s_add_u32 s26, s26, 0x10000
	s_addc_u32 s27, s27, 0
	s_add_u32 s30, s30, 0x400
	s_addc_u32 s31, s31, 0
	s_waitcnt vmcnt(25)
	v_add_f32_e32 v170, v132, v170
	v_add_f32_e32 v171, v133, v171
	v_add_f32_e32 v172, v134, v172
	v_add_f32_e32 v173, v135, v173
	global_store_dwordx4 v244, v[170:173], s[26:27]
	v_mul_f32_e32 v158, v170, v170
	v_mul_f32_e32 v159, v171, v171
	v_mul_f32_e32 v250, v172, v172
	v_mul_f32_e32 v251, v173, v173
	v_add_f32_e32 v158, v158, v159
	v_add_f32_e32 v250, v250, v251
	v_add_f32_e32 v161, v158, v250
	v_mul_f32_e32 v156, v170, v208
	v_mul_f32_e32 v157, v171, v209
	v_mul_f32_e32 v158, v172, v210
	v_mul_f32_e32 v159, v173, v211
	v_cvt_pk_bf16_f32 v156, v156, v157
	v_cvt_pk_bf16_f32 v157, v158, v159
	v_add_f32_e32 v174, v136, v174
	v_add_f32_e32 v175, v137, v175
	v_add_f32_e32 v176, v138, v176
	v_add_f32_e32 v177, v139, v177
	global_store_dwordx4 v244, v[174:177], s[26:27] offset:64
	v_mul_f32_e32 v158, v174, v174
	v_mul_f32_e32 v159, v175, v175
	v_mul_f32_e32 v250, v176, v176
	v_mul_f32_e32 v251, v177, v177
	v_add_f32_e32 v158, v158, v159
	v_add_f32_e32 v250, v250, v251
	v_add_f32_e32 v158, v158, v250
	v_add_f32_e32 v161, v161, v158
	v_mul_f32_e32 v158, v174, v212
	v_mul_f32_e32 v159, v175, v213
	v_mul_f32_e32 v250, v176, v214
	v_mul_f32_e32 v251, v177, v215
	v_cvt_pk_bf16_f32 v158, v158, v159
	v_cvt_pk_bf16_f32 v159, v250, v251
	s_nop 1
	v_permlane16_swap_b32_e32 v156, v158
	v_permlane16_swap_b32_e32 v157, v159
	s_add_u32 s28, s22, 0xc00
	s_addc_u32 s29, s23, 0
	global_store_dwordx4 v254, v[156:159], s[28:29]
	v_add_f32_e32 v178, v140, v178
	v_add_f32_e32 v179, v141, v179
	v_add_f32_e32 v180, v142, v180
	v_add_f32_e32 v181, v143, v181
	global_store_dwordx4 v244, v[178:181], s[26:27] offset:128
	v_mul_f32_e32 v158, v178, v178
	v_mul_f32_e32 v159, v179, v179
	v_mul_f32_e32 v250, v180, v180
	v_mul_f32_e32 v251, v181, v181
	v_add_f32_e32 v158, v158, v159
	v_add_f32_e32 v250, v250, v251
	v_add_f32_e32 v158, v158, v250
	v_add_f32_e32 v161, v161, v158
	v_mul_f32_e32 v156, v178, v216
	v_mul_f32_e32 v157, v179, v217
	v_mul_f32_e32 v158, v180, v218
	v_mul_f32_e32 v159, v181, v219
	v_cvt_pk_bf16_f32 v156, v156, v157
	v_cvt_pk_bf16_f32 v157, v158, v159
	v_add_f32_e32 v182, v144, v182
	v_add_f32_e32 v183, v145, v183
	v_add_f32_e32 v184, v146, v184
	v_add_f32_e32 v185, v147, v185
	global_store_dwordx4 v244, v[182:185], s[26:27] offset:192
	v_mul_f32_e32 v158, v182, v182
	v_mul_f32_e32 v159, v183, v183
	v_mul_f32_e32 v250, v184, v184
	v_mul_f32_e32 v251, v185, v185
	v_add_f32_e32 v158, v158, v159
	v_add_f32_e32 v250, v250, v251
	v_add_f32_e32 v158, v158, v250
	v_add_f32_e32 v161, v161, v158
	v_mul_f32_e32 v158, v182, v220
	v_mul_f32_e32 v159, v183, v221
	v_mul_f32_e32 v250, v184, v222
	v_mul_f32_e32 v251, v185, v223
	v_cvt_pk_bf16_f32 v158, v158, v159
	v_cvt_pk_bf16_f32 v159, v250, v251
	s_nop 1
	v_permlane16_swap_b32_e32 v156, v158
	v_permlane16_swap_b32_e32 v157, v159
	s_add_u32 s28, s22, 0x200c00
	s_addc_u32 s29, s23, 0
	global_store_dwordx4 v254, v[156:159], s[28:29]
	ds_bpermute_b32 v158, v248, v161
	s_waitcnt lgkmcnt(0)
	v_add_f32_e32 v161, v161, v158
	ds_bpermute_b32 v158, v249, v161
	s_waitcnt lgkmcnt(0)
	v_add_f32_e32 v161, v161, v158
	global_store_dword v247, v161, s[30:31]
	s_waitcnt vmcnt(21)
	v_add_f32_e32 v186, v76, v186
	v_add_f32_e32 v187, v77, v187
	v_add_f32_e32 v188, v78, v188
	v_add_f32_e32 v189, v79, v189
	global_store_dwordx4 v244, v[186:189], s[26:27] offset:256
	v_mul_f32_e32 v158, v186, v186
	v_mul_f32_e32 v159, v187, v187
	v_mul_f32_e32 v250, v188, v188
	v_mul_f32_e32 v251, v189, v189
	v_add_f32_e32 v158, v158, v159
	v_add_f32_e32 v250, v250, v251
	v_add_f32_e32 v161, v158, v250
	v_mul_f32_e32 v156, v186, v224
	v_mul_f32_e32 v157, v187, v225
	v_mul_f32_e32 v158, v188, v226
	v_mul_f32_e32 v159, v189, v227
	v_cvt_pk_bf16_f32 v156, v156, v157
	v_cvt_pk_bf16_f32 v157, v158, v159
	v_add_f32_e32 v190, v52, v190
	v_add_f32_e32 v191, v53, v191
	v_add_f32_e32 v192, v54, v192
	v_add_f32_e32 v193, v55, v193
	global_store_dwordx4 v244, v[190:193], s[26:27] offset:320
	v_mul_f32_e32 v158, v190, v190
	v_mul_f32_e32 v159, v191, v191
	v_mul_f32_e32 v250, v192, v192
	v_mul_f32_e32 v251, v193, v193
	v_add_f32_e32 v158, v158, v159
	v_add_f32_e32 v250, v250, v251
	v_add_f32_e32 v158, v158, v250
	v_add_f32_e32 v161, v161, v158
	v_mul_f32_e32 v158, v190, v228
	v_mul_f32_e32 v159, v191, v229
	v_mul_f32_e32 v250, v192, v230
	v_mul_f32_e32 v251, v193, v231
	v_cvt_pk_bf16_f32 v158, v158, v159
	v_cvt_pk_bf16_f32 v159, v250, v251
	s_nop 1
	v_permlane16_swap_b32_e32 v156, v158
	v_permlane16_swap_b32_e32 v157, v159
	s_add_u32 s28, s22, 0x400c00
	s_addc_u32 s29, s23, 0
	global_store_dwordx4 v254, v[156:159], s[28:29]
	v_add_f32_e32 v194, v44, v194
	v_add_f32_e32 v195, v45, v195
	v_add_f32_e32 v196, v46, v196
	v_add_f32_e32 v197, v47, v197
	global_store_dwordx4 v244, v[194:197], s[26:27] offset:384
	v_mul_f32_e32 v158, v194, v194
	v_mul_f32_e32 v159, v195, v195
	v_mul_f32_e32 v250, v196, v196
	v_mul_f32_e32 v251, v197, v197
	v_add_f32_e32 v158, v158, v159
	v_add_f32_e32 v250, v250, v251
	v_add_f32_e32 v158, v158, v250
	v_add_f32_e32 v161, v161, v158
	v_mul_f32_e32 v156, v194, v232
	v_mul_f32_e32 v157, v195, v233
	v_mul_f32_e32 v158, v196, v234
	v_mul_f32_e32 v159, v197, v235
	v_cvt_pk_bf16_f32 v156, v156, v157
	v_cvt_pk_bf16_f32 v157, v158, v159
	v_add_f32_e32 v240, v148, v240
	v_add_f32_e32 v241, v149, v241
	v_add_f32_e32 v242, v150, v242
	v_add_f32_e32 v243, v151, v243
	global_store_dwordx4 v244, v[240:243], s[26:27] offset:448
	v_mul_f32_e32 v158, v240, v240
	v_mul_f32_e32 v159, v241, v241
	v_mul_f32_e32 v250, v242, v242
	v_mul_f32_e32 v251, v243, v243
	v_add_f32_e32 v158, v158, v159
	v_add_f32_e32 v250, v250, v251
	v_add_f32_e32 v158, v158, v250
	v_add_f32_e32 v161, v161, v158
	v_mul_f32_e32 v158, v240, v236
	v_mul_f32_e32 v159, v241, v237
	v_mul_f32_e32 v250, v242, v238
	v_mul_f32_e32 v251, v243, v239
	v_cvt_pk_bf16_f32 v158, v158, v159
	v_cvt_pk_bf16_f32 v159, v250, v251
	s_nop 1
	v_permlane16_swap_b32_e32 v156, v158
	v_permlane16_swap_b32_e32 v157, v159
	s_add_u32 s28, s22, 0x600c00
	s_addc_u32 s29, s23, 0
	global_store_dwordx4 v254, v[156:159], s[28:29]
	ds_bpermute_b32 v158, v248, v161
	s_waitcnt lgkmcnt(0)
	v_add_f32_e32 v161, v161, v158
	ds_bpermute_b32 v158, v249, v161
	s_waitcnt lgkmcnt(0)
	v_add_f32_e32 v161, v161, v158
	global_store_dword v247, v161, s[30:31] offset:4
	s_add_u32 s26, s26, 0x10000
	s_addc_u32 s27, s27, 0
	s_add_u32 s30, s30, 0x400
	s_addc_u32 s31, s31, 0
	s_branch .LBB0_23

.LBB0_362:
	s_lshr_b32 s4, s20, 2
	s_and_b32 s4, s4, 24
	s_and_b32 s5, s20, 7
	s_or_b32 s4, s4, s5
	s_lshl_b32 s4, s4, 10
	v_mov_b32 v8, v198
	s_or_b32 s4, s4, s65
	v_ashrrev_i32_e32 v12, 2, v8
	v_add_u32_e32 v0, s4, v12
	s_waitcnt lgkmcnt(0)
	v_ashrrev_i32_e32 v1, 31, v0
	s_lshl_b32 s5, s20, 5
	v_lshlrev_b64 v[0:1], 6, v[0:1]
	v_lshlrev_b32_e32 v2, 4, v8
	s_and_b32 s5, s5, 0x300
	v_lshl_add_u64 v[0:1], s[92:93], 0, v[0:1]
	v_and_b32_e32 v152, 48, v2
	v_lshl_add_u64 v[14:15], v[0:1], 0, v[152:153]
	v_add_u32_e32 v0, s5, v12
	v_ashrrev_i32_e32 v1, 31, v0
	v_lshlrev_b64 v[0:1], 6, v[0:1]
	s_mov_b32 s12, 0x80000
	v_lshl_add_u64 v[0:1], s[6:7], 0, v[0:1]
	v_add_co_u32_e32 v54, vcc, s12, v14
	v_lshl_add_u64 v[0:1], v[0:1], 0, v[152:153]
	s_nop 0
	v_addc_co_u32_e32 v55, vcc, 0, v15, vcc
	s_lshl_b32 s13, s19, 13
	s_lshl_b32 s21, s20, 8
	s_and_b32 s22, s18, 7
	v_lshrrev_b32_e32 v6, 2, v8
	v_add_co_u32_e32 v2, vcc, s12, v0
	s_and_b32 s13, s13, 0x600000
	s_and_b32 s21, s21, 0x6000
	s_lshl_b32 s24, s22, 10
	v_and_b32_e32 v6, 12, v6
	s_movk_i32 s22, 0x1230
	v_addc_co_u32_e32 v3, vcc, 0, v1, vcc
	s_mov_b32 s12, 0x100000
	v_lshrrev_b32_e64 v10, v6, s22
	s_add_u32 s22, s15, s13
	v_add_co_u32_e32 v4, vcc, s12, v0
	s_addc_u32 s23, s16, 0
	s_or_b32 s13, s24, s21
	v_addc_co_u32_e32 v5, vcc, 0, v1, vcc
	s_mov_b32 s12, 0x180000
	v_and_b32_e32 v22, 3, v8
	v_ashrrev_i32_e32 v13, 31, v12
	v_xor_b32_e32 v8, v10, v8
	s_or_b32 s13, s13, s65
	v_add_co_u32_e32 v20, vcc, s12, v0
	v_lshlrev_b32_e32 v9, 6, v12
	v_lshlrev_b64 v[6:7], 13, v[12:13]
	v_lshlrev_b32_e32 v8, 4, v8
	v_add_u32_e32 v12, s13, v12
	v_addc_co_u32_e32 v21, vcc, 0, v1, vcc
	s_nop 0
	v_readfirstlane_b32 s26, v14
	v_readfirstlane_b32 s27, v15
	v_readfirstlane_b32 s28, v0
	v_readfirstlane_b32 s29, v1
	v_lshrrev_b32_e32 v250, 6, v198
	s_nop 0
	v_readfirstlane_b32 s24, v250
	s_lshl_b32 s24, s24, 10
	v_lshrrev_b32_e32 v250, 2, v200
	v_lshrrev_b32_e32 v251, 4, v200
	v_lshlrev_b32_e32 v251, 2, v251
	v_mov_b32_e32 v248, 0x1230
	v_lshrrev_b32_e32 v251, v251, v248
	v_xor_b32_e32 v251, v251, v200
	v_and_b32_e32 v251, 3, v251
	v_lshlrev_b32_e32 v251, 4, v251
	v_lshl_add_u32 v244, v250, 13, v251
	v_add_u32_e32 v245, 0x80000, v244
	v_add_u32_e32 v246, 0x100000, v244
	v_add_u32_e32 v247, 0x180000, v244
	v_lshl_add_u32 v156, v250, 6, v251
	v_add_u32_e32 v157, 0x1000, v156
	v_add_u32_e32 v158, 0x2000, v156
	v_add_u32_e32 v159, 0x3000, v156
	s_mov_b32 s25, 0
	s_add_u32 m0, s25, s24
	s_nop 0
	global_load_lds_dwordx4 v156, s[26:27]
	s_add_u32 m0, m0, 0x1000
	s_nop 0
	global_load_lds_dwordx4 v157, s[26:27]
	s_add_u32 m0, m0, 0x1000
	s_nop 0
	global_load_lds_dwordx4 v156, s[28:29]
	s_add_u32 m0, m0, 0x1000
	s_nop 0
	global_load_lds_dwordx4 v157, s[28:29]
	s_add_u32 m0, m0, 0x1000
	s_nop 0
	global_load_lds_dwordx4 v158, s[28:29]
	s_add_u32 m0, m0, 0x1000
	s_nop 0
	global_load_lds_dwordx4 v159, s[28:29]
	s_add_u32 s26, s26, 0x200000
	s_addc_u32 s27, s27, 0
	s_add_u32 s28, s28, 0x10000
	s_addc_u32 s29, s29, 0
	s_add_u32 s25, s25, 24576
	s_cmp_eq_u32 s25, 73728
	s_cselect_b32 s25, 0, s25
	s_add_u32 m0, s25, s24
	s_nop 0
	global_load_lds_dwordx4 v156, s[26:27]
	s_add_u32 m0, m0, 0x1000
	s_nop 0
	global_load_lds_dwordx4 v157, s[26:27]
	s_add_u32 m0, m0, 0x1000
	s_nop 0
	global_load_lds_dwordx4 v156, s[28:29]
	s_add_u32 m0, m0, 0x1000
	s_nop 0
	global_load_lds_dwordx4 v157, s[28:29]
	s_add_u32 m0, m0, 0x1000
	s_nop 0
	global_load_lds_dwordx4 v158, s[28:29]
	s_add_u32 m0, m0, 0x1000
	s_nop 0
	global_load_lds_dwordx4 v159, s[28:29]
	s_add_u32 s26, s26, 0x200000
	s_addc_u32 s27, s27, 0
	s_add_u32 s28, s28, 0x10000
	s_addc_u32 s29, s29, 0
	s_add_u32 s25, s25, 24576
	s_cmp_eq_u32 s25, 73728
	s_cselect_b32 s25, 0, s25
	s_add_u32 m0, s25, s24
	s_nop 0
	global_load_lds_dwordx4 v156, s[26:27]
	s_add_u32 m0, m0, 0x1000
	s_nop 0
	global_load_lds_dwordx4 v157, s[26:27]
	s_add_u32 m0, m0, 0x1000
	s_nop 0
	global_load_lds_dwordx4 v156, s[28:29]
	s_add_u32 m0, m0, 0x1000
	s_nop 0
	global_load_lds_dwordx4 v157, s[28:29]
	s_add_u32 m0, m0, 0x1000
	s_nop 0
	global_load_lds_dwordx4 v158, s[28:29]
	s_add_u32 m0, m0, 0x1000
	s_nop 0
	global_load_lds_dwordx4 v159, s[28:29]
	s_add_u32 s26, s26, 0x200000
	s_addc_u32 s27, s27, 0
	s_add_u32 s28, s28, 0x10000
	s_addc_u32 s29, s29, 0
	s_add_u32 s25, s25, 24576
	s_cmp_eq_u32 s25, 73728
	s_cselect_b32 s25, 0, s25
	v_mov_b32_e32 v24, 0
	v_mov_b32_e32 v25, v24
	v_mov_b32_e32 v26, v24
	v_mov_b32_e32 v27, v24
	v_mov_b32_e32 v28, v24
	v_mov_b32_e32 v29, v24
	v_mov_b32_e32 v54, v24
	v_mov_b32_e32 v55, v24
	v_mov_b32_e32 v56, v24
	v_mov_b32_e32 v57, v24
	v_mov_b32_e32 v58, v24
	v_mov_b32_e32 v59, v24
	v_mov_b32_e32 v64, v24
	v_mov_b32_e32 v65, v24
	v_mov_b32_e32 v66, v24
	v_mov_b32_e32 v67, v24
	v_mov_b32_e32 v68, v24
	v_mov_b32_e32 v69, v24
	v_mov_b32_e32 v70, v24
	v_mov_b32_e32 v71, v24
	v_mov_b32_e32 v60, v24
	v_mov_b32_e32 v61, v24
	v_mov_b32_e32 v62, v24
	v_mov_b32_e32 v63, v24
	v_mov_b32_e32 v100, v24
	v_mov_b32_e32 v30, v24
	v_mov_b32_e32 v31, v24
	v_mov_b32_e32 v32, v24
	v_mov_b32_e32 v33, v24
	v_mov_b32_e32 v34, v24
	v_mov_b32_e32 v35, v24
	v_mov_b32_e32 v36, v24
	v_mov_b32_e32 v37, v24
	v_mov_b32_e32 v38, v24
	v_mov_b32_e32 v39, v24
	v_mov_b32_e32 v52, v24
	v_mov_b32_e32 v53, v24
	v_mov_b32_e32 v40, v24
	v_mov_b32_e32 v41, v24
	v_mov_b32_e32 v42, v24
	v_mov_b32_e32 v43, v24
	v_mov_b32_e32 v44, v24
	v_mov_b32_e32 v45, v24
	v_mov_b32_e32 v46, v24
	v_mov_b32_e32 v47, v24
	v_mov_b32_e32 v48, v24
	v_mov_b32_e32 v49, v24
	v_mov_b32_e32 v50, v24
	v_mov_b32_e32 v51, v24
	v_mov_b32_e32 v101, v24
	v_mov_b32_e32 v102, v24
	v_mov_b32_e32 v103, v24
	v_mov_b32_e32 v104, v24
	v_mov_b32_e32 v105, v24
	v_mov_b32_e32 v106, v24
	v_mov_b32_e32 v107, v24
	v_mov_b32_e32 v120, v24
	v_mov_b32_e32 v121, v24
	v_mov_b32_e32 v122, v24
	v_mov_b32_e32 v123, v24
	v_mov_b32_e32 v128, v24
	v_mov_b32_e32 v129, v24
	v_mov_b32_e32 v130, v24
	v_mov_b32_e32 v131, v24
	v_mov_b32_e32 v108, v24
	v_mov_b32_e32 v109, v24
	v_mov_b32_e32 v110, v24
	v_mov_b32_e32 v111, v24
	v_mov_b32_e32 v112, v24
	v_mov_b32_e32 v113, v24
	v_mov_b32_e32 v114, v24
	v_mov_b32_e32 v115, v24
	v_mov_b32_e32 v116, v24
	v_mov_b32_e32 v117, v24
	v_mov_b32_e32 v118, v24
	v_mov_b32_e32 v119, v24
	v_mov_b32_e32 v124, v24
	v_mov_b32_e32 v125, v24
	v_mov_b32_e32 v126, v24
	v_mov_b32_e32 v127, v24
	v_mov_b32_e32 v80, v24
	v_mov_b32_e32 v81, v24
	v_mov_b32_e32 v82, v24
	v_mov_b32_e32 v83, v24
	v_mov_b32_e32 v84, v24
	v_mov_b32_e32 v85, v24
	v_mov_b32_e32 v86, v24
	v_mov_b32_e32 v87, v24
	v_mov_b32_e32 v96, v24
	v_mov_b32_e32 v97, v24
	v_mov_b32_e32 v98, v24
	v_mov_b32_e32 v99, v24
	v_mov_b32_e32 v72, v24
	v_mov_b32_e32 v73, v24
	v_mov_b32_e32 v74, v24
	v_mov_b32_e32 v75, v24
	v_mov_b32_e32 v132, v24
	v_mov_b32_e32 v133, v24
	v_mov_b32_e32 v134, v24
	v_mov_b32_e32 v135, v24
	v_mov_b32_e32 v136, v24
	v_mov_b32_e32 v137, v24
	v_mov_b32_e32 v138, v24
	v_mov_b32_e32 v139, v24
	v_mov_b32_e32 v140, v24
	v_mov_b32_e32 v141, v24
	v_mov_b32_e32 v142, v24
	v_mov_b32_e32 v143, v24
	v_mov_b32_e32 v144, v24
	v_mov_b32_e32 v145, v24
	v_mov_b32_e32 v146, v24
	v_mov_b32_e32 v147, v24
	v_mov_b32_e32 v92, v24
	v_mov_b32_e32 v93, v24
	v_mov_b32_e32 v94, v24
	v_mov_b32_e32 v95, v24
	v_mov_b32_e32 v88, v24
	v_mov_b32_e32 v89, v24
	v_mov_b32_e32 v90, v24
	v_mov_b32_e32 v91, v24
	v_mov_b32_e32 v76, v24
	v_mov_b32_e32 v77, v24
	v_mov_b32_e32 v78, v24
	v_mov_b32_e32 v79, v24
	v_mov_b32_e32 v148, v24
	v_mov_b32_e32 v149, v24
	v_mov_b32_e32 v150, v24
	v_mov_b32_e32 v151, v24
	s_waitcnt vmcnt(12)
	s_barrier
	s_mov_b32 s30, 0
	v_add_u32_e32 v248, s30, v155
	v_add_u32_e32 v249, s30, v160
	ds_read_b128 v[186:189], v248
	ds_read_b128 v[212:215], v249 offset:8192
	ds_read_b128 v[190:193], v248 offset:1024
	ds_read_b128 v[216:219], v249 offset:9216
	ds_read_b128 v[194:197], v248 offset:2048
	ds_read_b128 v[220:223], v249 offset:10240
	ds_read_b128 v[208:211], v248 offset:3072
	ds_read_b128 v[224:227], v249 offset:11264
	ds_read_b128 v[228:231], v249 offset:12288
	ds_read_b128 v[232:235], v249 offset:13312
	ds_read_b128 v[236:239], v249 offset:14336
	ds_read_b128 v[240:243], v249 offset:15360
	s_add_u32 s30, s30, 24576
	s_cmp_eq_u32 s30, 73728
	s_cselect_b32 s30, 0, s30
	s_waitcnt lgkmcnt(0)
	s_mov_b32 s31, 62
.Lgm2_loop:
	v_mfma_f32_16x16x32_bf16 v[128:131], v[212:215], v[186:189], v[128:131]
	v_mfma_f32_16x16x32_bf16 v[68:71], v[212:215], v[190:193], v[68:71]
	v_mfma_f32_16x16x32_bf16 v[108:111], v[212:215], v[194:197], v[108:111]
	v_mfma_f32_16x16x32_bf16 v[132:135], v[212:215], v[208:211], v[132:135]
	v_mfma_f32_16x16x32_bf16 v[120:123], v[216:219], v[186:189], v[120:123]
	v_mfma_f32_16x16x32_bf16 v[64:67], v[216:219], v[190:193], v[64:67]
	v_mfma_f32_16x16x32_bf16 v[112:115], v[216:219], v[194:197], v[112:115]
	v_mfma_f32_16x16x32_bf16 v[136:139], v[216:219], v[208:211], v[136:139]
	v_mfma_f32_16x16x32_bf16 v[104:107], v[220:223], v[186:189], v[104:107]
	v_mfma_f32_16x16x32_bf16 v[56:59], v[220:223], v[190:193], v[56:59]
	v_mfma_f32_16x16x32_bf16 v[116:119], v[220:223], v[194:197], v[116:119]
	v_mfma_f32_16x16x32_bf16 v[140:143], v[220:223], v[208:211], v[140:143]
	v_mfma_f32_16x16x32_bf16 v[100:103], v[224:227], v[186:189], v[100:103]
	v_mfma_f32_16x16x32_bf16 v[52:55], v[224:227], v[190:193], v[52:55]
	v_mfma_f32_16x16x32_bf16 v[124:127], v[224:227], v[194:197], v[124:127]
	v_mfma_f32_16x16x32_bf16 v[144:147], v[224:227], v[208:211], v[144:147]
	s_waitcnt vmcnt(6)
	s_barrier
	v_add_u32_e32 v248, s30, v155
	v_add_u32_e32 v249, s30, v160
	v_mfma_f32_16x16x32_bf16 v[60:63], v[228:231], v[186:189], v[60:63]
	ds_read_b128 v[0:3], v248
	s_add_u32 m0, s25, s24
	v_mfma_f32_16x16x32_bf16 v[36:39], v[228:231], v[190:193], v[36:39]
	ds_read_b128 v[16:19], v249 offset:8192
	global_load_lds_dwordx4 v156, s[26:27]
	v_mfma_f32_16x16x32_bf16 v[80:83], v[228:231], v[194:197], v[80:83]
	ds_read_b128 v[4:7], v248 offset:1024
	s_add_u32 m0, m0, 0x1000
	v_mfma_f32_16x16x32_bf16 v[92:95], v[228:231], v[208:211], v[92:95]
	ds_read_b128 v[20:23], v249 offset:9216
	global_load_lds_dwordx4 v157, s[26:27]
	v_mfma_f32_16x16x32_bf16 v[48:51], v[232:235], v[186:189], v[48:51]
	ds_read_b128 v[8:11], v248 offset:2048
	s_add_u32 m0, m0, 0x1000
	v_mfma_f32_16x16x32_bf16 v[32:35], v[232:235], v[190:193], v[32:35]
	ds_read_b128 v[162:165], v249 offset:10240
	global_load_lds_dwordx4 v156, s[28:29]
	v_mfma_f32_16x16x32_bf16 v[84:87], v[232:235], v[194:197], v[84:87]
	ds_read_b128 v[12:15], v248 offset:3072
	s_add_u32 m0, m0, 0x1000
	v_mfma_f32_16x16x32_bf16 v[88:91], v[232:235], v[208:211], v[88:91]
	ds_read_b128 v[166:169], v249 offset:11264
	global_load_lds_dwordx4 v157, s[28:29]
	v_mfma_f32_16x16x32_bf16 v[44:47], v[236:239], v[186:189], v[44:47]
	ds_read_b128 v[170:173], v249 offset:12288
	s_add_u32 m0, m0, 0x1000
	v_mfma_f32_16x16x32_bf16 v[28:31], v[236:239], v[190:193], v[28:31]
	ds_read_b128 v[174:177], v249 offset:13312
	global_load_lds_dwordx4 v158, s[28:29]
	v_mfma_f32_16x16x32_bf16 v[96:99], v[236:239], v[194:197], v[96:99]
	ds_read_b128 v[178:181], v249 offset:14336
	s_add_u32 m0, m0, 0x1000
	v_mfma_f32_16x16x32_bf16 v[76:79], v[236:239], v[208:211], v[76:79]
	ds_read_b128 v[182:185], v249 offset:15360
	global_load_lds_dwordx4 v159, s[28:29]
	v_mfma_f32_16x16x32_bf16 v[40:43], v[240:243], v[186:189], v[40:43]
	v_mfma_f32_16x16x32_bf16 v[24:27], v[240:243], v[190:193], v[24:27]
	v_mfma_f32_16x16x32_bf16 v[72:75], v[240:243], v[194:197], v[72:75]
	v_mfma_f32_16x16x32_bf16 v[148:151], v[240:243], v[208:211], v[148:151]
	s_add_u32 s26, s26, 0x200000
	s_addc_u32 s27, s27, 0
	s_add_u32 s28, s28, 0x10000
	s_addc_u32 s29, s29, 0
	s_add_u32 s25, s25, 24576
	s_cmp_eq_u32 s25, 73728
	s_cselect_b32 s25, 0, s25
	s_add_u32 s30, s30, 24576
	s_cmp_eq_u32 s30, 73728
	s_cselect_b32 s30, 0, s30
	s_waitcnt lgkmcnt(0)
	v_mfma_f32_16x16x32_bf16 v[128:131], v[16:19], v[0:3], v[128:131]
	v_mfma_f32_16x16x32_bf16 v[68:71], v[16:19], v[4:7], v[68:71]
	v_mfma_f32_16x16x32_bf16 v[108:111], v[16:19], v[8:11], v[108:111]
	v_mfma_f32_16x16x32_bf16 v[132:135], v[16:19], v[12:15], v[132:135]
	v_mfma_f32_16x16x32_bf16 v[120:123], v[20:23], v[0:3], v[120:123]
	v_mfma_f32_16x16x32_bf16 v[64:67], v[20:23], v[4:7], v[64:67]
	v_mfma_f32_16x16x32_bf16 v[112:115], v[20:23], v[8:11], v[112:115]
	v_mfma_f32_16x16x32_bf16 v[136:139], v[20:23], v[12:15], v[136:139]
	v_mfma_f32_16x16x32_bf16 v[104:107], v[162:165], v[0:3], v[104:107]
	v_mfma_f32_16x16x32_bf16 v[56:59], v[162:165], v[4:7], v[56:59]
	v_mfma_f32_16x16x32_bf16 v[116:119], v[162:165], v[8:11], v[116:119]
	v_mfma_f32_16x16x32_bf16 v[140:143], v[162:165], v[12:15], v[140:143]
	v_mfma_f32_16x16x32_bf16 v[100:103], v[166:169], v[0:3], v[100:103]
	v_mfma_f32_16x16x32_bf16 v[52:55], v[166:169], v[4:7], v[52:55]
	v_mfma_f32_16x16x32_bf16 v[124:127], v[166:169], v[8:11], v[124:127]
	v_mfma_f32_16x16x32_bf16 v[144:147], v[166:169], v[12:15], v[144:147]
	s_waitcnt vmcnt(6)
	s_barrier
	v_add_u32_e32 v248, s30, v155
	v_add_u32_e32 v249, s30, v160
	v_mfma_f32_16x16x32_bf16 v[60:63], v[170:173], v[0:3], v[60:63]
	ds_read_b128 v[186:189], v248
	s_add_u32 m0, s25, s24
	v_mfma_f32_16x16x32_bf16 v[36:39], v[170:173], v[4:7], v[36:39]
	ds_read_b128 v[212:215], v249 offset:8192
	global_load_lds_dwordx4 v156, s[26:27]
	v_mfma_f32_16x16x32_bf16 v[80:83], v[170:173], v[8:11], v[80:83]
	ds_read_b128 v[190:193], v248 offset:1024
	s_add_u32 m0, m0, 0x1000
	v_mfma_f32_16x16x32_bf16 v[92:95], v[170:173], v[12:15], v[92:95]
	ds_read_b128 v[216:219], v249 offset:9216
	global_load_lds_dwordx4 v157, s[26:27]
	v_mfma_f32_16x16x32_bf16 v[48:51], v[174:177], v[0:3], v[48:51]
	ds_read_b128 v[194:197], v248 offset:2048
	s_add_u32 m0, m0, 0x1000
	v_mfma_f32_16x16x32_bf16 v[32:35], v[174:177], v[4:7], v[32:35]
	ds_read_b128 v[220:223], v249 offset:10240
	global_load_lds_dwordx4 v156, s[28:29]
	v_mfma_f32_16x16x32_bf16 v[84:87], v[174:177], v[8:11], v[84:87]
	ds_read_b128 v[208:211], v248 offset:3072
	s_add_u32 m0, m0, 0x1000
	v_mfma_f32_16x16x32_bf16 v[88:91], v[174:177], v[12:15], v[88:91]
	ds_read_b128 v[224:227], v249 offset:11264
	global_load_lds_dwordx4 v157, s[28:29]
	v_mfma_f32_16x16x32_bf16 v[44:47], v[178:181], v[0:3], v[44:47]
	ds_read_b128 v[228:231], v249 offset:12288
	s_add_u32 m0, m0, 0x1000
	v_mfma_f32_16x16x32_bf16 v[28:31], v[178:181], v[4:7], v[28:31]
	ds_read_b128 v[232:235], v249 offset:13312
	global_load_lds_dwordx4 v158, s[28:29]
	v_mfma_f32_16x16x32_bf16 v[96:99], v[178:181], v[8:11], v[96:99]
	ds_read_b128 v[236:239], v249 offset:14336
	s_add_u32 m0, m0, 0x1000
	v_mfma_f32_16x16x32_bf16 v[76:79], v[178:181], v[12:15], v[76:79]
	ds_read_b128 v[240:243], v249 offset:15360
	global_load_lds_dwordx4 v159, s[28:29]
	v_mfma_f32_16x16x32_bf16 v[40:43], v[182:185], v[0:3], v[40:43]
	v_mfma_f32_16x16x32_bf16 v[24:27], v[182:185], v[4:7], v[24:27]
	v_mfma_f32_16x16x32_bf16 v[72:75], v[182:185], v[8:11], v[72:75]
	v_mfma_f32_16x16x32_bf16 v[148:151], v[182:185], v[12:15], v[148:151]
	s_add_u32 s26, s26, 0x200000
	s_addc_u32 s27, s27, 0
	s_add_u32 s28, s28, 0x10000
	s_addc_u32 s29, s29, 0
	s_add_u32 s25, s25, 24576
	s_cmp_eq_u32 s25, 73728
	s_cselect_b32 s25, 0, s25
	s_add_u32 s30, s30, 24576
	s_cmp_eq_u32 s30, 73728
	s_cselect_b32 s30, 0, s30
	s_waitcnt lgkmcnt(0)
	s_sub_u32 s31, s31, 1
	s_cmp_lg_u32 s31, 0
	s_cbranch_scc1 .Lgm2_loop
	v_mfma_f32_16x16x32_bf16 v[128:131], v[212:215], v[186:189], v[128:131]
	v_mfma_f32_16x16x32_bf16 v[68:71], v[212:215], v[190:193], v[68:71]
	v_mfma_f32_16x16x32_bf16 v[108:111], v[212:215], v[194:197], v[108:111]
	v_mfma_f32_16x16x32_bf16 v[132:135], v[212:215], v[208:211], v[132:135]
	v_mfma_f32_16x16x32_bf16 v[120:123], v[216:219], v[186:189], v[120:123]
	v_mfma_f32_16x16x32_bf16 v[64:67], v[216:219], v[190:193], v[64:67]
	v_mfma_f32_16x16x32_bf16 v[112:115], v[216:219], v[194:197], v[112:115]
	v_mfma_f32_16x16x32_bf16 v[136:139], v[216:219], v[208:211], v[136:139]
	v_mfma_f32_16x16x32_bf16 v[104:107], v[220:223], v[186:189], v[104:107]
	v_mfma_f32_16x16x32_bf16 v[56:59], v[220:223], v[190:193], v[56:59]
	v_mfma_f32_16x16x32_bf16 v[116:119], v[220:223], v[194:197], v[116:119]
	v_mfma_f32_16x16x32_bf16 v[140:143], v[220:223], v[208:211], v[140:143]
	v_mfma_f32_16x16x32_bf16 v[100:103], v[224:227], v[186:189], v[100:103]
	v_mfma_f32_16x16x32_bf16 v[52:55], v[224:227], v[190:193], v[52:55]
	v_mfma_f32_16x16x32_bf16 v[124:127], v[224:227], v[194:197], v[124:127]
	v_mfma_f32_16x16x32_bf16 v[144:147], v[224:227], v[208:211], v[144:147]
	s_waitcnt vmcnt(6)
	s_barrier
	v_add_u32_e32 v248, s30, v155
	v_add_u32_e32 v249, s30, v160
	v_mfma_f32_16x16x32_bf16 v[60:63], v[228:231], v[186:189], v[60:63]
	ds_read_b128 v[0:3], v248
	s_add_u32 m0, s25, s24
	v_mfma_f32_16x16x32_bf16 v[36:39], v[228:231], v[190:193], v[36:39]
	ds_read_b128 v[16:19], v249 offset:8192
	global_load_lds_dwordx4 v156, s[26:27]
	v_mfma_f32_16x16x32_bf16 v[80:83], v[228:231], v[194:197], v[80:83]
	ds_read_b128 v[4:7], v248 offset:1024
	s_add_u32 m0, m0, 0x1000
	v_mfma_f32_16x16x32_bf16 v[92:95], v[228:231], v[208:211], v[92:95]
	ds_read_b128 v[20:23], v249 offset:9216
	global_load_lds_dwordx4 v157, s[26:27]
	v_mfma_f32_16x16x32_bf16 v[48:51], v[232:235], v[186:189], v[48:51]
	ds_read_b128 v[8:11], v248 offset:2048
	s_add_u32 m0, m0, 0x1000
	v_mfma_f32_16x16x32_bf16 v[32:35], v[232:235], v[190:193], v[32:35]
	ds_read_b128 v[162:165], v249 offset:10240
	global_load_lds_dwordx4 v156, s[28:29]
	v_mfma_f32_16x16x32_bf16 v[84:87], v[232:235], v[194:197], v[84:87]
	ds_read_b128 v[12:15], v248 offset:3072
	s_add_u32 m0, m0, 0x1000
	v_mfma_f32_16x16x32_bf16 v[88:91], v[232:235], v[208:211], v[88:91]
	ds_read_b128 v[166:169], v249 offset:11264
	global_load_lds_dwordx4 v157, s[28:29]
	v_mfma_f32_16x16x32_bf16 v[44:47], v[236:239], v[186:189], v[44:47]
	ds_read_b128 v[170:173], v249 offset:12288
	s_add_u32 m0, m0, 0x1000
	v_mfma_f32_16x16x32_bf16 v[28:31], v[236:239], v[190:193], v[28:31]
	ds_read_b128 v[174:177], v249 offset:13312
	global_load_lds_dwordx4 v158, s[28:29]
	v_mfma_f32_16x16x32_bf16 v[96:99], v[236:239], v[194:197], v[96:99]
	ds_read_b128 v[178:181], v249 offset:14336
	s_add_u32 m0, m0, 0x1000
	v_mfma_f32_16x16x32_bf16 v[76:79], v[236:239], v[208:211], v[76:79]
	ds_read_b128 v[182:185], v249 offset:15360
	global_load_lds_dwordx4 v159, s[28:29]
	v_mfma_f32_16x16x32_bf16 v[40:43], v[240:243], v[186:189], v[40:43]
	v_mfma_f32_16x16x32_bf16 v[24:27], v[240:243], v[190:193], v[24:27]
	v_mfma_f32_16x16x32_bf16 v[72:75], v[240:243], v[194:197], v[72:75]
	v_mfma_f32_16x16x32_bf16 v[148:151], v[240:243], v[208:211], v[148:151]
	s_add_u32 s26, s26, 0x200000
	s_addc_u32 s27, s27, 0
	s_add_u32 s28, s28, 0x10000
	s_addc_u32 s29, s29, 0
	s_add_u32 s25, s25, 24576
	s_cmp_eq_u32 s25, 73728
	s_cselect_b32 s25, 0, s25
	s_add_u32 s30, s30, 24576
	s_cmp_eq_u32 s30, 73728
	s_cselect_b32 s30, 0, s30
	s_waitcnt lgkmcnt(0)
	v_mfma_f32_16x16x32_bf16 v[128:131], v[16:19], v[0:3], v[128:131]
	v_mfma_f32_16x16x32_bf16 v[68:71], v[16:19], v[4:7], v[68:71]
	v_mfma_f32_16x16x32_bf16 v[108:111], v[16:19], v[8:11], v[108:111]
	v_mfma_f32_16x16x32_bf16 v[132:135], v[16:19], v[12:15], v[132:135]
	v_mfma_f32_16x16x32_bf16 v[120:123], v[20:23], v[0:3], v[120:123]
	v_mfma_f32_16x16x32_bf16 v[64:67], v[20:23], v[4:7], v[64:67]
	v_mfma_f32_16x16x32_bf16 v[112:115], v[20:23], v[8:11], v[112:115]
	v_mfma_f32_16x16x32_bf16 v[136:139], v[20:23], v[12:15], v[136:139]
	v_mfma_f32_16x16x32_bf16 v[104:107], v[162:165], v[0:3], v[104:107]
	v_mfma_f32_16x16x32_bf16 v[56:59], v[162:165], v[4:7], v[56:59]
	v_mfma_f32_16x16x32_bf16 v[116:119], v[162:165], v[8:11], v[116:119]
	v_mfma_f32_16x16x32_bf16 v[140:143], v[162:165], v[12:15], v[140:143]
	v_mfma_f32_16x16x32_bf16 v[100:103], v[166:169], v[0:3], v[100:103]
	v_mfma_f32_16x16x32_bf16 v[52:55], v[166:169], v[4:7], v[52:55]
	v_mfma_f32_16x16x32_bf16 v[124:127], v[166:169], v[8:11], v[124:127]
	v_mfma_f32_16x16x32_bf16 v[144:147], v[166:169], v[12:15], v[144:147]
	s_waitcnt vmcnt(6)
	s_barrier
	v_add_u32_e32 v248, s30, v155
	v_add_u32_e32 v249, s30, v160
	v_mfma_f32_16x16x32_bf16 v[60:63], v[170:173], v[0:3], v[60:63]
	ds_read_b128 v[186:189], v248
	v_mfma_f32_16x16x32_bf16 v[36:39], v[170:173], v[4:7], v[36:39]
	ds_read_b128 v[212:215], v249 offset:8192
	v_mfma_f32_16x16x32_bf16 v[80:83], v[170:173], v[8:11], v[80:83]
	ds_read_b128 v[190:193], v248 offset:1024
	v_mfma_f32_16x16x32_bf16 v[92:95], v[170:173], v[12:15], v[92:95]
	ds_read_b128 v[216:219], v249 offset:9216
	v_mfma_f32_16x16x32_bf16 v[48:51], v[174:177], v[0:3], v[48:51]
	ds_read_b128 v[194:197], v248 offset:2048
	v_mfma_f32_16x16x32_bf16 v[32:35], v[174:177], v[4:7], v[32:35]
	ds_read_b128 v[220:223], v249 offset:10240
	v_mfma_f32_16x16x32_bf16 v[84:87], v[174:177], v[8:11], v[84:87]
	ds_read_b128 v[208:211], v248 offset:3072
	v_mfma_f32_16x16x32_bf16 v[88:91], v[174:177], v[12:15], v[88:91]
	ds_read_b128 v[224:227], v249 offset:11264
	v_mfma_f32_16x16x32_bf16 v[44:47], v[178:181], v[0:3], v[44:47]
	ds_read_b128 v[228:231], v249 offset:12288
	v_mfma_f32_16x16x32_bf16 v[28:31], v[178:181], v[4:7], v[28:31]
	ds_read_b128 v[232:235], v249 offset:13312
	v_mfma_f32_16x16x32_bf16 v[96:99], v[178:181], v[8:11], v[96:99]
	ds_read_b128 v[236:239], v249 offset:14336
	v_mfma_f32_16x16x32_bf16 v[76:79], v[178:181], v[12:15], v[76:79]
	ds_read_b128 v[240:243], v249 offset:15360
	v_mfma_f32_16x16x32_bf16 v[40:43], v[182:185], v[0:3], v[40:43]
	v_mfma_f32_16x16x32_bf16 v[24:27], v[182:185], v[4:7], v[24:27]
	v_mfma_f32_16x16x32_bf16 v[72:75], v[182:185], v[8:11], v[72:75]
	v_mfma_f32_16x16x32_bf16 v[148:151], v[182:185], v[12:15], v[148:151]
	s_add_u32 s30, s30, 24576
	s_cmp_eq_u32 s30, 73728
	s_cselect_b32 s30, 0, s30
	s_waitcnt lgkmcnt(0)
	v_mfma_f32_16x16x32_bf16 v[128:131], v[212:215], v[186:189], v[128:131]
	v_mfma_f32_16x16x32_bf16 v[68:71], v[212:215], v[190:193], v[68:71]
	v_mfma_f32_16x16x32_bf16 v[108:111], v[212:215], v[194:197], v[108:111]
	v_mfma_f32_16x16x32_bf16 v[132:135], v[212:215], v[208:211], v[132:135]
	v_mfma_f32_16x16x32_bf16 v[120:123], v[216:219], v[186:189], v[120:123]
	v_mfma_f32_16x16x32_bf16 v[64:67], v[216:219], v[190:193], v[64:67]
	v_mfma_f32_16x16x32_bf16 v[112:115], v[216:219], v[194:197], v[112:115]
	v_mfma_f32_16x16x32_bf16 v[136:139], v[216:219], v[208:211], v[136:139]
	v_mfma_f32_16x16x32_bf16 v[104:107], v[220:223], v[186:189], v[104:107]
	v_mfma_f32_16x16x32_bf16 v[56:59], v[220:223], v[190:193], v[56:59]
	v_mfma_f32_16x16x32_bf16 v[116:119], v[220:223], v[194:197], v[116:119]
	v_mfma_f32_16x16x32_bf16 v[140:143], v[220:223], v[208:211], v[140:143]
	v_mfma_f32_16x16x32_bf16 v[100:103], v[224:227], v[186:189], v[100:103]
	v_mfma_f32_16x16x32_bf16 v[52:55], v[224:227], v[190:193], v[52:55]
	v_mfma_f32_16x16x32_bf16 v[124:127], v[224:227], v[194:197], v[124:127]
	v_mfma_f32_16x16x32_bf16 v[144:147], v[224:227], v[208:211], v[144:147]
	s_waitcnt vmcnt(0)
	s_barrier
	v_add_u32_e32 v248, s30, v155
	v_add_u32_e32 v249, s30, v160
	v_mfma_f32_16x16x32_bf16 v[60:63], v[228:231], v[186:189], v[60:63]
	ds_read_b128 v[0:3], v248
	v_mfma_f32_16x16x32_bf16 v[36:39], v[228:231], v[190:193], v[36:39]
	ds_read_b128 v[16:19], v249 offset:8192
	v_mfma_f32_16x16x32_bf16 v[80:83], v[228:231], v[194:197], v[80:83]
	ds_read_b128 v[4:7], v248 offset:1024
	v_mfma_f32_16x16x32_bf16 v[92:95], v[228:231], v[208:211], v[92:95]
	ds_read_b128 v[20:23], v249 offset:9216
	v_mfma_f32_16x16x32_bf16 v[48:51], v[232:235], v[186:189], v[48:51]
	ds_read_b128 v[8:11], v248 offset:2048
	v_mfma_f32_16x16x32_bf16 v[32:35], v[232:235], v[190:193], v[32:35]
	ds_read_b128 v[162:165], v249 offset:10240
	v_mfma_f32_16x16x32_bf16 v[84:87], v[232:235], v[194:197], v[84:87]
	ds_read_b128 v[12:15], v248 offset:3072
	v_mfma_f32_16x16x32_bf16 v[88:91], v[232:235], v[208:211], v[88:91]
	ds_read_b128 v[166:169], v249 offset:11264
	v_mfma_f32_16x16x32_bf16 v[44:47], v[236:239], v[186:189], v[44:47]
	ds_read_b128 v[170:173], v249 offset:12288
	v_mfma_f32_16x16x32_bf16 v[28:31], v[236:239], v[190:193], v[28:31]
	ds_read_b128 v[174:177], v249 offset:13312
	v_mfma_f32_16x16x32_bf16 v[96:99], v[236:239], v[194:197], v[96:99]
	ds_read_b128 v[178:181], v249 offset:14336
	v_mfma_f32_16x16x32_bf16 v[76:79], v[236:239], v[208:211], v[76:79]
	ds_read_b128 v[182:185], v249 offset:15360
	v_mfma_f32_16x16x32_bf16 v[40:43], v[240:243], v[186:189], v[40:43]
	v_mfma_f32_16x16x32_bf16 v[24:27], v[240:243], v[190:193], v[24:27]
	v_mfma_f32_16x16x32_bf16 v[72:75], v[240:243], v[194:197], v[72:75]
	v_mfma_f32_16x16x32_bf16 v[148:151], v[240:243], v[208:211], v[148:151]
	s_add_u32 s30, s30, 24576
	s_cmp_eq_u32 s30, 73728
	s_cselect_b32 s30, 0, s30
	s_waitcnt lgkmcnt(0)
	v_mfma_f32_16x16x32_bf16 v[128:131], v[16:19], v[0:3], v[128:131]
	v_mfma_f32_16x16x32_bf16 v[68:71], v[16:19], v[4:7], v[68:71]
	v_mfma_f32_16x16x32_bf16 v[108:111], v[16:19], v[8:11], v[108:111]
	v_mfma_f32_16x16x32_bf16 v[132:135], v[16:19], v[12:15], v[132:135]
	v_mfma_f32_16x16x32_bf16 v[120:123], v[20:23], v[0:3], v[120:123]
	v_mfma_f32_16x16x32_bf16 v[64:67], v[20:23], v[4:7], v[64:67]
	v_mfma_f32_16x16x32_bf16 v[112:115], v[20:23], v[8:11], v[112:115]
	v_mfma_f32_16x16x32_bf16 v[136:139], v[20:23], v[12:15], v[136:139]
	v_mfma_f32_16x16x32_bf16 v[104:107], v[162:165], v[0:3], v[104:107]
	v_mfma_f32_16x16x32_bf16 v[56:59], v[162:165], v[4:7], v[56:59]
	v_mfma_f32_16x16x32_bf16 v[116:119], v[162:165], v[8:11], v[116:119]
	v_mfma_f32_16x16x32_bf16 v[140:143], v[162:165], v[12:15], v[140:143]
	v_mfma_f32_16x16x32_bf16 v[100:103], v[166:169], v[0:3], v[100:103]
	v_mfma_f32_16x16x32_bf16 v[52:55], v[166:169], v[4:7], v[52:55]
	v_mfma_f32_16x16x32_bf16 v[124:127], v[166:169], v[8:11], v[124:127]
	v_mfma_f32_16x16x32_bf16 v[144:147], v[166:169], v[12:15], v[144:147]
	v_mfma_f32_16x16x32_bf16 v[60:63], v[170:173], v[0:3], v[60:63]
	v_mfma_f32_16x16x32_bf16 v[36:39], v[170:173], v[4:7], v[36:39]
	v_mfma_f32_16x16x32_bf16 v[80:83], v[170:173], v[8:11], v[80:83]
	v_mfma_f32_16x16x32_bf16 v[92:95], v[170:173], v[12:15], v[92:95]
	v_mfma_f32_16x16x32_bf16 v[48:51], v[174:177], v[0:3], v[48:51]
	v_mfma_f32_16x16x32_bf16 v[32:35], v[174:177], v[4:7], v[32:35]
	v_mfma_f32_16x16x32_bf16 v[84:87], v[174:177], v[8:11], v[84:87]
	v_mfma_f32_16x16x32_bf16 v[88:91], v[174:177], v[12:15], v[88:91]
	v_mfma_f32_16x16x32_bf16 v[44:47], v[178:181], v[0:3], v[44:47]
	v_mfma_f32_16x16x32_bf16 v[28:31], v[178:181], v[4:7], v[28:31]
	v_mfma_f32_16x16x32_bf16 v[96:99], v[178:181], v[8:11], v[96:99]
	v_mfma_f32_16x16x32_bf16 v[76:79], v[178:181], v[12:15], v[76:79]
	v_mfma_f32_16x16x32_bf16 v[40:43], v[182:185], v[0:3], v[40:43]
	v_mfma_f32_16x16x32_bf16 v[24:27], v[182:185], v[4:7], v[24:27]
	v_mfma_f32_16x16x32_bf16 v[72:75], v[182:185], v[8:11], v[72:75]
	v_mfma_f32_16x16x32_bf16 v[148:151], v[182:185], v[12:15], v[148:151]
	v_mov_b32 v250, v198
	s_nop 0
	v_and_b32_e32 v251, 15, v250
	v_bfe_u32 v156, v250, 4, 2
	v_bfe_u32 v157, v250, 6, 1
	v_bfe_u32 v158, v250, 7, 1
	v_lshl_add_u32 v158, v158, 6, s4
	v_add_u32_e32 v158, v158, v251
	v_lshl_add_u32 v157, v157, 7, s5
	v_lshl_add_u32 v159, v156, 2, v157
	v_lshlrev_b32_e32 v246, 2, v159
	v_lshl_add_u32 v244, v158, 12, v246
	v_lshlrev_b32_e32 v161, 1, v159
	v_lshl_add_u32 v245, v158, 11, v161
	v_and_b32_e32 v254, 1, v156
	v_mul_u32_u24_e32 v254, 24, v254
	v_lshl_add_u32 v254, v156, 3, v254
	v_lshl_add_u32 v254, v158, 6, v254
	v_lshrrev_b32_e32 v161, 5, v157
	v_lshl_add_u32 v254, v161, 21, v254
	v_lshrrev_b32_e32 v161, 6, v157
	v_lshlrev_b32_e32 v161, 2, v161
	v_lshl_add_u32 v247, v158, 6, v161
	v_xor_b32_e32 v248, 16, v200
	v_lshlrev_b32_e32 v248, 2, v248
	v_xor_b32_e32 v249, 32, v200
	v_lshlrev_b32_e32 v249, 2, v249
	s_mov_b32 s24, s78
	s_mov_b32 s25, s79
	s_mov_b32 s26, s78
	s_mov_b32 s27, s79
	s_mov_b32 s28, s96
	s_mov_b32 s29, s97
	s_mov_b32 s30, s94
	s_mov_b32 s31, s95
	s_mov_b32 s22, s28
	s_mov_b32 s23, s29
	s_cmp_lg_u64 s[8:9], 0
	s_cbranch_scc0 .Lgm2_noemit
	global_load_dwordx4 v[208:211], v246, s[10:11]
	global_load_dwordx4 v[212:215], v246, s[10:11] offset:64
	global_load_dwordx4 v[216:219], v246, s[10:11] offset:128
	global_load_dwordx4 v[220:223], v246, s[10:11] offset:192
	global_load_dwordx4 v[224:227], v246, s[10:11] offset:256
	global_load_dwordx4 v[228:231], v246, s[10:11] offset:320
	global_load_dwordx4 v[232:235], v246, s[10:11] offset:384
	global_load_dwordx4 v[236:239], v246, s[10:11] offset:448
	global_load_dwordx4 v[0:3], v244, s[24:25]
	global_load_dwordx4 v[4:7], v244, s[24:25] offset:64
	global_load_dwordx4 v[8:11], v244, s[24:25] offset:128
	global_load_dwordx4 v[12:15], v244, s[24:25] offset:192
	global_load_dwordx4 v[16:19], v244, s[24:25] offset:256
	global_load_dwordx4 v[20:23], v244, s[24:25] offset:320
	global_load_dwordx4 v[162:165], v244, s[24:25] offset:384
	global_load_dwordx4 v[166:169], v244, s[24:25] offset:448
	s_add_u32 s24, s24, 0x10000
	s_addc_u32 s25, s25, 0
	global_load_dwordx4 v[170:173], v244, s[24:25]
	global_load_dwordx4 v[174:177], v244, s[24:25] offset:64
	global_load_dwordx4 v[178:181], v244, s[24:25] offset:128
	global_load_dwordx4 v[182:185], v244, s[24:25] offset:192
	global_load_dwordx4 v[186:189], v244, s[24:25] offset:256
	global_load_dwordx4 v[190:193], v244, s[24:25] offset:320
	global_load_dwordx4 v[194:197], v244, s[24:25] offset:384
	global_load_dwordx4 v[240:243], v244, s[24:25] offset:448
	s_add_u32 s24, s24, 0x10000
	s_addc_u32 s25, s25, 0
	s_waitcnt vmcnt(12)
	v_add_f32_e32 v0, v128, v0
	v_add_f32_e32 v1, v129, v1
	v_add_f32_e32 v2, v130, v2
	v_add_f32_e32 v3, v131, v3
	global_store_dwordx4 v244, v[0:3], s[26:27]
	v_mul_f32_e32 v158, v0, v0
	v_mul_f32_e32 v159, v1, v1
	v_mul_f32_e32 v250, v2, v2
	v_mul_f32_e32 v251, v3, v3
	v_add_f32_e32 v158, v158, v159
	v_add_f32_e32 v250, v250, v251
	v_add_f32_e32 v161, v158, v250
	v_mul_f32_e32 v156, v0, v208
	v_mul_f32_e32 v157, v1, v209
	v_mul_f32_e32 v158, v2, v210
	v_mul_f32_e32 v159, v3, v211
	v_cvt_pk_bf16_f32 v156, v156, v157
	v_cvt_pk_bf16_f32 v157, v158, v159
	v_add_f32_e32 v4, v120, v4
	v_add_f32_e32 v5, v121, v5
	v_add_f32_e32 v6, v122, v6
	v_add_f32_e32 v7, v123, v7
	global_store_dwordx4 v244, v[4:7], s[26:27] offset:64
	v_mul_f32_e32 v158, v4, v4
	v_mul_f32_e32 v159, v5, v5
	v_mul_f32_e32 v250, v6, v6
	v_mul_f32_e32 v251, v7, v7
	v_add_f32_e32 v158, v158, v159
	v_add_f32_e32 v250, v250, v251
	v_add_f32_e32 v158, v158, v250
	v_add_f32_e32 v161, v161, v158
	v_mul_f32_e32 v158, v4, v212
	v_mul_f32_e32 v159, v5, v213
	v_mul_f32_e32 v250, v6, v214
	v_mul_f32_e32 v251, v7, v215
	v_cvt_pk_bf16_f32 v158, v158, v159
	v_cvt_pk_bf16_f32 v159, v250, v251
	s_nop 1
	v_permlane16_swap_b32_e32 v156, v158
	v_permlane16_swap_b32_e32 v157, v159
	s_add_u32 s28, s22, 0x0
	s_addc_u32 s29, s23, 0
	global_store_dwordx4 v254, v[156:159], s[28:29]
	v_add_f32_e32 v8, v104, v8
	v_add_f32_e32 v9, v105, v9
	v_add_f32_e32 v10, v106, v10
	v_add_f32_e32 v11, v107, v11
	global_store_dwordx4 v244, v[8:11], s[26:27] offset:128
	v_mul_f32_e32 v158, v8, v8
	v_mul_f32_e32 v159, v9, v9
	v_mul_f32_e32 v250, v10, v10
	v_mul_f32_e32 v251, v11, v11
	v_add_f32_e32 v158, v158, v159
	v_add_f32_e32 v250, v250, v251
	v_add_f32_e32 v158, v158, v250
	v_add_f32_e32 v161, v161, v158
	v_mul_f32_e32 v156, v8, v216
	v_mul_f32_e32 v157, v9, v217
	v_mul_f32_e32 v158, v10, v218
	v_mul_f32_e32 v159, v11, v219
	v_cvt_pk_bf16_f32 v156, v156, v157
	v_cvt_pk_bf16_f32 v157, v158, v159
	v_add_f32_e32 v12, v100, v12
	v_add_f32_e32 v13, v101, v13
	v_add_f32_e32 v14, v102, v14
	v_add_f32_e32 v15, v103, v15
	global_store_dwordx4 v244, v[12:15], s[26:27] offset:192
	v_mul_f32_e32 v158, v12, v12
	v_mul_f32_e32 v159, v13, v13
	v_mul_f32_e32 v250, v14, v14
	v_mul_f32_e32 v251, v15, v15
	v_add_f32_e32 v158, v158, v159
	v_add_f32_e32 v250, v250, v251
	v_add_f32_e32 v158, v158, v250
	v_add_f32_e32 v161, v161, v158
	v_mul_f32_e32 v158, v12, v220
	v_mul_f32_e32 v159, v13, v221
	v_mul_f32_e32 v250, v14, v222
	v_mul_f32_e32 v251, v15, v223
	v_cvt_pk_bf16_f32 v158, v158, v159
	v_cvt_pk_bf16_f32 v159, v250, v251
	s_nop 1
	v_permlane16_swap_b32_e32 v156, v158
	v_permlane16_swap_b32_e32 v157, v159
	s_add_u32 s28, s22, 0x200000
	s_addc_u32 s29, s23, 0
	global_store_dwordx4 v254, v[156:159], s[28:29]
	ds_bpermute_b32 v158, v248, v161
	s_waitcnt lgkmcnt(0)
	v_add_f32_e32 v161, v161, v158
	ds_bpermute_b32 v158, v249, v161
	s_waitcnt lgkmcnt(0)
	v_add_f32_e32 v161, v161, v158
	global_store_dword v247, v161, s[30:31]
	global_load_dwordx4 v[0:3], v244, s[24:25]
	global_load_dwordx4 v[4:7], v244, s[24:25] offset:64
	global_load_dwordx4 v[8:11], v244, s[24:25] offset:128
	global_load_dwordx4 v[12:15], v244, s[24:25] offset:192
	s_waitcnt vmcnt(19)
	v_add_f32_e32 v16, v60, v16
	v_add_f32_e32 v17, v61, v17
	v_add_f32_e32 v18, v62, v18
	v_add_f32_e32 v19, v63, v19
	global_store_dwordx4 v244, v[16:19], s[26:27] offset:256
	v_mul_f32_e32 v158, v16, v16
	v_mul_f32_e32 v159, v17, v17
	v_mul_f32_e32 v250, v18, v18
	v_mul_f32_e32 v251, v19, v19
	v_add_f32_e32 v158, v158, v159
	v_add_f32_e32 v250, v250, v251
	v_add_f32_e32 v161, v158, v250
	v_mul_f32_e32 v156, v16, v224
	v_mul_f32_e32 v157, v17, v225
	v_mul_f32_e32 v158, v18, v226
	v_mul_f32_e32 v159, v19, v227
	v_cvt_pk_bf16_f32 v156, v156, v157
	v_cvt_pk_bf16_f32 v157, v158, v159
	v_add_f32_e32 v20, v48, v20
	v_add_f32_e32 v21, v49, v21
	v_add_f32_e32 v22, v50, v22
	v_add_f32_e32 v23, v51, v23
	global_store_dwordx4 v244, v[20:23], s[26:27] offset:320
	v_mul_f32_e32 v158, v20, v20
	v_mul_f32_e32 v159, v21, v21
	v_mul_f32_e32 v250, v22, v22
	v_mul_f32_e32 v251, v23, v23
	v_add_f32_e32 v158, v158, v159
	v_add_f32_e32 v250, v250, v251
	v_add_f32_e32 v158, v158, v250
	v_add_f32_e32 v161, v161, v158
	v_mul_f32_e32 v158, v20, v228
	v_mul_f32_e32 v159, v21, v229
	v_mul_f32_e32 v250, v22, v230
	v_mul_f32_e32 v251, v23, v231
	v_cvt_pk_bf16_f32 v158, v158, v159
	v_cvt_pk_bf16_f32 v159, v250, v251
	s_nop 1
	v_permlane16_swap_b32_e32 v156, v158
	v_permlane16_swap_b32_e32 v157, v159
	s_add_u32 s28, s22, 0x400000
	s_addc_u32 s29, s23, 0
	global_store_dwordx4 v254, v[156:159], s[28:29]
	v_add_f32_e32 v162, v44, v162
	v_add_f32_e32 v163, v45, v163
	v_add_f32_e32 v164, v46, v164
	v_add_f32_e32 v165, v47, v165
	global_store_dwordx4 v244, v[162:165], s[26:27] offset:384
	v_mul_f32_e32 v158, v162, v162
	v_mul_f32_e32 v159, v163, v163
	v_mul_f32_e32 v250, v164, v164
	v_mul_f32_e32 v251, v165, v165
	v_add_f32_e32 v158, v158, v159
	v_add_f32_e32 v250, v250, v251
	v_add_f32_e32 v158, v158, v250
	v_add_f32_e32 v161, v161, v158
	v_mul_f32_e32 v156, v162, v232
	v_mul_f32_e32 v157, v163, v233
	v_mul_f32_e32 v158, v164, v234
	v_mul_f32_e32 v159, v165, v235
	v_cvt_pk_bf16_f32 v156, v156, v157
	v_cvt_pk_bf16_f32 v157, v158, v159
	v_add_f32_e32 v166, v40, v166
	v_add_f32_e32 v167, v41, v167
	v_add_f32_e32 v168, v42, v168
	v_add_f32_e32 v169, v43, v169
	global_store_dwordx4 v244, v[166:169], s[26:27] offset:448
	v_mul_f32_e32 v158, v166, v166
	v_mul_f32_e32 v159, v167, v167
	v_mul_f32_e32 v250, v168, v168
	v_mul_f32_e32 v251, v169, v169
	v_add_f32_e32 v158, v158, v159
	v_add_f32_e32 v250, v250, v251
	v_add_f32_e32 v158, v158, v250
	v_add_f32_e32 v161, v161, v158
	v_mul_f32_e32 v158, v166, v236
	v_mul_f32_e32 v159, v167, v237
	v_mul_f32_e32 v250, v168, v238
	v_mul_f32_e32 v251, v169, v239
	v_cvt_pk_bf16_f32 v158, v158, v159
	v_cvt_pk_bf16_f32 v159, v250, v251
	s_nop 1
	v_permlane16_swap_b32_e32 v156, v158
	v_permlane16_swap_b32_e32 v157, v159
	s_add_u32 s28, s22, 0x600000
	s_addc_u32 s29, s23, 0
	global_store_dwordx4 v254, v[156:159], s[28:29]
	ds_bpermute_b32 v158, v248, v161
	s_waitcnt lgkmcnt(0)
	v_add_f32_e32 v161, v161, v158
	ds_bpermute_b32 v158, v249, v161
	s_waitcnt lgkmcnt(0)
	v_add_f32_e32 v161, v161, v158
	global_store_dword v247, v161, s[30:31] offset:4
	s_add_u32 s26, s26, 0x10000
	s_addc_u32 s27, s27, 0
	s_add_u32 s30, s30, 0x400
	s_addc_u32 s31, s31, 0
	global_load_dwordx4 v[16:19], v244, s[24:25] offset:256
	global_load_dwordx4 v[20:23], v244, s[24:25] offset:320
	global_load_dwordx4 v[162:165], v244, s[24:25] offset:384
	global_load_dwordx4 v[166:169], v244, s[24:25] offset:448
	s_add_u32 s24, s24, 0x10000
	s_addc_u32 s25, s25, 0
	s_waitcnt vmcnt(26)
	v_add_f32_e32 v170, v68, v170
	v_add_f32_e32 v171, v69, v171
	v_add_f32_e32 v172, v70, v172
	v_add_f32_e32 v173, v71, v173
	global_store_dwordx4 v244, v[170:173], s[26:27]
	v_mul_f32_e32 v158, v170, v170
	v_mul_f32_e32 v159, v171, v171
	v_mul_f32_e32 v250, v172, v172
	v_mul_f32_e32 v251, v173, v173
	v_add_f32_e32 v158, v158, v159
	v_add_f32_e32 v250, v250, v251
	v_add_f32_e32 v161, v158, v250
	v_mul_f32_e32 v156, v170, v208
	v_mul_f32_e32 v157, v171, v209
	v_mul_f32_e32 v158, v172, v210
	v_mul_f32_e32 v159, v173, v211
	v_cvt_pk_bf16_f32 v156, v156, v157
	v_cvt_pk_bf16_f32 v157, v158, v159
	v_add_f32_e32 v174, v64, v174
	v_add_f32_e32 v175, v65, v175
	v_add_f32_e32 v176, v66, v176
	v_add_f32_e32 v177, v67, v177
	global_store_dwordx4 v244, v[174:177], s[26:27] offset:64
	v_mul_f32_e32 v158, v174, v174
	v_mul_f32_e32 v159, v175, v175
	v_mul_f32_e32 v250, v176, v176
	v_mul_f32_e32 v251, v177, v177
	v_add_f32_e32 v158, v158, v159
	v_add_f32_e32 v250, v250, v251
	v_add_f32_e32 v158, v158, v250
	v_add_f32_e32 v161, v161, v158
	v_mul_f32_e32 v158, v174, v212
	v_mul_f32_e32 v159, v175, v213
	v_mul_f32_e32 v250, v176, v214
	v_mul_f32_e32 v251, v177, v215
	v_cvt_pk_bf16_f32 v158, v158, v159
	v_cvt_pk_bf16_f32 v159, v250, v251
	s_nop 1
	v_permlane16_swap_b32_e32 v156, v158
	v_permlane16_swap_b32_e32 v157, v159
	s_add_u32 s28, s22, 0x400
	s_addc_u32 s29, s23, 0
	global_store_dwordx4 v254, v[156:159], s[28:29]
	v_add_f32_e32 v178, v56, v178
	v_add_f32_e32 v179, v57, v179
	v_add_f32_e32 v180, v58, v180
	v_add_f32_e32 v181, v59, v181
	global_store_dwordx4 v244, v[178:181], s[26:27] offset:128
	v_mul_f32_e32 v158, v178, v178
	v_mul_f32_e32 v159, v179, v179
	v_mul_f32_e32 v250, v180, v180
	v_mul_f32_e32 v251, v181, v181
	v_add_f32_e32 v158, v158, v159
	v_add_f32_e32 v250, v250, v251
	v_add_f32_e32 v158, v158, v250
	v_add_f32_e32 v161, v161, v158
	v_mul_f32_e32 v156, v178, v216
	v_mul_f32_e32 v157, v179, v217
	v_mul_f32_e32 v158, v180, v218
	v_mul_f32_e32 v159, v181, v219
	v_cvt_pk_bf16_f32 v156, v156, v157
	v_cvt_pk_bf16_f32 v157, v158, v159
	v_add_f32_e32 v182, v52, v182
	v_add_f32_e32 v183, v53, v183
	v_add_f32_e32 v184, v54, v184
	v_add_f32_e32 v185, v55, v185
	global_store_dwordx4 v244, v[182:185], s[26:27] offset:192
	v_mul_f32_e32 v158, v182, v182
	v_mul_f32_e32 v159, v183, v183
	v_mul_f32_e32 v250, v184, v184
	v_mul_f32_e32 v251, v185, v185
	v_add_f32_e32 v158, v158, v159
	v_add_f32_e32 v250, v250, v251
	v_add_f32_e32 v158, v158, v250
	v_add_f32_e32 v161, v161, v158
	v_mul_f32_e32 v158, v182, v220
	v_mul_f32_e32 v159, v183, v221
	v_mul_f32_e32 v250, v184, v222
	v_mul_f32_e32 v251, v185, v223
	v_cvt_pk_bf16_f32 v158, v158, v159
	v_cvt_pk_bf16_f32 v159, v250, v251
	s_nop 1
	v_permlane16_swap_b32_e32 v156, v158
	v_permlane16_swap_b32_e32 v157, v159
	s_add_u32 s28, s22, 0x200400
	s_addc_u32 s29, s23, 0
	global_store_dwordx4 v254, v[156:159], s[28:29]
	ds_bpermute_b32 v158, v248, v161
	s_waitcnt lgkmcnt(0)
	v_add_f32_e32 v161, v161, v158
	ds_bpermute_b32 v158, v249, v161
	s_waitcnt lgkmcnt(0)
	v_add_f32_e32 v161, v161, v158
	global_store_dword v247, v161, s[30:31]
	global_load_dwordx4 v[170:173], v244, s[24:25]
	global_load_dwordx4 v[174:177], v244, s[24:25] offset:64
	global_load_dwordx4 v[178:181], v244, s[24:25] offset:128
	global_load_dwordx4 v[182:185], v244, s[24:25] offset:192
	s_waitcnt vmcnt(33)
	v_add_f32_e32 v186, v36, v186
	v_add_f32_e32 v187, v37, v187
	v_add_f32_e32 v188, v38, v188
	v_add_f32_e32 v189, v39, v189
	global_store_dwordx4 v244, v[186:189], s[26:27] offset:256
	v_mul_f32_e32 v158, v186, v186
	v_mul_f32_e32 v159, v187, v187
	v_mul_f32_e32 v250, v188, v188
	v_mul_f32_e32 v251, v189, v189
	v_add_f32_e32 v158, v158, v159
	v_add_f32_e32 v250, v250, v251
	v_add_f32_e32 v161, v158, v250
	v_mul_f32_e32 v156, v186, v224
	v_mul_f32_e32 v157, v187, v225
	v_mul_f32_e32 v158, v188, v226
	v_mul_f32_e32 v159, v189, v227
	v_cvt_pk_bf16_f32 v156, v156, v157
	v_cvt_pk_bf16_f32 v157, v158, v159
	v_add_f32_e32 v190, v32, v190
	v_add_f32_e32 v191, v33, v191
	v_add_f32_e32 v192, v34, v192
	v_add_f32_e32 v193, v35, v193
	global_store_dwordx4 v244, v[190:193], s[26:27] offset:320
	v_mul_f32_e32 v158, v190, v190
	v_mul_f32_e32 v159, v191, v191
	v_mul_f32_e32 v250, v192, v192
	v_mul_f32_e32 v251, v193, v193
	v_add_f32_e32 v158, v158, v159
	v_add_f32_e32 v250, v250, v251
	v_add_f32_e32 v158, v158, v250
	v_add_f32_e32 v161, v161, v158
	v_mul_f32_e32 v158, v190, v228
	v_mul_f32_e32 v159, v191, v229
	v_mul_f32_e32 v250, v192, v230
	v_mul_f32_e32 v251, v193, v231
	v_cvt_pk_bf16_f32 v158, v158, v159
	v_cvt_pk_bf16_f32 v159, v250, v251
	s_nop 1
	v_permlane16_swap_b32_e32 v156, v158
	v_permlane16_swap_b32_e32 v157, v159
	s_add_u32 s28, s22, 0x400400
	s_addc_u32 s29, s23, 0
	global_store_dwordx4 v254, v[156:159], s[28:29]
	v_add_f32_e32 v194, v28, v194
	v_add_f32_e32 v195, v29, v195
	v_add_f32_e32 v196, v30, v196
	v_add_f32_e32 v197, v31, v197
	global_store_dwordx4 v244, v[194:197], s[26:27] offset:384
	v_mul_f32_e32 v158, v194, v194
	v_mul_f32_e32 v159, v195, v195
	v_mul_f32_e32 v250, v196, v196
	v_mul_f32_e32 v251, v197, v197
	v_add_f32_e32 v158, v158, v159
	v_add_f32_e32 v250, v250, v251
	v_add_f32_e32 v158, v158, v250
	v_add_f32_e32 v161, v161, v158
	v_mul_f32_e32 v156, v194, v232
	v_mul_f32_e32 v157, v195, v233
	v_mul_f32_e32 v158, v196, v234
	v_mul_f32_e32 v159, v197, v235
	v_cvt_pk_bf16_f32 v156, v156, v157
	v_cvt_pk_bf16_f32 v157, v158, v159
	v_add_f32_e32 v240, v24, v240
	v_add_f32_e32 v241, v25, v241
	v_add_f32_e32 v242, v26, v242
	v_add_f32_e32 v243, v27, v243
	global_store_dwordx4 v244, v[240:243], s[26:27] offset:448
	v_mul_f32_e32 v158, v240, v240
	v_mul_f32_e32 v159, v241, v241
	v_mul_f32_e32 v250, v242, v242
	v_mul_f32_e32 v251, v243, v243
	v_add_f32_e32 v158, v158, v159
	v_add_f32_e32 v250, v250, v251
	v_add_f32_e32 v158, v158, v250
	v_add_f32_e32 v161, v161, v158
	v_mul_f32_e32 v158, v240, v236
	v_mul_f32_e32 v159, v241, v237
	v_mul_f32_e32 v250, v242, v238
	v_mul_f32_e32 v251, v243, v239
	v_cvt_pk_bf16_f32 v158, v158, v159
	v_cvt_pk_bf16_f32 v159, v250, v251
	s_nop 1
	v_permlane16_swap_b32_e32 v156, v158
	v_permlane16_swap_b32_e32 v157, v159
	s_add_u32 s28, s22, 0x600400
	s_addc_u32 s29, s23, 0
	global_store_dwordx4 v254, v[156:159], s[28:29]
	ds_bpermute_b32 v158, v248, v161
	s_waitcnt lgkmcnt(0)
	v_add_f32_e32 v161, v161, v158
	ds_bpermute_b32 v158, v249, v161
	s_waitcnt lgkmcnt(0)
	v_add_f32_e32 v161, v161, v158
	global_store_dword v247, v161, s[30:31] offset:4
	s_add_u32 s26, s26, 0x10000
	s_addc_u32 s27, s27, 0
	s_add_u32 s30, s30, 0x400
	s_addc_u32 s31, s31, 0
	global_load_dwordx4 v[186:189], v244, s[24:25] offset:256
	global_load_dwordx4 v[190:193], v244, s[24:25] offset:320
	global_load_dwordx4 v[194:197], v244, s[24:25] offset:384
	global_load_dwordx4 v[240:243], v244, s[24:25] offset:448
	s_add_u32 s24, s24, 0x10000
	s_addc_u32 s25, s25, 0
	s_waitcnt vmcnt(33)
	v_add_f32_e32 v0, v108, v0
	v_add_f32_e32 v1, v109, v1
	v_add_f32_e32 v2, v110, v2
	v_add_f32_e32 v3, v111, v3
	global_store_dwordx4 v244, v[0:3], s[26:27]
	v_mul_f32_e32 v158, v0, v0
	v_mul_f32_e32 v159, v1, v1
	v_mul_f32_e32 v250, v2, v2
	v_mul_f32_e32 v251, v3, v3
	v_add_f32_e32 v158, v158, v159
	v_add_f32_e32 v250, v250, v251
	v_add_f32_e32 v161, v158, v250
	v_mul_f32_e32 v156, v0, v208
	v_mul_f32_e32 v157, v1, v209
	v_mul_f32_e32 v158, v2, v210
	v_mul_f32_e32 v159, v3, v211
	v_cvt_pk_bf16_f32 v156, v156, v157
	v_cvt_pk_bf16_f32 v157, v158, v159
	v_add_f32_e32 v4, v112, v4
	v_add_f32_e32 v5, v113, v5
	v_add_f32_e32 v6, v114, v6
	v_add_f32_e32 v7, v115, v7
	global_store_dwordx4 v244, v[4:7], s[26:27] offset:64
	v_mul_f32_e32 v158, v4, v4
	v_mul_f32_e32 v159, v5, v5
	v_mul_f32_e32 v250, v6, v6
	v_mul_f32_e32 v251, v7, v7
	v_add_f32_e32 v158, v158, v159
	v_add_f32_e32 v250, v250, v251
	v_add_f32_e32 v158, v158, v250
	v_add_f32_e32 v161, v161, v158
	v_mul_f32_e32 v158, v4, v212
	v_mul_f32_e32 v159, v5, v213
	v_mul_f32_e32 v250, v6, v214
	v_mul_f32_e32 v251, v7, v215
	v_cvt_pk_bf16_f32 v158, v158, v159
	v_cvt_pk_bf16_f32 v159, v250, v251
	s_nop 1
	v_permlane16_swap_b32_e32 v156, v158
	v_permlane16_swap_b32_e32 v157, v159
	s_add_u32 s28, s22, 0x800
	s_addc_u32 s29, s23, 0
	global_store_dwordx4 v254, v[156:159], s[28:29]
	v_add_f32_e32 v8, v116, v8
	v_add_f32_e32 v9, v117, v9
	v_add_f32_e32 v10, v118, v10
	v_add_f32_e32 v11, v119, v11
	global_store_dwordx4 v244, v[8:11], s[26:27] offset:128
	v_mul_f32_e32 v158, v8, v8
	v_mul_f32_e32 v159, v9, v9
	v_mul_f32_e32 v250, v10, v10
	v_mul_f32_e32 v251, v11, v11
	v_add_f32_e32 v158, v158, v159
	v_add_f32_e32 v250, v250, v251
	v_add_f32_e32 v158, v158, v250
	v_add_f32_e32 v161, v161, v158
	v_mul_f32_e32 v156, v8, v216
	v_mul_f32_e32 v157, v9, v217
	v_mul_f32_e32 v158, v10, v218
	v_mul_f32_e32 v159, v11, v219
	v_cvt_pk_bf16_f32 v156, v156, v157
	v_cvt_pk_bf16_f32 v157, v158, v159
	v_add_f32_e32 v12, v124, v12
	v_add_f32_e32 v13, v125, v13
	v_add_f32_e32 v14, v126, v14
	v_add_f32_e32 v15, v127, v15
	global_store_dwordx4 v244, v[12:15], s[26:27] offset:192
	v_mul_f32_e32 v158, v12, v12
	v_mul_f32_e32 v159, v13, v13
	v_mul_f32_e32 v250, v14, v14
	v_mul_f32_e32 v251, v15, v15
	v_add_f32_e32 v158, v158, v159
	v_add_f32_e32 v250, v250, v251
	v_add_f32_e32 v158, v158, v250
	v_add_f32_e32 v161, v161, v158
	v_mul_f32_e32 v158, v12, v220
	v_mul_f32_e32 v159, v13, v221
	v_mul_f32_e32 v250, v14, v222
	v_mul_f32_e32 v251, v15, v223
	v_cvt_pk_bf16_f32 v158, v158, v159
	v_cvt_pk_bf16_f32 v159, v250, v251
	s_nop 1
	v_permlane16_swap_b32_e32 v156, v158
	v_permlane16_swap_b32_e32 v157, v159
	s_add_u32 s28, s22, 0x200800
	s_addc_u32 s29, s23, 0
	global_store_dwordx4 v254, v[156:159], s[28:29]
	ds_bpermute_b32 v158, v248, v161
	s_waitcnt lgkmcnt(0)
	v_add_f32_e32 v161, v161, v158
	ds_bpermute_b32 v158, v249, v161
	s_waitcnt lgkmcnt(0)
	v_add_f32_e32 v161, v161, v158
	global_store_dword v247, v161, s[30:31]
	s_waitcnt vmcnt(29)
	v_add_f32_e32 v16, v80, v16
	v_add_f32_e32 v17, v81, v17
	v_add_f32_e32 v18, v82, v18
	v_add_f32_e32 v19, v83, v19
	global_store_dwordx4 v244, v[16:19], s[26:27] offset:256
	v_mul_f32_e32 v158, v16, v16
	v_mul_f32_e32 v159, v17, v17
	v_mul_f32_e32 v250, v18, v18
	v_mul_f32_e32 v251, v19, v19
	v_add_f32_e32 v158, v158, v159
	v_add_f32_e32 v250, v250, v251
	v_add_f32_e32 v161, v158, v250
	v_mul_f32_e32 v156, v16, v224
	v_mul_f32_e32 v157, v17, v225
	v_mul_f32_e32 v158, v18, v226
	v_mul_f32_e32 v159, v19, v227
	v_cvt_pk_bf16_f32 v156, v156, v157
	v_cvt_pk_bf16_f32 v157, v158, v159
	v_add_f32_e32 v20, v84, v20
	v_add_f32_e32 v21, v85, v21
	v_add_f32_e32 v22, v86, v22
	v_add_f32_e32 v23, v87, v23
	global_store_dwordx4 v244, v[20:23], s[26:27] offset:320
	v_mul_f32_e32 v158, v20, v20
	v_mul_f32_e32 v159, v21, v21
	v_mul_f32_e32 v250, v22, v22
	v_mul_f32_e32 v251, v23, v23
	v_add_f32_e32 v158, v158, v159
	v_add_f32_e32 v250, v250, v251
	v_add_f32_e32 v158, v158, v250
	v_add_f32_e32 v161, v161, v158
	v_mul_f32_e32 v158, v20, v228
	v_mul_f32_e32 v159, v21, v229
	v_mul_f32_e32 v250, v22, v230
	v_mul_f32_e32 v251, v23, v231
	v_cvt_pk_bf16_f32 v158, v158, v159
	v_cvt_pk_bf16_f32 v159, v250, v251
	s_nop 1
	v_permlane16_swap_b32_e32 v156, v158
	v_permlane16_swap_b32_e32 v157, v159
	s_add_u32 s28, s22, 0x400800
	s_addc_u32 s29, s23, 0
	global_store_dwordx4 v254, v[156:159], s[28:29]
	v_add_f32_e32 v162, v96, v162
	v_add_f32_e32 v163, v97, v163
	v_add_f32_e32 v164, v98, v164
	v_add_f32_e32 v165, v99, v165
	global_store_dwordx4 v244, v[162:165], s[26:27] offset:384
	v_mul_f32_e32 v158, v162, v162
	v_mul_f32_e32 v159, v163, v163
	v_mul_f32_e32 v250, v164, v164
	v_mul_f32_e32 v251, v165, v165
	v_add_f32_e32 v158, v158, v159
	v_add_f32_e32 v250, v250, v251
	v_add_f32_e32 v158, v158, v250
	v_add_f32_e32 v161, v161, v158
	v_mul_f32_e32 v156, v162, v232
	v_mul_f32_e32 v157, v163, v233
	v_mul_f32_e32 v158, v164, v234
	v_mul_f32_e32 v159, v165, v235
	v_cvt_pk_bf16_f32 v156, v156, v157
	v_cvt_pk_bf16_f32 v157, v158, v159
	v_add_f32_e32 v166, v72, v166
	v_add_f32_e32 v167, v73, v167
	v_add_f32_e32 v168, v74, v168
	v_add_f32_e32 v169, v75, v169
	global_store_dwordx4 v244, v[166:169], s[26:27] offset:448
	v_mul_f32_e32 v158, v166, v166
	v_mul_f32_e32 v159, v167, v167
	v_mul_f32_e32 v250, v168, v168
	v_mul_f32_e32 v251, v169, v169
	v_add_f32_e32 v158, v158, v159
	v_add_f32_e32 v250, v250, v251
	v_add_f32_e32 v158, v158, v250
	v_add_f32_e32 v161, v161, v158
	v_mul_f32_e32 v158, v166, v236
	v_mul_f32_e32 v159, v167, v237
	v_mul_f32_e32 v250, v168, v238
	v_mul_f32_e32 v251, v169, v239
	v_cvt_pk_bf16_f32 v158, v158, v159
	v_cvt_pk_bf16_f32 v159, v250, v251
	s_nop 1
	v_permlane16_swap_b32_e32 v156, v158
	v_permlane16_swap_b32_e32 v157, v159
	s_add_u32 s28, s22, 0x600800
	s_addc_u32 s29, s23, 0
	global_store_dwordx4 v254, v[156:159], s[28:29]
	ds_bpermute_b32 v158, v248, v161
	s_waitcnt lgkmcnt(0)
	v_add_f32_e32 v161, v161, v158
	ds_bpermute_b32 v158, v249, v161
	s_waitcnt lgkmcnt(0)
	v_add_f32_e32 v161, v161, v158
	global_store_dword v247, v161, s[30:31] offset:4
	s_add_u32 s26, s26, 0x10000
	s_addc_u32 s27, s27, 0
	s_add_u32 s30, s30, 0x400
	s_addc_u32 s31, s31, 0
	s_waitcnt vmcnt(25)
	v_add_f32_e32 v170, v132, v170
	v_add_f32_e32 v171, v133, v171
	v_add_f32_e32 v172, v134, v172
	v_add_f32_e32 v173, v135, v173
	global_store_dwordx4 v244, v[170:173], s[26:27]
	v_mul_f32_e32 v158, v170, v170
	v_mul_f32_e32 v159, v171, v171
	v_mul_f32_e32 v250, v172, v172
	v_mul_f32_e32 v251, v173, v173
	v_add_f32_e32 v158, v158, v159
	v_add_f32_e32 v250, v250, v251
	v_add_f32_e32 v161, v158, v250
	v_mul_f32_e32 v156, v170, v208
	v_mul_f32_e32 v157, v171, v209
	v_mul_f32_e32 v158, v172, v210
	v_mul_f32_e32 v159, v173, v211
	v_cvt_pk_bf16_f32 v156, v156, v157
	v_cvt_pk_bf16_f32 v157, v158, v159
	v_add_f32_e32 v174, v136, v174
	v_add_f32_e32 v175, v137, v175
	v_add_f32_e32 v176, v138, v176
	v_add_f32_e32 v177, v139, v177
	global_store_dwordx4 v244, v[174:177], s[26:27] offset:64
	v_mul_f32_e32 v158, v174, v174
	v_mul_f32_e32 v159, v175, v175
	v_mul_f32_e32 v250, v176, v176
	v_mul_f32_e32 v251, v177, v177
	v_add_f32_e32 v158, v158, v159
	v_add_f32_e32 v250, v250, v251
	v_add_f32_e32 v158, v158, v250
	v_add_f32_e32 v161, v161, v158
	v_mul_f32_e32 v158, v174, v212
	v_mul_f32_e32 v159, v175, v213
	v_mul_f32_e32 v250, v176, v214
	v_mul_f32_e32 v251, v177, v215
	v_cvt_pk_bf16_f32 v158, v158, v159
	v_cvt_pk_bf16_f32 v159, v250, v251
	s_nop 1
	v_permlane16_swap_b32_e32 v156, v158
	v_permlane16_swap_b32_e32 v157, v159
	s_add_u32 s28, s22, 0xc00
	s_addc_u32 s29, s23, 0
	global_store_dwordx4 v254, v[156:159], s[28:29]
	v_add_f32_e32 v178, v140, v178
	v_add_f32_e32 v179, v141, v179
	v_add_f32_e32 v180, v142, v180
	v_add_f32_e32 v181, v143, v181
	global_store_dwordx4 v244, v[178:181], s[26:27] offset:128
	v_mul_f32_e32 v158, v178, v178
	v_mul_f32_e32 v159, v179, v179
	v_mul_f32_e32 v250, v180, v180
	v_mul_f32_e32 v251, v181, v181
	v_add_f32_e32 v158, v158, v159
	v_add_f32_e32 v250, v250, v251
	v_add_f32_e32 v158, v158, v250
	v_add_f32_e32 v161, v161, v158
	v_mul_f32_e32 v156, v178, v216
	v_mul_f32_e32 v157, v179, v217
	v_mul_f32_e32 v158, v180, v218
	v_mul_f32_e32 v159, v181, v219
	v_cvt_pk_bf16_f32 v156, v156, v157
	v_cvt_pk_bf16_f32 v157, v158, v159
	v_add_f32_e32 v182, v144, v182
	v_add_f32_e32 v183, v145, v183
	v_add_f32_e32 v184, v146, v184
	v_add_f32_e32 v185, v147, v185
	global_store_dwordx4 v244, v[182:185], s[26:27] offset:192
	v_mul_f32_e32 v158, v182, v182
	v_mul_f32_e32 v159, v183, v183
	v_mul_f32_e32 v250, v184, v184
	v_mul_f32_e32 v251, v185, v185
	v_add_f32_e32 v158, v158, v159
	v_add_f32_e32 v250, v250, v251
	v_add_f32_e32 v158, v158, v250
	v_add_f32_e32 v161, v161, v158
	v_mul_f32_e32 v158, v182, v220
	v_mul_f32_e32 v159, v183, v221
	v_mul_f32_e32 v250, v184, v222
	v_mul_f32_e32 v251, v185, v223
	v_cvt_pk_bf16_f32 v158, v158, v159
	v_cvt_pk_bf16_f32 v159, v250, v251
	s_nop 1
	v_permlane16_swap_b32_e32 v156, v158
	v_permlane16_swap_b32_e32 v157, v159
	s_add_u32 s28, s22, 0x200c00
	s_addc_u32 s29, s23, 0
	global_store_dwordx4 v254, v[156:159], s[28:29]
	ds_bpermute_b32 v158, v248, v161
	s_waitcnt lgkmcnt(0)
	v_add_f32_e32 v161, v161, v158
	ds_bpermute_b32 v158, v249, v161
	s_waitcnt lgkmcnt(0)
	v_add_f32_e32 v161, v161, v158
	global_store_dword v247, v161, s[30:31]
	s_waitcnt vmcnt(21)
	v_add_f32_e32 v186, v92, v186
	v_add_f32_e32 v187, v93, v187
	v_add_f32_e32 v188, v94, v188
	v_add_f32_e32 v189, v95, v189
	global_store_dwordx4 v244, v[186:189], s[26:27] offset:256
	v_mul_f32_e32 v158, v186, v186
	v_mul_f32_e32 v159, v187, v187
	v_mul_f32_e32 v250, v188, v188
	v_mul_f32_e32 v251, v189, v189
	v_add_f32_e32 v158, v158, v159
	v_add_f32_e32 v250, v250, v251
	v_add_f32_e32 v161, v158, v250
	v_mul_f32_e32 v156, v186, v224
	v_mul_f32_e32 v157, v187, v225
	v_mul_f32_e32 v158, v188, v226
	v_mul_f32_e32 v159, v189, v227
	v_cvt_pk_bf16_f32 v156, v156, v157
	v_cvt_pk_bf16_f32 v157, v158, v159
	v_add_f32_e32 v190, v88, v190
	v_add_f32_e32 v191, v89, v191
	v_add_f32_e32 v192, v90, v192
	v_add_f32_e32 v193, v91, v193
	global_store_dwordx4 v244, v[190:193], s[26:27] offset:320
	v_mul_f32_e32 v158, v190, v190
	v_mul_f32_e32 v159, v191, v191
	v_mul_f32_e32 v250, v192, v192
	v_mul_f32_e32 v251, v193, v193
	v_add_f32_e32 v158, v158, v159
	v_add_f32_e32 v250, v250, v251
	v_add_f32_e32 v158, v158, v250
	v_add_f32_e32 v161, v161, v158
	v_mul_f32_e32 v158, v190, v228
	v_mul_f32_e32 v159, v191, v229
	v_mul_f32_e32 v250, v192, v230
	v_mul_f32_e32 v251, v193, v231
	v_cvt_pk_bf16_f32 v158, v158, v159
	v_cvt_pk_bf16_f32 v159, v250, v251
	s_nop 1
	v_permlane16_swap_b32_e32 v156, v158
	v_permlane16_swap_b32_e32 v157, v159
	s_add_u32 s28, s22, 0x400c00
	s_addc_u32 s29, s23, 0
	global_store_dwordx4 v254, v[156:159], s[28:29]
	v_add_f32_e32 v194, v76, v194
	v_add_f32_e32 v195, v77, v195
	v_add_f32_e32 v196, v78, v196
	v_add_f32_e32 v197, v79, v197
	global_store_dwordx4 v244, v[194:197], s[26:27] offset:384
	v_mul_f32_e32 v158, v194, v194
	v_mul_f32_e32 v159, v195, v195
	v_mul_f32_e32 v250, v196, v196
	v_mul_f32_e32 v251, v197, v197
	v_add_f32_e32 v158, v158, v159
	v_add_f32_e32 v250, v250, v251
	v_add_f32_e32 v158, v158, v250
	v_add_f32_e32 v161, v161, v158
	v_mul_f32_e32 v156, v194, v232
	v_mul_f32_e32 v157, v195, v233
	v_mul_f32_e32 v158, v196, v234
	v_mul_f32_e32 v159, v197, v235
	v_cvt_pk_bf16_f32 v156, v156, v157
	v_cvt_pk_bf16_f32 v157, v158, v159
	v_add_f32_e32 v240, v148, v240
	v_add_f32_e32 v241, v149, v241
	v_add_f32_e32 v242, v150, v242
	v_add_f32_e32 v243, v151, v243
	global_store_dwordx4 v244, v[240:243], s[26:27] offset:448
	v_mul_f32_e32 v158, v240, v240
	v_mul_f32_e32 v159, v241, v241
	v_mul_f32_e32 v250, v242, v242
	v_mul_f32_e32 v251, v243, v243
	v_add_f32_e32 v158, v158, v159
	v_add_f32_e32 v250, v250, v251
	v_add_f32_e32 v158, v158, v250
	v_add_f32_e32 v161, v161, v158
	v_mul_f32_e32 v158, v240, v236
	v_mul_f32_e32 v159, v241, v237
	v_mul_f32_e32 v250, v242, v238
	v_mul_f32_e32 v251, v243, v239
	v_cvt_pk_bf16_f32 v158, v158, v159
	v_cvt_pk_bf16_f32 v159, v250, v251
	s_nop 1
	v_permlane16_swap_b32_e32 v156, v158
	v_permlane16_swap_b32_e32 v157, v159
	s_add_u32 s28, s22, 0x600c00
	s_addc_u32 s29, s23, 0
	global_store_dwordx4 v254, v[156:159], s[28:29]
	ds_bpermute_b32 v158, v248, v161
	s_waitcnt lgkmcnt(0)
	v_add_f32_e32 v161, v161, v158
	ds_bpermute_b32 v158, v249, v161
	s_waitcnt lgkmcnt(0)
	v_add_f32_e32 v161, v161, v158
	global_store_dword v247, v161, s[30:31] offset:4
	s_add_u32 s26, s26, 0x10000
	s_addc_u32 s27, s27, 0
	s_add_u32 s30, s30, 0x400
	s_addc_u32 s31, s31, 0
	s_branch .LBB0_360

.Lproj_cd:
	s_or_b32 s4, s16, s67
	v_mov_b32 v10, v198
	v_ashrrev_i32_e32 v0, 2, v10
	s_lshl_b32 s4, s4, 7
	v_add_u32_e32 v2, s4, v0
	v_ashrrev_i32_e32 v3, 31, v2
	v_lshlrev_b64 v[2:3], 6, v[2:3]
	v_lshlrev_b32_e32 v1, 4, v10
	v_add_u32_e32 v4, s17, v0
	v_lshl_add_u64 v[2:3], s[96:97], 0, v[2:3]
	v_and_b32_e32 v152, 48, v1
	v_ashrrev_i32_e32 v5, 31, v4
	v_lshl_add_u64 v[2:3], v[2:3], 0, v[152:153]
	v_lshlrev_b64 v[4:5], 6, v[4:5]
	v_lshl_add_u64 v[156:157], s[8:9], 0, v[4:5]
	v_add_co_u32_e32 v6, vcc, s62, v2
	v_lshl_add_u64 v[4:5], v[156:157], 0, v[152:153]
	s_nop 0
	v_addc_co_u32_e32 v7, vcc, 0, v3, vcc
	v_add_co_u32_e32 v8, vcc, s62, v4
	s_and_b32 s7, s42, 56
	v_lshrrev_b32_e32 v1, 2, v10
	s_or_b32 s6, s67, s6
	v_addc_co_u32_e32 v9, vcc, 0, v5, vcc
	v_and_b32_e32 v12, 12, v1
	s_movk_i32 s20, 0x1230
	s_or_b32 s84, s6, s7
	v_add_co_u32_e32 v60, vcc, s33, v4
	v_lshrrev_b32_e64 v12, v12, s20
	s_lshl_b64 s[6:7], s[84:85], 18
	v_addc_co_u32_e32 v61, vcc, 0, v5, vcc
	v_and_b32_e32 v11, 3, v10
	v_ashrrev_i32_e32 v1, 31, v0
	v_xor_b32_e32 v10, v12, v10
	s_add_u32 s6, s82, s6
	v_add_co_u32_e32 v62, vcc, s72, v4
	v_lshlrev_b32_e32 v13, 6, v0
	v_lshlrev_b64 v[0:1], 11, v[0:1]
	v_lshlrev_b32_e32 v10, 4, v10
	s_addc_u32 s7, s83, s7
	v_addc_co_u32_e32 v63, vcc, 0, v5, vcc
	s_nop 0
	v_readfirstlane_b32 s26, v2
	v_readfirstlane_b32 s27, v3
	v_readfirstlane_b32 s28, v4
	v_readfirstlane_b32 s29, v5
	v_lshrrev_b32_e32 v250, 6, v198
	s_nop 0
	v_readfirstlane_b32 s24, v250
	s_lshl_b32 s24, s24, 10
	v_lshrrev_b32_e32 v250, 2, v200
	v_lshrrev_b32_e32 v251, 4, v200
	v_lshlrev_b32_e32 v251, 2, v251
	v_mov_b32_e32 v248, 0x1230
	v_lshrrev_b32_e32 v251, v251, v248
	v_xor_b32_e32 v251, v251, v200
	v_and_b32_e32 v251, 3, v251
	v_lshlrev_b32_e32 v251, 4, v251
	v_lshl_add_u32 v244, v250, 11, v251
	v_add_u32_e32 v245, 0x20000, v244
	v_add_u32_e32 v246, 0x40000, v244
	v_add_u32_e32 v247, 0x60000, v244
	v_lshl_add_u32 v156, v250, 6, v251
	v_add_u32_e32 v157, 0x1000, v156
	v_add_u32_e32 v158, 0x2000, v156
	v_add_u32_e32 v159, 0x3000, v156
	s_mov_b32 s25, 0
	s_add_u32 m0, s25, s24
	s_nop 0
	global_load_lds_dwordx4 v156, s[26:27]
	s_add_u32 m0, m0, 0x1000
	s_nop 0
	global_load_lds_dwordx4 v157, s[26:27]
	s_add_u32 m0, m0, 0x1000
	s_nop 0
	global_load_lds_dwordx4 v156, s[28:29]
	s_add_u32 m0, m0, 0x1000
	s_nop 0
	global_load_lds_dwordx4 v157, s[28:29]
	s_add_u32 m0, m0, 0x1000
	s_nop 0
	global_load_lds_dwordx4 v158, s[28:29]
	s_add_u32 m0, m0, 0x1000
	s_nop 0
	global_load_lds_dwordx4 v159, s[28:29]
	s_add_u32 s26, s26, 0x200000
	s_addc_u32 s27, s27, 0
	s_add_u32 s28, s28, 0x34000
	s_addc_u32 s29, s29, 0
	s_add_u32 s25, s25, 24576
	s_cmp_eq_u32 s25, 73728
	s_cselect_b32 s25, 0, s25
	s_add_u32 m0, s25, s24
	s_nop 0
	global_load_lds_dwordx4 v156, s[26:27]
	s_add_u32 m0, m0, 0x1000
	s_nop 0
	global_load_lds_dwordx4 v157, s[26:27]
	s_add_u32 m0, m0, 0x1000
	s_nop 0
	global_load_lds_dwordx4 v156, s[28:29]
	s_add_u32 m0, m0, 0x1000
	s_nop 0
	global_load_lds_dwordx4 v157, s[28:29]
	s_add_u32 m0, m0, 0x1000
	s_nop 0
	global_load_lds_dwordx4 v158, s[28:29]
	s_add_u32 m0, m0, 0x1000
	s_nop 0
	global_load_lds_dwordx4 v159, s[28:29]
	s_add_u32 s26, s26, 0x200000
	s_addc_u32 s27, s27, 0
	s_add_u32 s28, s28, 0x34000
	s_addc_u32 s29, s29, 0
	s_add_u32 s25, s25, 24576
	s_cmp_eq_u32 s25, 73728
	s_cselect_b32 s25, 0, s25
	s_add_u32 m0, s25, s24
	s_nop 0
	global_load_lds_dwordx4 v156, s[26:27]
	s_add_u32 m0, m0, 0x1000
	s_nop 0
	global_load_lds_dwordx4 v157, s[26:27]
	s_add_u32 m0, m0, 0x1000
	s_nop 0
	global_load_lds_dwordx4 v156, s[28:29]
	s_add_u32 m0, m0, 0x1000
	s_nop 0
	global_load_lds_dwordx4 v157, s[28:29]
	s_add_u32 m0, m0, 0x1000
	s_nop 0
	global_load_lds_dwordx4 v158, s[28:29]
	s_add_u32 m0, m0, 0x1000
	s_nop 0
	global_load_lds_dwordx4 v159, s[28:29]
	s_add_u32 s26, s26, 0x200000
	s_addc_u32 s27, s27, 0
	s_add_u32 s28, s28, 0x34000
	s_addc_u32 s29, s29, 0
	s_add_u32 s25, s25, 24576
	s_cmp_eq_u32 s25, 73728
	s_cselect_b32 s25, 0, s25
	v_mov_b32_e32 v24, 0
	v_mov_b32_e32 v25, v24
	v_mov_b32_e32 v26, v24
	v_mov_b32_e32 v27, v24
	v_mov_b32_e32 v28, v24
	v_mov_b32_e32 v29, v24
	v_mov_b32_e32 v30, v24
	v_mov_b32_e32 v31, v24
	v_mov_b32_e32 v32, v24
	v_mov_b32_e32 v33, v24
	v_mov_b32_e32 v34, v24
	v_mov_b32_e32 v35, v24
	v_mov_b32_e32 v64, v24
	v_mov_b32_e32 v65, v24
	v_mov_b32_e32 v66, v24
	v_mov_b32_e32 v67, v24
	v_mov_b32_e32 v68, v24
	v_mov_b32_e32 v69, v24
	v_mov_b32_e32 v70, v24
	v_mov_b32_e32 v71, v24
	v_mov_b32_e32 v60, v24
	v_mov_b32_e32 v61, v24
	v_mov_b32_e32 v62, v24
	v_mov_b32_e32 v63, v24
	v_mov_b32_e32 v100, v24
	v_mov_b32_e32 v101, v24
	v_mov_b32_e32 v102, v24
	v_mov_b32_e32 v103, v24
	v_mov_b32_e32 v104, v24
	v_mov_b32_e32 v105, v24
	v_mov_b32_e32 v106, v24
	v_mov_b32_e32 v107, v24
	v_mov_b32_e32 v120, v24
	v_mov_b32_e32 v121, v24
	v_mov_b32_e32 v122, v24
	v_mov_b32_e32 v36, v24
	v_mov_b32_e32 v37, v24
	v_mov_b32_e32 v38, v24
	v_mov_b32_e32 v39, v24
	v_mov_b32_e32 v52, v24
	v_mov_b32_e32 v53, v24
	v_mov_b32_e32 v54, v24
	v_mov_b32_e32 v55, v24
	v_mov_b32_e32 v56, v24
	v_mov_b32_e32 v57, v24
	v_mov_b32_e32 v58, v24
	v_mov_b32_e32 v59, v24
	v_mov_b32_e32 v40, v24
	v_mov_b32_e32 v41, v24
	v_mov_b32_e32 v42, v24
	v_mov_b32_e32 v43, v24
	v_mov_b32_e32 v44, v24
	v_mov_b32_e32 v45, v24
	v_mov_b32_e32 v46, v24
	v_mov_b32_e32 v47, v24
	v_mov_b32_e32 v48, v24
	v_mov_b32_e32 v49, v24
	v_mov_b32_e32 v50, v24
	v_mov_b32_e32 v51, v24
	v_mov_b32_e32 v123, v24
	v_mov_b32_e32 v128, v24
	v_mov_b32_e32 v129, v24
	v_mov_b32_e32 v130, v24
	v_mov_b32_e32 v131, v24
	v_mov_b32_e32 v108, v24
	v_mov_b32_e32 v109, v24
	v_mov_b32_e32 v110, v24
	v_mov_b32_e32 v111, v24
	v_mov_b32_e32 v112, v24
	v_mov_b32_e32 v113, v24
	v_mov_b32_e32 v114, v24
	v_mov_b32_e32 v115, v24
	v_mov_b32_e32 v116, v24
	v_mov_b32_e32 v117, v24
	v_mov_b32_e32 v118, v24
	v_mov_b32_e32 v119, v24
	v_mov_b32_e32 v124, v24
	v_mov_b32_e32 v125, v24
	v_mov_b32_e32 v126, v24
	v_mov_b32_e32 v127, v24
	v_mov_b32_e32 v80, v24
	v_mov_b32_e32 v81, v24
	v_mov_b32_e32 v82, v24
	v_mov_b32_e32 v83, v24
	v_mov_b32_e32 v88, v24
	v_mov_b32_e32 v89, v24
	v_mov_b32_e32 v90, v24
	v_mov_b32_e32 v91, v24
	v_mov_b32_e32 v92, v24
	v_mov_b32_e32 v93, v24
	v_mov_b32_e32 v94, v24
	v_mov_b32_e32 v95, v24
	v_mov_b32_e32 v76, v24
	v_mov_b32_e32 v77, v24
	v_mov_b32_e32 v78, v24
	v_mov_b32_e32 v79, v24
	v_mov_b32_e32 v132, v24
	v_mov_b32_e32 v133, v24
	v_mov_b32_e32 v134, v24
	v_mov_b32_e32 v135, v24
	v_mov_b32_e32 v136, v24
	v_mov_b32_e32 v137, v24
	v_mov_b32_e32 v138, v24
	v_mov_b32_e32 v139, v24
	v_mov_b32_e32 v140, v24
	v_mov_b32_e32 v141, v24
	v_mov_b32_e32 v142, v24
	v_mov_b32_e32 v143, v24
	v_mov_b32_e32 v144, v24
	v_mov_b32_e32 v145, v24
	v_mov_b32_e32 v146, v24
	v_mov_b32_e32 v147, v24
	v_mov_b32_e32 v96, v24
	v_mov_b32_e32 v97, v24
	v_mov_b32_e32 v98, v24
	v_mov_b32_e32 v99, v24
	v_mov_b32_e32 v84, v24
	v_mov_b32_e32 v85, v24
	v_mov_b32_e32 v86, v24
	v_mov_b32_e32 v87, v24
	v_mov_b32_e32 v72, v24
	v_mov_b32_e32 v73, v24
	v_mov_b32_e32 v74, v24
	v_mov_b32_e32 v75, v24
	v_mov_b32_e32 v148, v24
	v_mov_b32_e32 v149, v24
	v_mov_b32_e32 v150, v24
	v_mov_b32_e32 v151, v24
	s_waitcnt vmcnt(12)
	s_barrier
	s_mov_b32 s30, 0
	v_add_u32_e32 v248, s30, v155
	v_add_u32_e32 v249, s30, v160
	ds_read_b128 v[186:189], v248
	ds_read_b128 v[212:215], v249 offset:8192
	ds_read_b128 v[190:193], v248 offset:1024
	ds_read_b128 v[216:219], v249 offset:9216
	ds_read_b128 v[194:197], v248 offset:2048
	ds_read_b128 v[220:223], v249 offset:10240
	ds_read_b128 v[208:211], v248 offset:3072
	ds_read_b128 v[224:227], v249 offset:11264
	ds_read_b128 v[228:231], v249 offset:12288
	ds_read_b128 v[232:235], v249 offset:13312
	ds_read_b128 v[236:239], v249 offset:14336
	ds_read_b128 v[240:243], v249 offset:15360
	s_add_u32 s30, s30, 24576
	s_cmp_eq_u32 s30, 73728
	s_cselect_b32 s30, 0, s30
	s_waitcnt lgkmcnt(0)
	s_mov_b32 s31, 14
	s_cmpk_lt_u32 s43, 0x180
	s_cbranch_scc0 .Lgm3_cheap
.Lgm3_loop:
	v_mfma_f32_16x16x32_bf16 v[128:131], v[212:215], v[186:189], v[128:131]
	v_mfma_f32_16x16x32_bf16 v[68:71], v[212:215], v[190:193], v[68:71]
	v_mfma_f32_16x16x32_bf16 v[108:111], v[212:215], v[194:197], v[108:111]
	v_mfma_f32_16x16x32_bf16 v[132:135], v[212:215], v[208:211], v[132:135]
	v_mfma_f32_16x16x32_bf16 v[120:123], v[216:219], v[186:189], v[120:123]
	v_mfma_f32_16x16x32_bf16 v[64:67], v[216:219], v[190:193], v[64:67]
	v_mfma_f32_16x16x32_bf16 v[112:115], v[216:219], v[194:197], v[112:115]
	v_mfma_f32_16x16x32_bf16 v[136:139], v[216:219], v[208:211], v[136:139]
	v_mfma_f32_16x16x32_bf16 v[104:107], v[220:223], v[186:189], v[104:107]
	v_mfma_f32_16x16x32_bf16 v[56:59], v[220:223], v[190:193], v[56:59]
	v_mfma_f32_16x16x32_bf16 v[116:119], v[220:223], v[194:197], v[116:119]
	v_mfma_f32_16x16x32_bf16 v[140:143], v[220:223], v[208:211], v[140:143]
	v_mfma_f32_16x16x32_bf16 v[100:103], v[224:227], v[186:189], v[100:103]
	v_mfma_f32_16x16x32_bf16 v[52:55], v[224:227], v[190:193], v[52:55]
	v_mfma_f32_16x16x32_bf16 v[124:127], v[224:227], v[194:197], v[124:127]
	v_mfma_f32_16x16x32_bf16 v[144:147], v[224:227], v[208:211], v[144:147]
	s_waitcnt vmcnt(6)
	s_barrier
	v_add_u32_e32 v248, s30, v155
	v_add_u32_e32 v249, s30, v160
	v_mfma_f32_16x16x32_bf16 v[60:63], v[228:231], v[186:189], v[60:63]
	ds_read_b128 v[0:3], v248
	s_add_u32 m0, s25, s24
	v_mfma_f32_16x16x32_bf16 v[36:39], v[228:231], v[190:193], v[36:39]
	ds_read_b128 v[16:19], v249 offset:8192
	global_load_lds_dwordx4 v156, s[26:27]
	v_mfma_f32_16x16x32_bf16 v[80:83], v[228:231], v[194:197], v[80:83]
	ds_read_b128 v[4:7], v248 offset:1024
	s_add_u32 m0, m0, 0x1000
	v_mfma_f32_16x16x32_bf16 v[96:99], v[228:231], v[208:211], v[96:99]
	ds_read_b128 v[20:23], v249 offset:9216
	global_load_lds_dwordx4 v157, s[26:27]
	v_mfma_f32_16x16x32_bf16 v[48:51], v[232:235], v[186:189], v[48:51]
	ds_read_b128 v[8:11], v248 offset:2048
	s_add_u32 m0, m0, 0x1000
	v_mfma_f32_16x16x32_bf16 v[32:35], v[232:235], v[190:193], v[32:35]
	ds_read_b128 v[162:165], v249 offset:10240
	global_load_lds_dwordx4 v156, s[28:29]
	v_mfma_f32_16x16x32_bf16 v[88:91], v[232:235], v[194:197], v[88:91]
	ds_read_b128 v[12:15], v248 offset:3072
	s_add_u32 m0, m0, 0x1000
	v_mfma_f32_16x16x32_bf16 v[84:87], v[232:235], v[208:211], v[84:87]
	ds_read_b128 v[166:169], v249 offset:11264
	global_load_lds_dwordx4 v157, s[28:29]
	v_mfma_f32_16x16x32_bf16 v[44:47], v[236:239], v[186:189], v[44:47]
	ds_read_b128 v[170:173], v249 offset:12288
	s_add_u32 m0, m0, 0x1000
	v_mfma_f32_16x16x32_bf16 v[28:31], v[236:239], v[190:193], v[28:31]
	ds_read_b128 v[174:177], v249 offset:13312
	global_load_lds_dwordx4 v158, s[28:29]
	v_mfma_f32_16x16x32_bf16 v[92:95], v[236:239], v[194:197], v[92:95]
	ds_read_b128 v[178:181], v249 offset:14336
	s_add_u32 m0, m0, 0x1000
	v_mfma_f32_16x16x32_bf16 v[72:75], v[236:239], v[208:211], v[72:75]
	ds_read_b128 v[182:185], v249 offset:15360
	global_load_lds_dwordx4 v159, s[28:29]
	v_mfma_f32_16x16x32_bf16 v[40:43], v[240:243], v[186:189], v[40:43]
	v_mfma_f32_16x16x32_bf16 v[24:27], v[240:243], v[190:193], v[24:27]
	v_mfma_f32_16x16x32_bf16 v[76:79], v[240:243], v[194:197], v[76:79]
	v_mfma_f32_16x16x32_bf16 v[148:151], v[240:243], v[208:211], v[148:151]
	s_add_u32 s26, s26, 0x200000
	s_addc_u32 s27, s27, 0
	s_add_u32 s28, s28, 0x34000
	s_addc_u32 s29, s29, 0
	s_add_u32 s25, s25, 24576
	s_cmp_eq_u32 s25, 73728
	s_cselect_b32 s25, 0, s25
	s_add_u32 s30, s30, 24576
	s_cmp_eq_u32 s30, 73728
	s_cselect_b32 s30, 0, s30
	s_waitcnt lgkmcnt(0)
	v_mfma_f32_16x16x32_bf16 v[128:131], v[16:19], v[0:3], v[128:131]
	v_mfma_f32_16x16x32_bf16 v[68:71], v[16:19], v[4:7], v[68:71]
	v_mfma_f32_16x16x32_bf16 v[108:111], v[16:19], v[8:11], v[108:111]
	v_mfma_f32_16x16x32_bf16 v[132:135], v[16:19], v[12:15], v[132:135]
	v_mfma_f32_16x16x32_bf16 v[120:123], v[20:23], v[0:3], v[120:123]
	v_mfma_f32_16x16x32_bf16 v[64:67], v[20:23], v[4:7], v[64:67]
	v_mfma_f32_16x16x32_bf16 v[112:115], v[20:23], v[8:11], v[112:115]
	v_mfma_f32_16x16x32_bf16 v[136:139], v[20:23], v[12:15], v[136:139]
	v_mfma_f32_16x16x32_bf16 v[104:107], v[162:165], v[0:3], v[104:107]
	v_mfma_f32_16x16x32_bf16 v[56:59], v[162:165], v[4:7], v[56:59]
	v_mfma_f32_16x16x32_bf16 v[116:119], v[162:165], v[8:11], v[116:119]
	v_mfma_f32_16x16x32_bf16 v[140:143], v[162:165], v[12:15], v[140:143]
	v_mfma_f32_16x16x32_bf16 v[100:103], v[166:169], v[0:3], v[100:103]
	v_mfma_f32_16x16x32_bf16 v[52:55], v[166:169], v[4:7], v[52:55]
	v_mfma_f32_16x16x32_bf16 v[124:127], v[166:169], v[8:11], v[124:127]
	v_mfma_f32_16x16x32_bf16 v[144:147], v[166:169], v[12:15], v[144:147]
	s_waitcnt vmcnt(6)
	s_barrier
	v_add_u32_e32 v248, s30, v155
	v_add_u32_e32 v249, s30, v160
	v_mfma_f32_16x16x32_bf16 v[60:63], v[170:173], v[0:3], v[60:63]
	ds_read_b128 v[186:189], v248
	s_add_u32 m0, s25, s24
	v_mfma_f32_16x16x32_bf16 v[36:39], v[170:173], v[4:7], v[36:39]
	ds_read_b128 v[212:215], v249 offset:8192
	global_load_lds_dwordx4 v156, s[26:27]
	v_mfma_f32_16x16x32_bf16 v[80:83], v[170:173], v[8:11], v[80:83]
	ds_read_b128 v[190:193], v248 offset:1024
	s_add_u32 m0, m0, 0x1000
	v_mfma_f32_16x16x32_bf16 v[96:99], v[170:173], v[12:15], v[96:99]
	ds_read_b128 v[216:219], v249 offset:9216
	global_load_lds_dwordx4 v157, s[26:27]
	v_mfma_f32_16x16x32_bf16 v[48:51], v[174:177], v[0:3], v[48:51]
	ds_read_b128 v[194:197], v248 offset:2048
	s_add_u32 m0, m0, 0x1000
	v_mfma_f32_16x16x32_bf16 v[32:35], v[174:177], v[4:7], v[32:35]
	ds_read_b128 v[220:223], v249 offset:10240
	global_load_lds_dwordx4 v156, s[28:29]
	v_mfma_f32_16x16x32_bf16 v[88:91], v[174:177], v[8:11], v[88:91]
	ds_read_b128 v[208:211], v248 offset:3072
	s_add_u32 m0, m0, 0x1000
	v_mfma_f32_16x16x32_bf16 v[84:87], v[174:177], v[12:15], v[84:87]
	ds_read_b128 v[224:227], v249 offset:11264
	global_load_lds_dwordx4 v157, s[28:29]
	v_mfma_f32_16x16x32_bf16 v[44:47], v[178:181], v[0:3], v[44:47]
	ds_read_b128 v[228:231], v249 offset:12288
	s_add_u32 m0, m0, 0x1000
	v_mfma_f32_16x16x32_bf16 v[28:31], v[178:181], v[4:7], v[28:31]
	ds_read_b128 v[232:235], v249 offset:13312
	global_load_lds_dwordx4 v158, s[28:29]
	v_mfma_f32_16x16x32_bf16 v[92:95], v[178:181], v[8:11], v[92:95]
	ds_read_b128 v[236:239], v249 offset:14336
	s_add_u32 m0, m0, 0x1000
	v_mfma_f32_16x16x32_bf16 v[72:75], v[178:181], v[12:15], v[72:75]
	ds_read_b128 v[240:243], v249 offset:15360
	global_load_lds_dwordx4 v159, s[28:29]
	v_mfma_f32_16x16x32_bf16 v[40:43], v[182:185], v[0:3], v[40:43]
	v_mfma_f32_16x16x32_bf16 v[24:27], v[182:185], v[4:7], v[24:27]
	v_mfma_f32_16x16x32_bf16 v[76:79], v[182:185], v[8:11], v[76:79]
	v_mfma_f32_16x16x32_bf16 v[148:151], v[182:185], v[12:15], v[148:151]
	s_add_u32 s26, s26, 0x200000
	s_addc_u32 s27, s27, 0
	s_add_u32 s28, s28, 0x34000
	s_addc_u32 s29, s29, 0
	s_add_u32 s25, s25, 24576
	s_cmp_eq_u32 s25, 73728
	s_cselect_b32 s25, 0, s25
	s_add_u32 s30, s30, 24576
	s_cmp_eq_u32 s30, 73728
	s_cselect_b32 s30, 0, s30
	s_waitcnt lgkmcnt(0)
	s_sub_u32 s31, s31, 1
	s_cmp_lg_u32 s31, 0
	s_cbranch_scc1 .Lgm3_loop
	v_mfma_f32_16x16x32_bf16 v[128:131], v[212:215], v[186:189], v[128:131]
	v_mfma_f32_16x16x32_bf16 v[68:71], v[212:215], v[190:193], v[68:71]
	v_mfma_f32_16x16x32_bf16 v[108:111], v[212:215], v[194:197], v[108:111]
	v_mfma_f32_16x16x32_bf16 v[132:135], v[212:215], v[208:211], v[132:135]
	v_mfma_f32_16x16x32_bf16 v[120:123], v[216:219], v[186:189], v[120:123]
	v_mfma_f32_16x16x32_bf16 v[64:67], v[216:219], v[190:193], v[64:67]
	v_mfma_f32_16x16x32_bf16 v[112:115], v[216:219], v[194:197], v[112:115]
	v_mfma_f32_16x16x32_bf16 v[136:139], v[216:219], v[208:211], v[136:139]
	v_mfma_f32_16x16x32_bf16 v[104:107], v[220:223], v[186:189], v[104:107]
	v_mfma_f32_16x16x32_bf16 v[56:59], v[220:223], v[190:193], v[56:59]
	v_mfma_f32_16x16x32_bf16 v[116:119], v[220:223], v[194:197], v[116:119]
	v_mfma_f32_16x16x32_bf16 v[140:143], v[220:223], v[208:211], v[140:143]
	v_mfma_f32_16x16x32_bf16 v[100:103], v[224:227], v[186:189], v[100:103]
	v_mfma_f32_16x16x32_bf16 v[52:55], v[224:227], v[190:193], v[52:55]
	v_mfma_f32_16x16x32_bf16 v[124:127], v[224:227], v[194:197], v[124:127]
	v_mfma_f32_16x16x32_bf16 v[144:147], v[224:227], v[208:211], v[144:147]
	s_waitcnt vmcnt(6)
	s_barrier
	v_add_u32_e32 v248, s30, v155
	v_add_u32_e32 v249, s30, v160
	v_mfma_f32_16x16x32_bf16 v[60:63], v[228:231], v[186:189], v[60:63]
	ds_read_b128 v[0:3], v248
	s_add_u32 m0, s25, s24
	v_mfma_f32_16x16x32_bf16 v[36:39], v[228:231], v[190:193], v[36:39]
	ds_read_b128 v[16:19], v249 offset:8192
	global_load_lds_dwordx4 v156, s[26:27]
	v_mfma_f32_16x16x32_bf16 v[80:83], v[228:231], v[194:197], v[80:83]
	ds_read_b128 v[4:7], v248 offset:1024
	s_add_u32 m0, m0, 0x1000
	v_mfma_f32_16x16x32_bf16 v[96:99], v[228:231], v[208:211], v[96:99]
	ds_read_b128 v[20:23], v249 offset:9216
	global_load_lds_dwordx4 v157, s[26:27]
	v_mfma_f32_16x16x32_bf16 v[48:51], v[232:235], v[186:189], v[48:51]
	ds_read_b128 v[8:11], v248 offset:2048
	s_add_u32 m0, m0, 0x1000
	v_mfma_f32_16x16x32_bf16 v[32:35], v[232:235], v[190:193], v[32:35]
	ds_read_b128 v[162:165], v249 offset:10240
	global_load_lds_dwordx4 v156, s[28:29]
	v_mfma_f32_16x16x32_bf16 v[88:91], v[232:235], v[194:197], v[88:91]
	ds_read_b128 v[12:15], v248 offset:3072
	s_add_u32 m0, m0, 0x1000
	v_mfma_f32_16x16x32_bf16 v[84:87], v[232:235], v[208:211], v[84:87]
	ds_read_b128 v[166:169], v249 offset:11264
	global_load_lds_dwordx4 v157, s[28:29]
	v_mfma_f32_16x16x32_bf16 v[44:47], v[236:239], v[186:189], v[44:47]
	ds_read_b128 v[170:173], v249 offset:12288
	s_add_u32 m0, m0, 0x1000
	v_mfma_f32_16x16x32_bf16 v[28:31], v[236:239], v[190:193], v[28:31]
	ds_read_b128 v[174:177], v249 offset:13312
	global_load_lds_dwordx4 v158, s[28:29]
	v_mfma_f32_16x16x32_bf16 v[92:95], v[236:239], v[194:197], v[92:95]
	ds_read_b128 v[178:181], v249 offset:14336
	s_add_u32 m0, m0, 0x1000
	v_mfma_f32_16x16x32_bf16 v[72:75], v[236:239], v[208:211], v[72:75]
	ds_read_b128 v[182:185], v249 offset:15360
	global_load_lds_dwordx4 v159, s[28:29]
	v_mfma_f32_16x16x32_bf16 v[40:43], v[240:243], v[186:189], v[40:43]
	v_mfma_f32_16x16x32_bf16 v[24:27], v[240:243], v[190:193], v[24:27]
	v_mfma_f32_16x16x32_bf16 v[76:79], v[240:243], v[194:197], v[76:79]
	v_mfma_f32_16x16x32_bf16 v[148:151], v[240:243], v[208:211], v[148:151]
	s_add_u32 s26, s26, 0x200000
	s_addc_u32 s27, s27, 0
	s_add_u32 s28, s28, 0x34000
	s_addc_u32 s29, s29, 0
	s_add_u32 s25, s25, 24576
	s_cmp_eq_u32 s25, 73728
	s_cselect_b32 s25, 0, s25
	s_add_u32 s30, s30, 24576
	s_cmp_eq_u32 s30, 73728
	s_cselect_b32 s30, 0, s30
	s_waitcnt lgkmcnt(0)
	v_mfma_f32_16x16x32_bf16 v[128:131], v[16:19], v[0:3], v[128:131]
	v_mfma_f32_16x16x32_bf16 v[68:71], v[16:19], v[4:7], v[68:71]
	v_mfma_f32_16x16x32_bf16 v[108:111], v[16:19], v[8:11], v[108:111]
	v_mfma_f32_16x16x32_bf16 v[132:135], v[16:19], v[12:15], v[132:135]
	v_mfma_f32_16x16x32_bf16 v[120:123], v[20:23], v[0:3], v[120:123]
	v_mfma_f32_16x16x32_bf16 v[64:67], v[20:23], v[4:7], v[64:67]
	v_mfma_f32_16x16x32_bf16 v[112:115], v[20:23], v[8:11], v[112:115]
	v_mfma_f32_16x16x32_bf16 v[136:139], v[20:23], v[12:15], v[136:139]
	v_mfma_f32_16x16x32_bf16 v[104:107], v[162:165], v[0:3], v[104:107]
	v_mfma_f32_16x16x32_bf16 v[56:59], v[162:165], v[4:7], v[56:59]
	v_mfma_f32_16x16x32_bf16 v[116:119], v[162:165], v[8:11], v[116:119]
	v_mfma_f32_16x16x32_bf16 v[140:143], v[162:165], v[12:15], v[140:143]
	v_mfma_f32_16x16x32_bf16 v[100:103], v[166:169], v[0:3], v[100:103]
	v_mfma_f32_16x16x32_bf16 v[52:55], v[166:169], v[4:7], v[52:55]
	v_mfma_f32_16x16x32_bf16 v[124:127], v[166:169], v[8:11], v[124:127]
	v_mfma_f32_16x16x32_bf16 v[144:147], v[166:169], v[12:15], v[144:147]
	v_mfma_f32_16x16x32_bf16 v[60:63], v[170:173], v[0:3], v[60:63]
	v_mfma_f32_16x16x32_bf16 v[36:39], v[170:173], v[4:7], v[36:39]
	v_mfma_f32_16x16x32_bf16 v[80:83], v[170:173], v[8:11], v[80:83]
	v_mfma_f32_16x16x32_bf16 v[96:99], v[170:173], v[12:15], v[96:99]
	v_mfma_f32_16x16x32_bf16 v[48:51], v[174:177], v[0:3], v[48:51]
	v_mfma_f32_16x16x32_bf16 v[32:35], v[174:177], v[4:7], v[32:35]
	v_mfma_f32_16x16x32_bf16 v[88:91], v[174:177], v[8:11], v[88:91]
	v_mfma_f32_16x16x32_bf16 v[84:87], v[174:177], v[12:15], v[84:87]
	v_mfma_f32_16x16x32_bf16 v[44:47], v[178:181], v[0:3], v[44:47]
	v_mfma_f32_16x16x32_bf16 v[28:31], v[178:181], v[4:7], v[28:31]
	v_mfma_f32_16x16x32_bf16 v[92:95], v[178:181], v[8:11], v[92:95]
	v_mfma_f32_16x16x32_bf16 v[72:75], v[178:181], v[12:15], v[72:75]
	v_mfma_f32_16x16x32_bf16 v[40:43], v[182:185], v[0:3], v[40:43]
	v_mfma_f32_16x16x32_bf16 v[24:27], v[182:185], v[4:7], v[24:27]
	v_mfma_f32_16x16x32_bf16 v[76:79], v[182:185], v[8:11], v[76:79]
	v_mfma_f32_16x16x32_bf16 v[148:151], v[182:185], v[12:15], v[148:151]
	s_waitcnt vmcnt(0)
	s_waitcnt lgkmcnt(0)
	s_barrier
	s_branch .Lgm3_tail
.Lgm3_cheap:
	s_waitcnt vmcnt(6)
	s_barrier
	v_add_u32_e32 v248, s30, v155
	v_add_u32_e32 v249, s30, v160
	v_mfma_f32_16x16x32_bf16 v[128:131], v[212:215], v[186:189], v[128:131]
	ds_read_b128 v[0:3], v248
	v_mfma_f32_16x16x32_bf16 v[68:71], v[212:215], v[190:193], v[68:71]
	ds_read_b128 v[16:19], v249 offset:8192
	v_mfma_f32_16x16x32_bf16 v[108:111], v[212:215], v[194:197], v[108:111]
	ds_read_b128 v[4:7], v248 offset:1024
	v_mfma_f32_16x16x32_bf16 v[132:135], v[212:215], v[208:211], v[132:135]
	ds_read_b128 v[20:23], v249 offset:9216
	v_mfma_f32_16x16x32_bf16 v[120:123], v[216:219], v[186:189], v[120:123]
	ds_read_b128 v[8:11], v248 offset:2048
	s_add_u32 m0, s25, s24
	v_mfma_f32_16x16x32_bf16 v[64:67], v[216:219], v[190:193], v[64:67]
	ds_read_b128 v[12:15], v248 offset:3072
	global_load_lds_dwordx4 v156, s[26:27]
	s_add_u32 m0, m0, 0x1000
	v_mfma_f32_16x16x32_bf16 v[112:115], v[216:219], v[194:197], v[112:115]
	global_load_lds_dwordx4 v157, s[26:27]
	s_add_u32 m0, m0, 0x1000
	v_mfma_f32_16x16x32_bf16 v[136:139], v[216:219], v[208:211], v[136:139]
	global_load_lds_dwordx4 v156, s[28:29]
	s_add_u32 s26, s26, 0x200000
	s_addc_u32 s27, s27, 0
	s_add_u32 s28, s28, 0x34000
	s_addc_u32 s29, s29, 0
	s_add_u32 s25, s25, 24576
	s_cmp_eq_u32 s25, 73728
	s_cselect_b32 s25, 0, s25
	s_add_u32 s30, s30, 24576
	s_cmp_eq_u32 s30, 73728
	s_cselect_b32 s30, 0, s30
	s_waitcnt vmcnt(3)
	s_waitcnt lgkmcnt(0)
	s_barrier
	v_add_u32_e32 v248, s30, v155
	v_add_u32_e32 v249, s30, v160
	v_mfma_f32_16x16x32_bf16 v[128:131], v[16:19], v[0:3], v[128:131]
	ds_read_b128 v[186:189], v248
	v_mfma_f32_16x16x32_bf16 v[68:71], v[16:19], v[4:7], v[68:71]
	ds_read_b128 v[212:215], v249 offset:8192
	v_mfma_f32_16x16x32_bf16 v[108:111], v[16:19], v[8:11], v[108:111]
	ds_read_b128 v[190:193], v248 offset:1024
	v_mfma_f32_16x16x32_bf16 v[132:135], v[16:19], v[12:15], v[132:135]
	ds_read_b128 v[216:219], v249 offset:9216
	v_mfma_f32_16x16x32_bf16 v[120:123], v[20:23], v[0:3], v[120:123]
	ds_read_b128 v[194:197], v248 offset:2048
	s_add_u32 m0, s25, s24
	v_mfma_f32_16x16x32_bf16 v[64:67], v[20:23], v[4:7], v[64:67]
	ds_read_b128 v[208:211], v248 offset:3072
	global_load_lds_dwordx4 v156, s[26:27]
	s_add_u32 m0, m0, 0x1000
	v_mfma_f32_16x16x32_bf16 v[112:115], v[20:23], v[8:11], v[112:115]
	global_load_lds_dwordx4 v157, s[26:27]
	s_add_u32 m0, m0, 0x1000
	v_mfma_f32_16x16x32_bf16 v[136:139], v[20:23], v[12:15], v[136:139]
	global_load_lds_dwordx4 v156, s[28:29]
	s_add_u32 s26, s26, 0x200000
	s_addc_u32 s27, s27, 0
	s_add_u32 s28, s28, 0x34000
	s_addc_u32 s29, s29, 0
	s_add_u32 s25, s25, 24576
	s_cmp_eq_u32 s25, 73728
	s_cselect_b32 s25, 0, s25
	s_add_u32 s30, s30, 24576
	s_cmp_eq_u32 s30, 73728
	s_cselect_b32 s30, 0, s30
	s_waitcnt vmcnt(3)
	s_waitcnt lgkmcnt(0)
	s_barrier
	s_sub_u32 s31, s31, 1
	s_cmp_lg_u32 s31, 0
	s_cbranch_scc1 .Lgm3_cheap
	v_add_u32_e32 v248, s30, v155
	v_add_u32_e32 v249, s30, v160
	v_mfma_f32_16x16x32_bf16 v[128:131], v[212:215], v[186:189], v[128:131]
	ds_read_b128 v[0:3], v248
	v_mfma_f32_16x16x32_bf16 v[68:71], v[212:215], v[190:193], v[68:71]
	ds_read_b128 v[16:19], v249 offset:8192
	v_mfma_f32_16x16x32_bf16 v[108:111], v[212:215], v[194:197], v[108:111]
	ds_read_b128 v[4:7], v248 offset:1024
	v_mfma_f32_16x16x32_bf16 v[132:135], v[212:215], v[208:211], v[132:135]
	ds_read_b128 v[20:23], v249 offset:9216
	v_mfma_f32_16x16x32_bf16 v[120:123], v[216:219], v[186:189], v[120:123]
	ds_read_b128 v[8:11], v248 offset:2048
	s_add_u32 m0, s25, s24
	v_mfma_f32_16x16x32_bf16 v[64:67], v[216:219], v[190:193], v[64:67]
	ds_read_b128 v[12:15], v248 offset:3072
	global_load_lds_dwordx4 v156, s[26:27]
	s_add_u32 m0, m0, 0x1000
	v_mfma_f32_16x16x32_bf16 v[112:115], v[216:219], v[194:197], v[112:115]
	global_load_lds_dwordx4 v157, s[26:27]
	s_add_u32 m0, m0, 0x1000
	v_mfma_f32_16x16x32_bf16 v[136:139], v[216:219], v[208:211], v[136:139]
	global_load_lds_dwordx4 v156, s[28:29]
	s_add_u32 s26, s26, 0x200000
	s_addc_u32 s27, s27, 0
	s_add_u32 s28, s28, 0x34000
	s_addc_u32 s29, s29, 0
	s_add_u32 s25, s25, 24576
	s_cmp_eq_u32 s25, 73728
	s_cselect_b32 s25, 0, s25
	s_add_u32 s30, s30, 24576
	s_cmp_eq_u32 s30, 73728
	s_cselect_b32 s30, 0, s30
	s_waitcnt vmcnt(3)
	s_waitcnt lgkmcnt(0)
	s_barrier
	v_mfma_f32_16x16x32_bf16 v[128:131], v[16:19], v[0:3], v[128:131]
	v_mfma_f32_16x16x32_bf16 v[68:71], v[16:19], v[4:7], v[68:71]
	v_mfma_f32_16x16x32_bf16 v[108:111], v[16:19], v[8:11], v[108:111]
	v_mfma_f32_16x16x32_bf16 v[132:135], v[16:19], v[12:15], v[132:135]
	v_mfma_f32_16x16x32_bf16 v[120:123], v[20:23], v[0:3], v[120:123]
	v_mfma_f32_16x16x32_bf16 v[64:67], v[20:23], v[4:7], v[64:67]
	v_mfma_f32_16x16x32_bf16 v[112:115], v[20:23], v[8:11], v[112:115]
	v_mfma_f32_16x16x32_bf16 v[136:139], v[20:23], v[12:15], v[136:139]
	s_waitcnt vmcnt(0)
	s_waitcnt lgkmcnt(0)
	s_barrier
